# v51 + GEMM first load segment: B1 reads stay outstanding across the barrier (lgkmcnt(4)), waited before the 17th MFMA
# baseline (speedup 1.0000x reference)
.LBB0_268:
	s_ashr_i32 s9, s8, 31
	v_cmp_lt_i64_e32 vcc, s[16:17], v[142:143]
	s_lshl_b64 s[16:17], s[8:9], 20
	s_add_u32 s16, s88, s16
	s_addc_u32 s17, s89, s17
	s_and_b64 s[18:19], vcc, exec
	s_cselect_b32 s9, s17, s23
	s_cselect_b32 s53, s16, s22
	s_ashr_i32 s7, s6, 31
	s_lshl_b64 s[18:19], s[6:7], 20
	s_add_u32 s18, s38, s18
	s_addc_u32 s19, s39, s19
	s_and_b64 s[26:27], vcc, exec
	s_cselect_b32 s7, s19, s25
	s_cselect_b32 s58, s18, s24
	s_add_u32 s22, s22, 0x80080
	s_addc_u32 s23, s23, 0
	s_add_u32 s59, s24, 0x100
	v_mov_b32_e32 v2, 0
	s_addc_u32 s60, s25, 0
	s_mov_b32 s61, -2
	v_mov_b32_e32 v3, v2
	v_mov_b32_e32 v4, v2
	v_mov_b32_e32 v5, v2
	v_mov_b32_e32 v6, v2
	v_mov_b32_e32 v7, v2
	v_mov_b32_e32 v8, v2
	v_mov_b32_e32 v9, v2
	v_mov_b32_e32 v10, v2
	v_mov_b32_e32 v11, v2
	v_mov_b32_e32 v12, v2
	v_mov_b32_e32 v13, v2
	v_mov_b32_e32 v18, v2
	v_mov_b32_e32 v19, v2
	v_mov_b32_e32 v20, v2
	v_mov_b32_e32 v21, v2
	v_mov_b32_e32 v26, v2
	v_mov_b32_e32 v27, v2
	v_mov_b32_e32 v28, v2
	v_mov_b32_e32 v29, v2
	v_mov_b32_e32 v34, v2
	v_mov_b32_e32 v35, v2
	v_mov_b32_e32 v36, v2
	v_mov_b32_e32 v37, v2
	v_mov_b32_e32 v42, v2
	v_mov_b32_e32 v43, v2
	v_mov_b32_e32 v44, v2
	v_mov_b32_e32 v45, v2
	v_mov_b32_e32 v50, v2
	v_mov_b32_e32 v51, v2
	v_mov_b32_e32 v52, v2
	v_mov_b32_e32 v53, v2
	v_mov_b32_e32 v14, v2
	v_mov_b32_e32 v15, v2
	v_mov_b32_e32 v16, v2
	v_mov_b32_e32 v17, v2
	v_mov_b32_e32 v22, v2
	v_mov_b32_e32 v23, v2
	v_mov_b32_e32 v24, v2
	v_mov_b32_e32 v25, v2
	v_mov_b32_e32 v30, v2
	v_mov_b32_e32 v31, v2
	v_mov_b32_e32 v32, v2
	v_mov_b32_e32 v33, v2
	v_mov_b32_e32 v38, v2
	v_mov_b32_e32 v39, v2
	v_mov_b32_e32 v40, v2
	v_mov_b32_e32 v41, v2
	v_mov_b32_e32 v46, v2
	v_mov_b32_e32 v47, v2
	v_mov_b32_e32 v48, v2
	v_mov_b32_e32 v49, v2
	v_mov_b32_e32 v54, v2
	v_mov_b32_e32 v55, v2
	v_mov_b32_e32 v56, v2
	v_mov_b32_e32 v57, v2
	v_mov_b32_e32 v58, v2
	v_mov_b32_e32 v59, v2
	v_mov_b32_e32 v60, v2
	v_mov_b32_e32 v61, v2
	v_mov_b32_e32 v62, v2
	v_mov_b32_e32 v63, v2
	v_mov_b32_e32 v64, v2
	v_mov_b32_e32 v65, v2
	v_mov_b32_e32 v66, v2
	v_mov_b32_e32 v67, v2
	v_mov_b32_e32 v68, v2
	v_mov_b32_e32 v69, v2
	v_mov_b32_e32 v70, v2
	v_mov_b32_e32 v71, v2
	v_mov_b32_e32 v72, v2
	v_mov_b32_e32 v73, v2
	v_mov_b32_e32 v74, v2
	v_mov_b32_e32 v75, v2
	v_mov_b32_e32 v76, v2
	v_mov_b32_e32 v77, v2
	v_mov_b32_e32 v82, v2
	v_mov_b32_e32 v83, v2
	v_mov_b32_e32 v84, v2
	v_mov_b32_e32 v85, v2
	v_mov_b32_e32 v90, v2
	v_mov_b32_e32 v91, v2
	v_mov_b32_e32 v92, v2
	v_mov_b32_e32 v93, v2
	v_mov_b32_e32 v98, v2
	v_mov_b32_e32 v99, v2
	v_mov_b32_e32 v100, v2
	v_mov_b32_e32 v101, v2
	v_mov_b32_e32 v106, v2
	v_mov_b32_e32 v107, v2
	v_mov_b32_e32 v108, v2
	v_mov_b32_e32 v109, v2
	v_mov_b32_e32 v114, v2
	v_mov_b32_e32 v115, v2
	v_mov_b32_e32 v116, v2
	v_mov_b32_e32 v117, v2
	v_mov_b32_e32 v78, v2
	v_mov_b32_e32 v79, v2
	v_mov_b32_e32 v80, v2
	v_mov_b32_e32 v81, v2
	v_mov_b32_e32 v86, v2
	v_mov_b32_e32 v87, v2
	v_mov_b32_e32 v88, v2
	v_mov_b32_e32 v89, v2
	v_mov_b32_e32 v94, v2
	v_mov_b32_e32 v95, v2
	v_mov_b32_e32 v96, v2
	v_mov_b32_e32 v97, v2
	v_mov_b32_e32 v102, v2
	v_mov_b32_e32 v103, v2
	v_mov_b32_e32 v104, v2
	v_mov_b32_e32 v105, v2
	v_mov_b32_e32 v110, v2
	v_mov_b32_e32 v111, v2
	v_mov_b32_e32 v112, v2
	v_mov_b32_e32 v113, v2
	v_mov_b32_e32 v118, v2
	v_mov_b32_e32 v119, v2
	v_mov_b32_e32 v120, v2
	v_mov_b32_e32 v121, v2
	v_mov_b32_e32 v122, v2
	v_mov_b32_e32 v123, v2
	v_mov_b32_e32 v124, v2
	v_mov_b32_e32 v125, v2
	v_mov_b32_e32 v126, v2
	v_mov_b32_e32 v127, v2
	v_mov_b32_e32 v128, v2
	v_mov_b32_e32 v129, v2
	s_cmp_eq_u32 s98, 0
	s_cbranch_scc1 .LBB0_269
	ds_read_b128 v[146:149], v152
	ds_read_b128 v[156:159], v152 offset:1024
	ds_read_b128 v[160:163], v152 offset:2048
	ds_read_b128 v[164:167], v152 offset:3072
	s_add_u32 s24, s22, 0xfff80080
	s_addc_u32 s25, s23, -1
	s_cmp_eq_u32 s61, 28
	s_cselect_b32 s27, s9, s25
	s_cselect_b32 s26, s53, s24
	s_cselect_b32 s25, s7, s60
	s_cselect_b32 s24, s58, s59
	s_add_i32 m0, s21, 0xc000
	ds_read_b128 v[168:171], v153
	ds_read_b128 v[172:175], v153 offset:1024
	ds_read_b128 v[176:179], v153 offset:2048
	ds_read_b128 v[180:183], v153 offset:3072
	ds_read_b128 v[186:189], v153 offset:4096
	ds_read_b128 v[190:193], v153 offset:5120
	ds_read_b128 v[194:197], v153 offset:6144
	ds_read_b128 v[198:201], v153 offset:7168
	ds_read_b128 v[202:205], v154
	ds_read_b128 v[206:209], v154 offset:1024
	ds_read_b128 v[210:213], v154 offset:2048
	ds_read_b128 v[214:217], v154 offset:3072
	global_load_lds_dwordx4 v138, s[22:23]
	s_add_i32 m0, s21, 0xe000
	s_nop 0
	global_load_lds_dwordx4 v140, s[22:23]
	s_waitcnt vmcnt(24)
	s_waitcnt lgkmcnt(4)
	s_barrier
	s_setprio 1
	v_mfma_f32_16x16x32_bf16 v[126:129], v[146:149], v[168:171], v[126:129]
	v_mfma_f32_16x16x32_bf16 v[122:125], v[160:163], v[168:171], v[122:125]
	v_mfma_f32_16x16x32_bf16 v[118:121], v[146:149], v[176:179], v[118:121]
	v_mfma_f32_16x16x32_bf16 v[110:113], v[160:163], v[176:179], v[110:113]
	v_mfma_f32_16x16x32_bf16 v[102:105], v[146:149], v[186:189], v[102:105]
	v_mfma_f32_16x16x32_bf16 v[94:97], v[160:163], v[186:189], v[94:97]
	v_mfma_f32_16x16x32_bf16 v[86:89], v[146:149], v[194:197], v[86:89]
	v_mfma_f32_16x16x32_bf16 v[78:81], v[160:163], v[194:197], v[78:81]
	v_mfma_f32_16x16x32_bf16 v[126:129], v[156:159], v[172:175], v[126:129]
	v_mfma_f32_16x16x32_bf16 v[122:125], v[164:167], v[172:175], v[122:125]
	v_mfma_f32_16x16x32_bf16 v[118:121], v[156:159], v[180:183], v[118:121]
	v_mfma_f32_16x16x32_bf16 v[110:113], v[164:167], v[180:183], v[110:113]
	v_mfma_f32_16x16x32_bf16 v[102:105], v[156:159], v[190:193], v[102:105]
	v_mfma_f32_16x16x32_bf16 v[94:97], v[164:167], v[190:193], v[94:97]
	v_mfma_f32_16x16x32_bf16 v[86:89], v[156:159], v[198:201], v[86:89]
	v_mfma_f32_16x16x32_bf16 v[78:81], v[164:167], v[198:201], v[78:81]
	s_waitcnt lgkmcnt(0)
	v_mfma_f32_16x16x32_bf16 v[114:117], v[202:205], v[168:171], v[114:117]
	v_mfma_f32_16x16x32_bf16 v[106:109], v[210:213], v[168:171], v[106:109]
	v_mfma_f32_16x16x32_bf16 v[98:101], v[202:205], v[176:179], v[98:101]
	v_mfma_f32_16x16x32_bf16 v[90:93], v[210:213], v[176:179], v[90:93]
	v_mfma_f32_16x16x32_bf16 v[82:85], v[202:205], v[186:189], v[82:85]
	v_mfma_f32_16x16x32_bf16 v[74:77], v[210:213], v[186:189], v[74:77]
	v_mfma_f32_16x16x32_bf16 v[70:73], v[202:205], v[194:197], v[70:73]
	v_mfma_f32_16x16x32_bf16 v[66:69], v[210:213], v[194:197], v[66:69]
	v_mfma_f32_16x16x32_bf16 v[114:117], v[206:209], v[172:175], v[114:117]
	v_mfma_f32_16x16x32_bf16 v[106:109], v[214:217], v[172:175], v[106:109]
	v_mfma_f32_16x16x32_bf16 v[98:101], v[206:209], v[180:183], v[98:101]
	v_mfma_f32_16x16x32_bf16 v[90:93], v[214:217], v[180:183], v[90:93]
	v_mfma_f32_16x16x32_bf16 v[82:85], v[206:209], v[190:193], v[82:85]
	v_mfma_f32_16x16x32_bf16 v[74:77], v[214:217], v[190:193], v[74:77]
	v_mfma_f32_16x16x32_bf16 v[70:73], v[206:209], v[198:201], v[70:73]
	v_mfma_f32_16x16x32_bf16 v[66:69], v[214:217], v[198:201], v[66:69]
	s_setprio 0
	s_barrier
	s_add_i32 s68, s45, s29
	v_lshl_add_u64 v[218:219], s[24:25], 0, v[134:135]
	s_mov_b32 m0, s68
	global_load_lds_dwordx4 v134, s[24:25]
	v_lshl_add_u64 v[220:221], s[24:25], 0, v[130:131]
	s_add_i32 m0, s68, 0x2000
	s_nop 0
	global_load_lds_dwordx4 v130, s[24:25]
	s_mov_b32 m0, s21
	v_lshl_add_u64 v[222:223], s[26:27], 0, v[136:137]
	ds_read_b128 v[168:171], v153 offset:16384
	ds_read_b128 v[172:175], v153 offset:17408
	ds_read_b128 v[176:179], v153 offset:18432
	ds_read_b128 v[180:183], v153 offset:19456
	ds_read_b128 v[186:189], v153 offset:20480
	ds_read_b128 v[190:193], v153 offset:21504
	ds_read_b128 v[194:197], v153 offset:22528
	ds_read_b128 v[198:201], v153 offset:23552
	global_load_lds_dwordx4 v136, s[26:27]
	v_lshl_add_u64 v[224:225], s[26:27], 0, v[132:133]
	s_mov_b32 m0, s34
	s_nop 0
	global_load_lds_dwordx4 v132, s[26:27]
	s_waitcnt vmcnt(22)
	s_waitcnt lgkmcnt(0)
	s_barrier
	s_setprio 1
	v_mfma_f32_16x16x32_bf16 v[62:65], v[146:149], v[168:171], v[62:65]
	v_mfma_f32_16x16x32_bf16 v[58:61], v[160:163], v[168:171], v[58:61]
	v_mfma_f32_16x16x32_bf16 v[54:57], v[146:149], v[176:179], v[54:57]
	v_mfma_f32_16x16x32_bf16 v[46:49], v[160:163], v[176:179], v[46:49]
	v_mfma_f32_16x16x32_bf16 v[38:41], v[146:149], v[186:189], v[38:41]
	v_mfma_f32_16x16x32_bf16 v[30:33], v[160:163], v[186:189], v[30:33]
	v_mfma_f32_16x16x32_bf16 v[22:25], v[146:149], v[194:197], v[22:25]
	v_mfma_f32_16x16x32_bf16 v[14:17], v[160:163], v[194:197], v[14:17]
	v_mfma_f32_16x16x32_bf16 v[62:65], v[156:159], v[172:175], v[62:65]
	v_mfma_f32_16x16x32_bf16 v[58:61], v[164:167], v[172:175], v[58:61]
	v_mfma_f32_16x16x32_bf16 v[54:57], v[156:159], v[180:183], v[54:57]
	v_mfma_f32_16x16x32_bf16 v[46:49], v[164:167], v[180:183], v[46:49]
	v_mfma_f32_16x16x32_bf16 v[38:41], v[156:159], v[190:193], v[38:41]
	v_mfma_f32_16x16x32_bf16 v[30:33], v[164:167], v[190:193], v[30:33]
	v_mfma_f32_16x16x32_bf16 v[22:25], v[156:159], v[198:201], v[22:25]
	v_mfma_f32_16x16x32_bf16 v[14:17], v[164:167], v[198:201], v[14:17]
	v_mfma_f32_16x16x32_bf16 v[50:53], v[202:205], v[168:171], v[50:53]
	v_mfma_f32_16x16x32_bf16 v[42:45], v[210:213], v[168:171], v[42:45]
	v_mfma_f32_16x16x32_bf16 v[34:37], v[202:205], v[176:179], v[34:37]
	v_mfma_f32_16x16x32_bf16 v[26:29], v[210:213], v[176:179], v[26:29]
	v_mfma_f32_16x16x32_bf16 v[18:21], v[202:205], v[186:189], v[18:21]
	v_mfma_f32_16x16x32_bf16 v[10:13], v[210:213], v[186:189], v[10:13]
	v_mfma_f32_16x16x32_bf16 v[6:9], v[202:205], v[194:197], v[6:9]
	v_mfma_f32_16x16x32_bf16 v[2:5], v[210:213], v[194:197], v[2:5]
	v_mfma_f32_16x16x32_bf16 v[50:53], v[206:209], v[172:175], v[50:53]
	v_mfma_f32_16x16x32_bf16 v[42:45], v[214:217], v[172:175], v[42:45]
	v_mfma_f32_16x16x32_bf16 v[34:37], v[206:209], v[180:183], v[34:37]
	v_mfma_f32_16x16x32_bf16 v[26:29], v[214:217], v[180:183], v[26:29]
	v_mfma_f32_16x16x32_bf16 v[18:21], v[206:209], v[190:193], v[18:21]
	v_mfma_f32_16x16x32_bf16 v[10:13], v[214:217], v[190:193], v[10:13]
	v_mfma_f32_16x16x32_bf16 v[6:9], v[206:209], v[198:201], v[6:9]
	v_mfma_f32_16x16x32_bf16 v[2:5], v[214:217], v[198:201], v[2:5]
	s_setprio 0
	s_barrier
	s_add_u32 s68, s24, 0x80000
	s_addc_u32 s69, s25, 0
	s_add_i32 s70, s46, s29
	s_mov_b32 m0, s70
	s_nop 0
	global_load_lds_dwordx4 v134, s[68:69]
	s_add_i32 m0, s70, 0x2000
	s_nop 0
	global_load_lds_dwordx4 v130, s[68:69]
	s_add_i32 s68, 0, 0x18000
	v_add_u32_e32 v155, s68, v150
	ds_read_b128 v[146:149], v155
	ds_read_b128 v[156:159], v155 offset:1024
	ds_read_b128 v[160:163], v155 offset:2048
	ds_read_b128 v[164:167], v155 offset:3072
	s_add_u32 s26, s26, 0x80000
	s_addc_u32 s27, s27, 0
	s_mov_b32 m0, s35
	ds_read_b128 v[168:171], v153 offset:32768
	ds_read_b128 v[172:175], v153 offset:33792
	ds_read_b128 v[176:179], v153 offset:34816
	ds_read_b128 v[180:183], v153 offset:35840
	ds_read_b128 v[186:189], v153 offset:36864
	ds_read_b128 v[190:193], v153 offset:37888
	ds_read_b128 v[194:197], v153 offset:38912
	ds_read_b128 v[198:201], v153 offset:39936
	v_add_u32_e32 v214, 0x1c000, v150
	ds_read_b128 v[202:205], v214
	ds_read_b128 v[206:209], v214 offset:1024
	ds_read_b128 v[210:213], v214 offset:2048
	ds_read_b128 v[214:217], v214 offset:3072
	global_load_lds_dwordx4 v136, s[26:27]
	s_mov_b32 m0, s36
	s_nop 0
	global_load_lds_dwordx4 v132, s[26:27]
	s_waitcnt vmcnt(8)
	s_waitcnt lgkmcnt(0)
	s_barrier
	s_setprio 1
	v_mfma_f32_16x16x32_bf16 v[126:129], v[146:149], v[168:171], v[126:129]
	v_mfma_f32_16x16x32_bf16 v[122:125], v[160:163], v[168:171], v[122:125]
	v_mfma_f32_16x16x32_bf16 v[118:121], v[146:149], v[176:179], v[118:121]
	v_mfma_f32_16x16x32_bf16 v[110:113], v[160:163], v[176:179], v[110:113]
	v_mfma_f32_16x16x32_bf16 v[102:105], v[146:149], v[186:189], v[102:105]
	v_mfma_f32_16x16x32_bf16 v[94:97], v[160:163], v[186:189], v[94:97]
	v_mfma_f32_16x16x32_bf16 v[86:89], v[146:149], v[194:197], v[86:89]
	v_mfma_f32_16x16x32_bf16 v[78:81], v[160:163], v[194:197], v[78:81]
	v_mfma_f32_16x16x32_bf16 v[126:129], v[156:159], v[172:175], v[126:129]
	v_mfma_f32_16x16x32_bf16 v[122:125], v[164:167], v[172:175], v[122:125]
	v_mfma_f32_16x16x32_bf16 v[118:121], v[156:159], v[180:183], v[118:121]
	v_mfma_f32_16x16x32_bf16 v[110:113], v[164:167], v[180:183], v[110:113]
	v_mfma_f32_16x16x32_bf16 v[102:105], v[156:159], v[190:193], v[102:105]
	v_mfma_f32_16x16x32_bf16 v[94:97], v[164:167], v[190:193], v[94:97]
	v_mfma_f32_16x16x32_bf16 v[86:89], v[156:159], v[198:201], v[86:89]
	v_mfma_f32_16x16x32_bf16 v[78:81], v[164:167], v[198:201], v[78:81]
	v_mfma_f32_16x16x32_bf16 v[114:117], v[202:205], v[168:171], v[114:117]
	v_mfma_f32_16x16x32_bf16 v[106:109], v[210:213], v[168:171], v[106:109]
	v_mfma_f32_16x16x32_bf16 v[98:101], v[202:205], v[176:179], v[98:101]
	v_mfma_f32_16x16x32_bf16 v[90:93], v[210:213], v[176:179], v[90:93]
	v_mfma_f32_16x16x32_bf16 v[82:85], v[202:205], v[186:189], v[82:85]
	v_mfma_f32_16x16x32_bf16 v[74:77], v[210:213], v[186:189], v[74:77]
	v_mfma_f32_16x16x32_bf16 v[70:73], v[202:205], v[194:197], v[70:73]
	v_mfma_f32_16x16x32_bf16 v[66:69], v[210:213], v[194:197], v[66:69]
	v_mfma_f32_16x16x32_bf16 v[114:117], v[206:209], v[172:175], v[114:117]
	v_mfma_f32_16x16x32_bf16 v[106:109], v[214:217], v[172:175], v[106:109]
	v_mfma_f32_16x16x32_bf16 v[98:101], v[206:209], v[180:183], v[98:101]
	v_mfma_f32_16x16x32_bf16 v[90:93], v[214:217], v[180:183], v[90:93]
	v_mfma_f32_16x16x32_bf16 v[82:85], v[206:209], v[190:193], v[82:85]
	v_mfma_f32_16x16x32_bf16 v[74:77], v[214:217], v[190:193], v[74:77]
	v_mfma_f32_16x16x32_bf16 v[70:73], v[206:209], v[198:201], v[70:73]
	v_mfma_f32_16x16x32_bf16 v[66:69], v[214:217], v[198:201], v[66:69]
	s_setprio 0
	s_barrier
	s_add_i32 s26, 0, 0x1c000
	s_add_i32 s27, s68, s29
	v_lshl_add_u64 v[218:219], v[218:219], 0, s[4:5]
	s_mov_b32 m0, s27
	global_load_lds_dwordx4 v[218:219], off
	v_lshl_add_u64 v[218:219], v[220:221], 0, s[4:5]
	s_add_i32 m0, s27, 0x2000
	s_nop 0
	global_load_lds_dwordx4 v[218:219], off
	s_mov_b32 m0, s41
	v_lshl_add_u64 v[218:219], v[222:223], 0, s[4:5]
	ds_read_b128 v[168:171], v153 offset:49152
	ds_read_b128 v[172:175], v153 offset:50176
	ds_read_b128 v[176:179], v153 offset:51200
	ds_read_b128 v[180:183], v153 offset:52224
	ds_read_b128 v[186:189], v153 offset:53248
	ds_read_b128 v[190:193], v153 offset:54272
	ds_read_b128 v[194:197], v153 offset:55296
	ds_read_b128 v[198:201], v153 offset:56320
	global_load_lds_dwordx4 v[218:219], off
	v_lshl_add_u64 v[218:219], v[224:225], 0, s[4:5]
	s_mov_b32 m0, s42
	s_nop 0
	global_load_lds_dwordx4 v[218:219], off
	s_add_u32 s24, s24, 0x80080
	s_addc_u32 s25, s25, 0
	s_add_i32 s26, s26, s29
	s_mov_b32 m0, s26
	s_nop 0
	global_load_lds_dwordx4 v134, s[24:25]
	s_add_i32 m0, s26, 0x2000
	s_nop 0
	global_load_lds_dwordx4 v130, s[24:25]
	s_waitcnt vmcnt(8)
	s_waitcnt lgkmcnt(0)
	s_barrier
	s_setprio 1
	v_mfma_f32_16x16x32_bf16 v[62:65], v[146:149], v[168:171], v[62:65]
	v_mfma_f32_16x16x32_bf16 v[58:61], v[160:163], v[168:171], v[58:61]
	v_mfma_f32_16x16x32_bf16 v[54:57], v[146:149], v[176:179], v[54:57]
	v_mfma_f32_16x16x32_bf16 v[46:49], v[160:163], v[176:179], v[46:49]
	v_mfma_f32_16x16x32_bf16 v[38:41], v[146:149], v[186:189], v[38:41]
	v_mfma_f32_16x16x32_bf16 v[30:33], v[160:163], v[186:189], v[30:33]
	v_mfma_f32_16x16x32_bf16 v[22:25], v[146:149], v[194:197], v[22:25]
	v_mfma_f32_16x16x32_bf16 v[14:17], v[160:163], v[194:197], v[14:17]
	v_mfma_f32_16x16x32_bf16 v[62:65], v[156:159], v[172:175], v[62:65]
	v_mfma_f32_16x16x32_bf16 v[58:61], v[164:167], v[172:175], v[58:61]
	v_mfma_f32_16x16x32_bf16 v[54:57], v[156:159], v[180:183], v[54:57]
	v_mfma_f32_16x16x32_bf16 v[46:49], v[164:167], v[180:183], v[46:49]
	v_mfma_f32_16x16x32_bf16 v[38:41], v[156:159], v[190:193], v[38:41]
	v_mfma_f32_16x16x32_bf16 v[30:33], v[164:167], v[190:193], v[30:33]
	v_mfma_f32_16x16x32_bf16 v[22:25], v[156:159], v[198:201], v[22:25]
	v_mfma_f32_16x16x32_bf16 v[14:17], v[164:167], v[198:201], v[14:17]
	v_mfma_f32_16x16x32_bf16 v[50:53], v[202:205], v[168:171], v[50:53]
	v_mfma_f32_16x16x32_bf16 v[42:45], v[210:213], v[168:171], v[42:45]
	v_mfma_f32_16x16x32_bf16 v[34:37], v[202:205], v[176:179], v[34:37]
	v_mfma_f32_16x16x32_bf16 v[26:29], v[210:213], v[176:179], v[26:29]
	v_mfma_f32_16x16x32_bf16 v[18:21], v[202:205], v[186:189], v[18:21]
	v_mfma_f32_16x16x32_bf16 v[10:13], v[210:213], v[186:189], v[10:13]
	v_mfma_f32_16x16x32_bf16 v[6:9], v[202:205], v[194:197], v[6:9]
	v_mfma_f32_16x16x32_bf16 v[2:5], v[210:213], v[194:197], v[2:5]
	v_mfma_f32_16x16x32_bf16 v[50:53], v[206:209], v[172:175], v[50:53]
	v_mfma_f32_16x16x32_bf16 v[42:45], v[214:217], v[172:175], v[42:45]
	v_mfma_f32_16x16x32_bf16 v[34:37], v[206:209], v[180:183], v[34:37]
	v_mfma_f32_16x16x32_bf16 v[26:29], v[214:217], v[180:183], v[26:29]
	v_mfma_f32_16x16x32_bf16 v[18:21], v[206:209], v[190:193], v[18:21]
	v_mfma_f32_16x16x32_bf16 v[10:13], v[214:217], v[190:193], v[10:13]
	v_mfma_f32_16x16x32_bf16 v[6:9], v[206:209], v[198:201], v[6:9]
	v_mfma_f32_16x16x32_bf16 v[2:5], v[214:217], v[198:201], v[2:5]
	s_setprio 0
	s_add_i32 s61, s61, 2
	s_add_u32 s22, s22, 0x100
	s_addc_u32 s23, s23, 0
	s_add_u32 s59, s59, 0x100
	s_addc_u32 s60, s60, 0
	s_cmp_gt_u32 s61, 29
	s_barrier
	s_cbranch_scc1 .Lgemm_epi_0
.LBB0_269:
	ds_read_b128 v[146:149], v152
	ds_read_b128 v[156:159], v152 offset:1024
	ds_read_b128 v[160:163], v152 offset:2048
	ds_read_b128 v[164:167], v152 offset:3072
	s_add_u32 s24, s22, 0xfff80080
	s_addc_u32 s25, s23, -1
	s_cmp_eq_u32 s61, 28
	s_cselect_b32 s27, s9, s25
	s_cselect_b32 s26, s53, s24
	s_cselect_b32 s25, s7, s60
	s_cselect_b32 s24, s58, s59
	s_add_i32 m0, s21, 0xc000
	ds_read_b128 v[168:171], v153
	ds_read_b128 v[172:175], v153 offset:1024
	ds_read_b128 v[176:179], v153 offset:2048
	ds_read_b128 v[180:183], v153 offset:3072
	ds_read_b128 v[186:189], v153 offset:4096
	ds_read_b128 v[190:193], v153 offset:5120
	ds_read_b128 v[194:197], v153 offset:6144
	ds_read_b128 v[198:201], v153 offset:7168
	ds_read_b128 v[202:205], v154
	ds_read_b128 v[206:209], v154 offset:1024
	ds_read_b128 v[210:213], v154 offset:2048
	ds_read_b128 v[214:217], v154 offset:3072
	global_load_lds_dwordx4 v138, s[22:23]
	s_add_i32 m0, s21, 0xe000
	s_nop 0
	global_load_lds_dwordx4 v140, s[22:23]
	s_waitcnt vmcnt(8)
	s_waitcnt lgkmcnt(4)
	s_barrier
	s_setprio 1
	v_mfma_f32_16x16x32_bf16 v[126:129], v[146:149], v[168:171], v[126:129]
	v_mfma_f32_16x16x32_bf16 v[122:125], v[160:163], v[168:171], v[122:125]
	v_mfma_f32_16x16x32_bf16 v[118:121], v[146:149], v[176:179], v[118:121]
	v_mfma_f32_16x16x32_bf16 v[110:113], v[160:163], v[176:179], v[110:113]
	v_mfma_f32_16x16x32_bf16 v[102:105], v[146:149], v[186:189], v[102:105]
	v_mfma_f32_16x16x32_bf16 v[94:97], v[160:163], v[186:189], v[94:97]
	v_mfma_f32_16x16x32_bf16 v[86:89], v[146:149], v[194:197], v[86:89]
	v_mfma_f32_16x16x32_bf16 v[78:81], v[160:163], v[194:197], v[78:81]
	v_mfma_f32_16x16x32_bf16 v[126:129], v[156:159], v[172:175], v[126:129]
	v_mfma_f32_16x16x32_bf16 v[122:125], v[164:167], v[172:175], v[122:125]
	v_mfma_f32_16x16x32_bf16 v[118:121], v[156:159], v[180:183], v[118:121]
	v_mfma_f32_16x16x32_bf16 v[110:113], v[164:167], v[180:183], v[110:113]
	v_mfma_f32_16x16x32_bf16 v[102:105], v[156:159], v[190:193], v[102:105]
	v_mfma_f32_16x16x32_bf16 v[94:97], v[164:167], v[190:193], v[94:97]
	v_mfma_f32_16x16x32_bf16 v[86:89], v[156:159], v[198:201], v[86:89]
	v_mfma_f32_16x16x32_bf16 v[78:81], v[164:167], v[198:201], v[78:81]
	s_waitcnt lgkmcnt(0)
	v_mfma_f32_16x16x32_bf16 v[114:117], v[202:205], v[168:171], v[114:117]
	v_mfma_f32_16x16x32_bf16 v[106:109], v[210:213], v[168:171], v[106:109]
	v_mfma_f32_16x16x32_bf16 v[98:101], v[202:205], v[176:179], v[98:101]
	v_mfma_f32_16x16x32_bf16 v[90:93], v[210:213], v[176:179], v[90:93]
	v_mfma_f32_16x16x32_bf16 v[82:85], v[202:205], v[186:189], v[82:85]
	v_mfma_f32_16x16x32_bf16 v[74:77], v[210:213], v[186:189], v[74:77]
	v_mfma_f32_16x16x32_bf16 v[70:73], v[202:205], v[194:197], v[70:73]
	v_mfma_f32_16x16x32_bf16 v[66:69], v[210:213], v[194:197], v[66:69]
	v_mfma_f32_16x16x32_bf16 v[114:117], v[206:209], v[172:175], v[114:117]
	v_mfma_f32_16x16x32_bf16 v[106:109], v[214:217], v[172:175], v[106:109]
	v_mfma_f32_16x16x32_bf16 v[98:101], v[206:209], v[180:183], v[98:101]
	v_mfma_f32_16x16x32_bf16 v[90:93], v[214:217], v[180:183], v[90:93]
	v_mfma_f32_16x16x32_bf16 v[82:85], v[206:209], v[190:193], v[82:85]
	v_mfma_f32_16x16x32_bf16 v[74:77], v[214:217], v[190:193], v[74:77]
	v_mfma_f32_16x16x32_bf16 v[70:73], v[206:209], v[198:201], v[70:73]
	v_mfma_f32_16x16x32_bf16 v[66:69], v[214:217], v[198:201], v[66:69]
	s_setprio 0
	s_barrier
	s_add_i32 s68, s45, s29
	v_lshl_add_u64 v[218:219], s[24:25], 0, v[134:135]
	s_mov_b32 m0, s68
	global_load_lds_dwordx4 v134, s[24:25]
	v_lshl_add_u64 v[220:221], s[24:25], 0, v[130:131]
	s_add_i32 m0, s68, 0x2000
	s_nop 0
	global_load_lds_dwordx4 v130, s[24:25]
	s_mov_b32 m0, s21
	v_lshl_add_u64 v[222:223], s[26:27], 0, v[136:137]
	ds_read_b128 v[168:171], v153 offset:16384
	ds_read_b128 v[172:175], v153 offset:17408
	ds_read_b128 v[176:179], v153 offset:18432
	ds_read_b128 v[180:183], v153 offset:19456
	ds_read_b128 v[186:189], v153 offset:20480
	ds_read_b128 v[190:193], v153 offset:21504
	ds_read_b128 v[194:197], v153 offset:22528
	ds_read_b128 v[198:201], v153 offset:23552
	global_load_lds_dwordx4 v136, s[26:27]
	v_lshl_add_u64 v[224:225], s[26:27], 0, v[132:133]
	s_mov_b32 m0, s34
	s_nop 0
	global_load_lds_dwordx4 v132, s[26:27]
	s_waitcnt vmcnt(6)
	s_waitcnt lgkmcnt(0)
	s_barrier
	s_setprio 1
	v_mfma_f32_16x16x32_bf16 v[62:65], v[146:149], v[168:171], v[62:65]
	v_mfma_f32_16x16x32_bf16 v[58:61], v[160:163], v[168:171], v[58:61]
	v_mfma_f32_16x16x32_bf16 v[54:57], v[146:149], v[176:179], v[54:57]
	v_mfma_f32_16x16x32_bf16 v[46:49], v[160:163], v[176:179], v[46:49]
	v_mfma_f32_16x16x32_bf16 v[38:41], v[146:149], v[186:189], v[38:41]
	v_mfma_f32_16x16x32_bf16 v[30:33], v[160:163], v[186:189], v[30:33]
	v_mfma_f32_16x16x32_bf16 v[22:25], v[146:149], v[194:197], v[22:25]
	v_mfma_f32_16x16x32_bf16 v[14:17], v[160:163], v[194:197], v[14:17]
	v_mfma_f32_16x16x32_bf16 v[62:65], v[156:159], v[172:175], v[62:65]
	v_mfma_f32_16x16x32_bf16 v[58:61], v[164:167], v[172:175], v[58:61]
	v_mfma_f32_16x16x32_bf16 v[54:57], v[156:159], v[180:183], v[54:57]
	v_mfma_f32_16x16x32_bf16 v[46:49], v[164:167], v[180:183], v[46:49]
	v_mfma_f32_16x16x32_bf16 v[38:41], v[156:159], v[190:193], v[38:41]
	v_mfma_f32_16x16x32_bf16 v[30:33], v[164:167], v[190:193], v[30:33]
	v_mfma_f32_16x16x32_bf16 v[22:25], v[156:159], v[198:201], v[22:25]
	v_mfma_f32_16x16x32_bf16 v[14:17], v[164:167], v[198:201], v[14:17]
	v_mfma_f32_16x16x32_bf16 v[50:53], v[202:205], v[168:171], v[50:53]
	v_mfma_f32_16x16x32_bf16 v[42:45], v[210:213], v[168:171], v[42:45]
	v_mfma_f32_16x16x32_bf16 v[34:37], v[202:205], v[176:179], v[34:37]
	v_mfma_f32_16x16x32_bf16 v[26:29], v[210:213], v[176:179], v[26:29]
	v_mfma_f32_16x16x32_bf16 v[18:21], v[202:205], v[186:189], v[18:21]
	v_mfma_f32_16x16x32_bf16 v[10:13], v[210:213], v[186:189], v[10:13]
	v_mfma_f32_16x16x32_bf16 v[6:9], v[202:205], v[194:197], v[6:9]
	v_mfma_f32_16x16x32_bf16 v[2:5], v[210:213], v[194:197], v[2:5]
	v_mfma_f32_16x16x32_bf16 v[50:53], v[206:209], v[172:175], v[50:53]
	v_mfma_f32_16x16x32_bf16 v[42:45], v[214:217], v[172:175], v[42:45]
	v_mfma_f32_16x16x32_bf16 v[34:37], v[206:209], v[180:183], v[34:37]
	v_mfma_f32_16x16x32_bf16 v[26:29], v[214:217], v[180:183], v[26:29]
	v_mfma_f32_16x16x32_bf16 v[18:21], v[206:209], v[190:193], v[18:21]
	v_mfma_f32_16x16x32_bf16 v[10:13], v[214:217], v[190:193], v[10:13]
	v_mfma_f32_16x16x32_bf16 v[6:9], v[206:209], v[198:201], v[6:9]
	v_mfma_f32_16x16x32_bf16 v[2:5], v[214:217], v[198:201], v[2:5]
	s_setprio 0
	s_barrier
	s_add_u32 s68, s24, 0x80000
	s_addc_u32 s69, s25, 0
	s_add_i32 s70, s46, s29
	s_mov_b32 m0, s70
	s_nop 0
	global_load_lds_dwordx4 v134, s[68:69]
	s_add_i32 m0, s70, 0x2000
	s_nop 0
	global_load_lds_dwordx4 v130, s[68:69]
	s_add_i32 s68, 0, 0x18000
	v_add_u32_e32 v155, s68, v150
	ds_read_b128 v[146:149], v155
	ds_read_b128 v[156:159], v155 offset:1024
	ds_read_b128 v[160:163], v155 offset:2048
	ds_read_b128 v[164:167], v155 offset:3072
	s_add_u32 s26, s26, 0x80000
	s_addc_u32 s27, s27, 0
	s_mov_b32 m0, s35
	ds_read_b128 v[168:171], v153 offset:32768
	ds_read_b128 v[172:175], v153 offset:33792
	ds_read_b128 v[176:179], v153 offset:34816
	ds_read_b128 v[180:183], v153 offset:35840
	ds_read_b128 v[186:189], v153 offset:36864
	ds_read_b128 v[190:193], v153 offset:37888
	ds_read_b128 v[194:197], v153 offset:38912
	ds_read_b128 v[198:201], v153 offset:39936
	v_add_u32_e32 v214, 0x1c000, v150
	ds_read_b128 v[202:205], v214
	ds_read_b128 v[206:209], v214 offset:1024
	ds_read_b128 v[210:213], v214 offset:2048
	ds_read_b128 v[214:217], v214 offset:3072
	global_load_lds_dwordx4 v136, s[26:27]
	s_mov_b32 m0, s36
	s_nop 0
	global_load_lds_dwordx4 v132, s[26:27]
	s_waitcnt vmcnt(8)
	s_waitcnt lgkmcnt(0)
	s_barrier
	s_setprio 1
	v_mfma_f32_16x16x32_bf16 v[126:129], v[146:149], v[168:171], v[126:129]
	v_mfma_f32_16x16x32_bf16 v[122:125], v[160:163], v[168:171], v[122:125]
	v_mfma_f32_16x16x32_bf16 v[118:121], v[146:149], v[176:179], v[118:121]
	v_mfma_f32_16x16x32_bf16 v[110:113], v[160:163], v[176:179], v[110:113]
	v_mfma_f32_16x16x32_bf16 v[102:105], v[146:149], v[186:189], v[102:105]
	v_mfma_f32_16x16x32_bf16 v[94:97], v[160:163], v[186:189], v[94:97]
	v_mfma_f32_16x16x32_bf16 v[86:89], v[146:149], v[194:197], v[86:89]
	v_mfma_f32_16x16x32_bf16 v[78:81], v[160:163], v[194:197], v[78:81]
	v_mfma_f32_16x16x32_bf16 v[126:129], v[156:159], v[172:175], v[126:129]
	v_mfma_f32_16x16x32_bf16 v[122:125], v[164:167], v[172:175], v[122:125]
	v_mfma_f32_16x16x32_bf16 v[118:121], v[156:159], v[180:183], v[118:121]
	v_mfma_f32_16x16x32_bf16 v[110:113], v[164:167], v[180:183], v[110:113]
	v_mfma_f32_16x16x32_bf16 v[102:105], v[156:159], v[190:193], v[102:105]
	v_mfma_f32_16x16x32_bf16 v[94:97], v[164:167], v[190:193], v[94:97]
	v_mfma_f32_16x16x32_bf16 v[86:89], v[156:159], v[198:201], v[86:89]
	v_mfma_f32_16x16x32_bf16 v[78:81], v[164:167], v[198:201], v[78:81]
	v_mfma_f32_16x16x32_bf16 v[114:117], v[202:205], v[168:171], v[114:117]
	v_mfma_f32_16x16x32_bf16 v[106:109], v[210:213], v[168:171], v[106:109]
	v_mfma_f32_16x16x32_bf16 v[98:101], v[202:205], v[176:179], v[98:101]
	v_mfma_f32_16x16x32_bf16 v[90:93], v[210:213], v[176:179], v[90:93]
	v_mfma_f32_16x16x32_bf16 v[82:85], v[202:205], v[186:189], v[82:85]
	v_mfma_f32_16x16x32_bf16 v[74:77], v[210:213], v[186:189], v[74:77]
	v_mfma_f32_16x16x32_bf16 v[70:73], v[202:205], v[194:197], v[70:73]
	v_mfma_f32_16x16x32_bf16 v[66:69], v[210:213], v[194:197], v[66:69]
	v_mfma_f32_16x16x32_bf16 v[114:117], v[206:209], v[172:175], v[114:117]
	v_mfma_f32_16x16x32_bf16 v[106:109], v[214:217], v[172:175], v[106:109]
	v_mfma_f32_16x16x32_bf16 v[98:101], v[206:209], v[180:183], v[98:101]
	v_mfma_f32_16x16x32_bf16 v[90:93], v[214:217], v[180:183], v[90:93]
	v_mfma_f32_16x16x32_bf16 v[82:85], v[206:209], v[190:193], v[82:85]
	v_mfma_f32_16x16x32_bf16 v[74:77], v[214:217], v[190:193], v[74:77]
	v_mfma_f32_16x16x32_bf16 v[70:73], v[206:209], v[198:201], v[70:73]
	v_mfma_f32_16x16x32_bf16 v[66:69], v[214:217], v[198:201], v[66:69]
	s_setprio 0
	s_barrier
	s_add_i32 s26, 0, 0x1c000
	s_add_i32 s27, s68, s29
	v_lshl_add_u64 v[218:219], v[218:219], 0, s[4:5]
	s_mov_b32 m0, s27
	global_load_lds_dwordx4 v[218:219], off
	v_lshl_add_u64 v[218:219], v[220:221], 0, s[4:5]
	s_add_i32 m0, s27, 0x2000
	s_nop 0
	global_load_lds_dwordx4 v[218:219], off
	s_mov_b32 m0, s41
	v_lshl_add_u64 v[218:219], v[222:223], 0, s[4:5]
	ds_read_b128 v[168:171], v153 offset:49152
	ds_read_b128 v[172:175], v153 offset:50176
	ds_read_b128 v[176:179], v153 offset:51200
	ds_read_b128 v[180:183], v153 offset:52224
	ds_read_b128 v[186:189], v153 offset:53248
	ds_read_b128 v[190:193], v153 offset:54272
	ds_read_b128 v[194:197], v153 offset:55296
	ds_read_b128 v[198:201], v153 offset:56320
	global_load_lds_dwordx4 v[218:219], off
	v_lshl_add_u64 v[218:219], v[224:225], 0, s[4:5]
	s_mov_b32 m0, s42
	s_nop 0
	global_load_lds_dwordx4 v[218:219], off
	s_add_u32 s24, s24, 0x80080
	s_addc_u32 s25, s25, 0
	s_add_i32 s26, s26, s29
	s_mov_b32 m0, s26
	s_nop 0
	global_load_lds_dwordx4 v134, s[24:25]
	s_add_i32 m0, s26, 0x2000
	s_nop 0
	global_load_lds_dwordx4 v130, s[24:25]
	s_waitcnt vmcnt(8)
	s_waitcnt lgkmcnt(0)
	s_barrier
	s_setprio 1
	v_mfma_f32_16x16x32_bf16 v[62:65], v[146:149], v[168:171], v[62:65]
	v_mfma_f32_16x16x32_bf16 v[58:61], v[160:163], v[168:171], v[58:61]
	v_mfma_f32_16x16x32_bf16 v[54:57], v[146:149], v[176:179], v[54:57]
	v_mfma_f32_16x16x32_bf16 v[46:49], v[160:163], v[176:179], v[46:49]
	v_mfma_f32_16x16x32_bf16 v[38:41], v[146:149], v[186:189], v[38:41]
	v_mfma_f32_16x16x32_bf16 v[30:33], v[160:163], v[186:189], v[30:33]
	v_mfma_f32_16x16x32_bf16 v[22:25], v[146:149], v[194:197], v[22:25]
	v_mfma_f32_16x16x32_bf16 v[14:17], v[160:163], v[194:197], v[14:17]
	v_mfma_f32_16x16x32_bf16 v[62:65], v[156:159], v[172:175], v[62:65]
	v_mfma_f32_16x16x32_bf16 v[58:61], v[164:167], v[172:175], v[58:61]
	v_mfma_f32_16x16x32_bf16 v[54:57], v[156:159], v[180:183], v[54:57]
	v_mfma_f32_16x16x32_bf16 v[46:49], v[164:167], v[180:183], v[46:49]
	v_mfma_f32_16x16x32_bf16 v[38:41], v[156:159], v[190:193], v[38:41]
	v_mfma_f32_16x16x32_bf16 v[30:33], v[164:167], v[190:193], v[30:33]
	v_mfma_f32_16x16x32_bf16 v[22:25], v[156:159], v[198:201], v[22:25]
	v_mfma_f32_16x16x32_bf16 v[14:17], v[164:167], v[198:201], v[14:17]
	v_mfma_f32_16x16x32_bf16 v[50:53], v[202:205], v[168:171], v[50:53]
	v_mfma_f32_16x16x32_bf16 v[42:45], v[210:213], v[168:171], v[42:45]
	v_mfma_f32_16x16x32_bf16 v[34:37], v[202:205], v[176:179], v[34:37]
	v_mfma_f32_16x16x32_bf16 v[26:29], v[210:213], v[176:179], v[26:29]
	v_mfma_f32_16x16x32_bf16 v[18:21], v[202:205], v[186:189], v[18:21]
	v_mfma_f32_16x16x32_bf16 v[10:13], v[210:213], v[186:189], v[10:13]
	v_mfma_f32_16x16x32_bf16 v[6:9], v[202:205], v[194:197], v[6:9]
	v_mfma_f32_16x16x32_bf16 v[2:5], v[210:213], v[194:197], v[2:5]
	v_mfma_f32_16x16x32_bf16 v[50:53], v[206:209], v[172:175], v[50:53]
	v_mfma_f32_16x16x32_bf16 v[42:45], v[214:217], v[172:175], v[42:45]
	v_mfma_f32_16x16x32_bf16 v[34:37], v[206:209], v[180:183], v[34:37]
	v_mfma_f32_16x16x32_bf16 v[26:29], v[214:217], v[180:183], v[26:29]
	v_mfma_f32_16x16x32_bf16 v[18:21], v[206:209], v[190:193], v[18:21]
	v_mfma_f32_16x16x32_bf16 v[10:13], v[214:217], v[190:193], v[10:13]
	v_mfma_f32_16x16x32_bf16 v[6:9], v[206:209], v[198:201], v[6:9]
	v_mfma_f32_16x16x32_bf16 v[2:5], v[214:217], v[198:201], v[2:5]
	s_setprio 0
	s_add_i32 s61, s61, 2
	s_add_u32 s22, s22, 0x100
	s_addc_u32 s23, s23, 0
	s_add_u32 s59, s59, 0x100
	s_addc_u32 s60, s60, 0
	s_cmp_gt_u32 s61, 29
	s_barrier
	s_cbranch_scc0 .LBB0_269

.LBB0_456:
	s_ashr_i32 s23, s22, 31
	s_lshl_b64 s[26:27], s[22:23], 18
	s_add_u32 s26, s43, s26
	s_addc_u32 s27, s44, s27
	s_and_b64 s[4:5], s[4:5], exec
	s_cselect_b32 s23, s27, s31
	s_cselect_b32 s78, s26, s30
	s_add_u32 s79, s30, 0x100
	v_mov_b32_e32 v2, 0
	s_addc_u32 s80, s31, 0
	s_mov_b32 s81, -2
	v_mov_b32_e32 v3, v2
	v_mov_b32_e32 v4, v2
	v_mov_b32_e32 v5, v2
	v_mov_b32_e32 v6, v2
	v_mov_b32_e32 v7, v2
	v_mov_b32_e32 v8, v2
	v_mov_b32_e32 v9, v2
	v_mov_b32_e32 v10, v2
	v_mov_b32_e32 v11, v2
	v_mov_b32_e32 v12, v2
	v_mov_b32_e32 v13, v2
	v_mov_b32_e32 v18, v2
	v_mov_b32_e32 v19, v2
	v_mov_b32_e32 v20, v2
	v_mov_b32_e32 v21, v2
	v_mov_b32_e32 v26, v2
	v_mov_b32_e32 v27, v2
	v_mov_b32_e32 v28, v2
	v_mov_b32_e32 v29, v2
	v_mov_b32_e32 v34, v2
	v_mov_b32_e32 v35, v2
	v_mov_b32_e32 v36, v2
	v_mov_b32_e32 v37, v2
	v_mov_b32_e32 v42, v2
	v_mov_b32_e32 v43, v2
	v_mov_b32_e32 v44, v2
	v_mov_b32_e32 v45, v2
	v_mov_b32_e32 v50, v2
	v_mov_b32_e32 v51, v2
	v_mov_b32_e32 v52, v2
	v_mov_b32_e32 v53, v2
	v_mov_b32_e32 v14, v2
	v_mov_b32_e32 v15, v2
	v_mov_b32_e32 v16, v2
	v_mov_b32_e32 v17, v2
	v_mov_b32_e32 v22, v2
	v_mov_b32_e32 v23, v2
	v_mov_b32_e32 v24, v2
	v_mov_b32_e32 v25, v2
	v_mov_b32_e32 v30, v2
	v_mov_b32_e32 v31, v2
	v_mov_b32_e32 v32, v2
	v_mov_b32_e32 v33, v2
	v_mov_b32_e32 v38, v2
	v_mov_b32_e32 v39, v2
	v_mov_b32_e32 v40, v2
	v_mov_b32_e32 v41, v2
	v_mov_b32_e32 v46, v2
	v_mov_b32_e32 v47, v2
	v_mov_b32_e32 v48, v2
	v_mov_b32_e32 v49, v2
	v_mov_b32_e32 v54, v2
	v_mov_b32_e32 v55, v2
	v_mov_b32_e32 v56, v2
	v_mov_b32_e32 v57, v2
	v_mov_b32_e32 v58, v2
	v_mov_b32_e32 v59, v2
	v_mov_b32_e32 v60, v2
	v_mov_b32_e32 v61, v2
	v_mov_b32_e32 v62, v2
	v_mov_b32_e32 v63, v2
	v_mov_b32_e32 v64, v2
	v_mov_b32_e32 v65, v2
	v_mov_b32_e32 v66, v2
	v_mov_b32_e32 v67, v2
	v_mov_b32_e32 v68, v2
	v_mov_b32_e32 v69, v2
	v_mov_b32_e32 v70, v2
	v_mov_b32_e32 v71, v2
	v_mov_b32_e32 v72, v2
	v_mov_b32_e32 v73, v2
	v_mov_b32_e32 v78, v2
	v_mov_b32_e32 v79, v2
	v_mov_b32_e32 v80, v2
	v_mov_b32_e32 v81, v2
	v_mov_b32_e32 v86, v2
	v_mov_b32_e32 v87, v2
	v_mov_b32_e32 v88, v2
	v_mov_b32_e32 v89, v2
	v_mov_b32_e32 v94, v2
	v_mov_b32_e32 v95, v2
	v_mov_b32_e32 v96, v2
	v_mov_b32_e32 v97, v2
	v_mov_b32_e32 v102, v2
	v_mov_b32_e32 v103, v2
	v_mov_b32_e32 v104, v2
	v_mov_b32_e32 v105, v2
	v_mov_b32_e32 v110, v2
	v_mov_b32_e32 v111, v2
	v_mov_b32_e32 v112, v2
	v_mov_b32_e32 v113, v2
	v_mov_b32_e32 v118, v2
	v_mov_b32_e32 v119, v2
	v_mov_b32_e32 v120, v2
	v_mov_b32_e32 v121, v2
	v_mov_b32_e32 v74, v2
	v_mov_b32_e32 v75, v2
	v_mov_b32_e32 v76, v2
	v_mov_b32_e32 v77, v2
	v_mov_b32_e32 v82, v2
	v_mov_b32_e32 v83, v2
	v_mov_b32_e32 v84, v2
	v_mov_b32_e32 v85, v2
	v_mov_b32_e32 v90, v2
	v_mov_b32_e32 v91, v2
	v_mov_b32_e32 v92, v2
	v_mov_b32_e32 v93, v2
	v_mov_b32_e32 v98, v2
	v_mov_b32_e32 v99, v2
	v_mov_b32_e32 v100, v2
	v_mov_b32_e32 v101, v2
	v_mov_b32_e32 v106, v2
	v_mov_b32_e32 v107, v2
	v_mov_b32_e32 v108, v2
	v_mov_b32_e32 v109, v2
	v_mov_b32_e32 v114, v2
	v_mov_b32_e32 v115, v2
	v_mov_b32_e32 v116, v2
	v_mov_b32_e32 v117, v2
	v_mov_b32_e32 v122, v2
	v_mov_b32_e32 v123, v2
	v_mov_b32_e32 v124, v2
	v_mov_b32_e32 v125, v2
	v_mov_b32_e32 v126, v2
	v_mov_b32_e32 v127, v2
	v_mov_b32_e32 v128, v2
	v_mov_b32_e32 v129, v2
	s_cmp_eq_u32 s98, 0
	s_cbranch_scc1 .LBB0_457
	ds_read_b128 v[154:157], v150
	ds_read_b128 v[158:161], v150 offset:1024
	ds_read_b128 v[162:165], v150 offset:2048
	ds_read_b128 v[166:169], v150 offset:3072
	s_add_u32 s4, s28, 0x100
	s_addc_u32 s5, s29, 0
	s_cmp_eq_u32 s81, 4
	s_cselect_b32 s35, s25, s5
	s_cselect_b32 s34, s24, s4
	s_cselect_b32 s31, s23, s80
	s_cselect_b32 s30, s78, s79
	v_lshl_add_u64 v[146:147], s[28:29], 0, v[138:139]
	s_add_i32 m0, s46, 0xc000
	ds_read_b128 v[170:173], v151
	ds_read_b128 v[174:177], v151 offset:1024
	ds_read_b128 v[178:181], v151 offset:2048
	ds_read_b128 v[186:189], v151 offset:3072
	ds_read_b128 v[190:193], v151 offset:4096
	ds_read_b128 v[194:197], v151 offset:5120
	ds_read_b128 v[198:201], v151 offset:6144
	ds_read_b128 v[202:205], v151 offset:7168
	global_load_lds_dwordx4 v[146:147], off
	v_lshl_add_u64 v[146:147], s[28:29], 0, v[140:141]
	s_add_i32 m0, s46, 0xe000
	s_nop 0
	global_load_lds_dwordx4 v[146:147], off
	ds_read_b128 v[206:209], v152
	ds_read_b128 v[210:213], v152 offset:1024
	ds_read_b128 v[214:217], v152 offset:2048
	ds_read_b128 v[218:221], v152 offset:3072
	s_waitcnt vmcnt(24)
	s_waitcnt lgkmcnt(4)
	s_barrier
	s_setprio 1
	v_mfma_f32_16x16x32_bf16 v[126:129], v[154:157], v[170:173], v[126:129]
	v_mfma_f32_16x16x32_bf16 v[122:125], v[162:165], v[170:173], v[122:125]
	v_mfma_f32_16x16x32_bf16 v[114:117], v[154:157], v[178:181], v[114:117]
	v_mfma_f32_16x16x32_bf16 v[106:109], v[162:165], v[178:181], v[106:109]
	v_mfma_f32_16x16x32_bf16 v[98:101], v[154:157], v[190:193], v[98:101]
	v_mfma_f32_16x16x32_bf16 v[90:93], v[162:165], v[190:193], v[90:93]
	v_mfma_f32_16x16x32_bf16 v[82:85], v[154:157], v[198:201], v[82:85]
	v_mfma_f32_16x16x32_bf16 v[74:77], v[162:165], v[198:201], v[74:77]
	v_mfma_f32_16x16x32_bf16 v[126:129], v[158:161], v[174:177], v[126:129]
	v_mfma_f32_16x16x32_bf16 v[122:125], v[166:169], v[174:177], v[122:125]
	v_mfma_f32_16x16x32_bf16 v[114:117], v[158:161], v[186:189], v[114:117]
	v_mfma_f32_16x16x32_bf16 v[106:109], v[166:169], v[186:189], v[106:109]
	v_mfma_f32_16x16x32_bf16 v[98:101], v[158:161], v[194:197], v[98:101]
	v_mfma_f32_16x16x32_bf16 v[90:93], v[166:169], v[194:197], v[90:93]
	v_mfma_f32_16x16x32_bf16 v[82:85], v[158:161], v[202:205], v[82:85]
	v_mfma_f32_16x16x32_bf16 v[74:77], v[166:169], v[202:205], v[74:77]
	s_waitcnt lgkmcnt(0)
	v_mfma_f32_16x16x32_bf16 v[118:121], v[206:209], v[170:173], v[118:121]
	v_mfma_f32_16x16x32_bf16 v[110:113], v[214:217], v[170:173], v[110:113]
	v_mfma_f32_16x16x32_bf16 v[102:105], v[206:209], v[178:181], v[102:105]
	v_mfma_f32_16x16x32_bf16 v[94:97], v[214:217], v[178:181], v[94:97]
	v_mfma_f32_16x16x32_bf16 v[86:89], v[206:209], v[190:193], v[86:89]
	v_mfma_f32_16x16x32_bf16 v[78:81], v[214:217], v[190:193], v[78:81]
	v_mfma_f32_16x16x32_bf16 v[70:73], v[206:209], v[198:201], v[70:73]
	v_mfma_f32_16x16x32_bf16 v[66:69], v[214:217], v[198:201], v[66:69]
	v_mfma_f32_16x16x32_bf16 v[118:121], v[210:213], v[174:177], v[118:121]
	v_mfma_f32_16x16x32_bf16 v[110:113], v[218:221], v[174:177], v[110:113]
	v_mfma_f32_16x16x32_bf16 v[102:105], v[210:213], v[186:189], v[102:105]
	v_mfma_f32_16x16x32_bf16 v[94:97], v[218:221], v[186:189], v[94:97]
	v_mfma_f32_16x16x32_bf16 v[86:89], v[210:213], v[194:197], v[86:89]
	v_mfma_f32_16x16x32_bf16 v[78:81], v[218:221], v[194:197], v[78:81]
	v_mfma_f32_16x16x32_bf16 v[70:73], v[210:213], v[202:205], v[70:73]
	v_mfma_f32_16x16x32_bf16 v[66:69], v[218:221], v[202:205], v[66:69]
	s_setprio 0
	s_barrier
	s_add_i32 s28, s61, s45
	v_lshl_add_u64 v[146:147], s[30:31], 0, v[132:133]
	s_mov_b32 m0, s28
	global_load_lds_dwordx4 v132, s[30:31]
	v_lshl_add_u64 v[182:183], s[30:31], 0, v[136:137]
	s_add_i32 m0, s28, 0x2000
	s_nop 0
	global_load_lds_dwordx4 v136, s[30:31]
	s_mov_b32 m0, s46
	v_lshl_add_u64 v[222:223], s[34:35], 0, v[130:131]
	ds_read_b128 v[170:173], v151 offset:16384
	ds_read_b128 v[174:177], v151 offset:17408
	ds_read_b128 v[178:181], v151 offset:18432
	ds_read_b128 v[186:189], v151 offset:19456
	ds_read_b128 v[190:193], v151 offset:20480
	ds_read_b128 v[194:197], v151 offset:21504
	ds_read_b128 v[198:201], v151 offset:22528
	ds_read_b128 v[202:205], v151 offset:23552
	global_load_lds_dwordx4 v130, s[34:35]
	v_lshl_add_u64 v[224:225], s[34:35], 0, v[134:135]
	s_mov_b32 m0, s47
	s_nop 0
	global_load_lds_dwordx4 v134, s[34:35]
	s_waitcnt vmcnt(22)
	s_waitcnt lgkmcnt(0)
	s_barrier
	s_setprio 1
	v_mfma_f32_16x16x32_bf16 v[62:65], v[154:157], v[170:173], v[62:65]
	v_mfma_f32_16x16x32_bf16 v[58:61], v[162:165], v[170:173], v[58:61]
	v_mfma_f32_16x16x32_bf16 v[54:57], v[154:157], v[178:181], v[54:57]
	v_mfma_f32_16x16x32_bf16 v[46:49], v[162:165], v[178:181], v[46:49]
	v_mfma_f32_16x16x32_bf16 v[38:41], v[154:157], v[190:193], v[38:41]
	v_mfma_f32_16x16x32_bf16 v[30:33], v[162:165], v[190:193], v[30:33]
	v_mfma_f32_16x16x32_bf16 v[22:25], v[154:157], v[198:201], v[22:25]
	v_mfma_f32_16x16x32_bf16 v[14:17], v[162:165], v[198:201], v[14:17]
	v_mfma_f32_16x16x32_bf16 v[62:65], v[158:161], v[174:177], v[62:65]
	v_mfma_f32_16x16x32_bf16 v[58:61], v[166:169], v[174:177], v[58:61]
	v_mfma_f32_16x16x32_bf16 v[54:57], v[158:161], v[186:189], v[54:57]
	v_mfma_f32_16x16x32_bf16 v[46:49], v[166:169], v[186:189], v[46:49]
	v_mfma_f32_16x16x32_bf16 v[38:41], v[158:161], v[194:197], v[38:41]
	v_mfma_f32_16x16x32_bf16 v[30:33], v[166:169], v[194:197], v[30:33]
	v_mfma_f32_16x16x32_bf16 v[22:25], v[158:161], v[202:205], v[22:25]
	v_mfma_f32_16x16x32_bf16 v[14:17], v[166:169], v[202:205], v[14:17]
	v_mfma_f32_16x16x32_bf16 v[50:53], v[206:209], v[170:173], v[50:53]
	v_mfma_f32_16x16x32_bf16 v[42:45], v[214:217], v[170:173], v[42:45]
	v_mfma_f32_16x16x32_bf16 v[34:37], v[206:209], v[178:181], v[34:37]
	v_mfma_f32_16x16x32_bf16 v[26:29], v[214:217], v[178:181], v[26:29]
	v_mfma_f32_16x16x32_bf16 v[18:21], v[206:209], v[190:193], v[18:21]
	v_mfma_f32_16x16x32_bf16 v[10:13], v[214:217], v[190:193], v[10:13]
	v_mfma_f32_16x16x32_bf16 v[6:9], v[206:209], v[198:201], v[6:9]
	v_mfma_f32_16x16x32_bf16 v[2:5], v[214:217], v[198:201], v[2:5]
	v_mfma_f32_16x16x32_bf16 v[50:53], v[210:213], v[174:177], v[50:53]
	v_mfma_f32_16x16x32_bf16 v[42:45], v[218:221], v[174:177], v[42:45]
	v_mfma_f32_16x16x32_bf16 v[34:37], v[210:213], v[186:189], v[34:37]
	v_mfma_f32_16x16x32_bf16 v[26:29], v[218:221], v[186:189], v[26:29]
	v_mfma_f32_16x16x32_bf16 v[18:21], v[210:213], v[194:197], v[18:21]
	v_mfma_f32_16x16x32_bf16 v[10:13], v[218:221], v[194:197], v[10:13]
	v_mfma_f32_16x16x32_bf16 v[6:9], v[210:213], v[202:205], v[6:9]
	v_mfma_f32_16x16x32_bf16 v[2:5], v[218:221], v[202:205], v[2:5]
	s_setprio 0
	s_barrier
	s_add_u32 s28, s30, 0x20000
	s_addc_u32 s29, s31, 0
	s_add_i32 s82, s71, s45
	s_mov_b32 m0, s82
	s_nop 0
	global_load_lds_dwordx4 v132, s[28:29]
	s_add_i32 m0, s82, 0x2000
	s_nop 0
	global_load_lds_dwordx4 v136, s[28:29]
	s_add_i32 s82, 0, 0x18000
	v_add_u32_e32 v153, s82, v148
	ds_read_b128 v[154:157], v153
	ds_read_b128 v[158:161], v153 offset:1024
	ds_read_b128 v[162:165], v153 offset:2048
	ds_read_b128 v[166:169], v153 offset:3072
	s_add_u32 s28, s34, 0xf0000
	s_addc_u32 s29, s35, 0
	s_mov_b32 m0, s50
	ds_read_b128 v[170:173], v151 offset:32768
	ds_read_b128 v[174:177], v151 offset:33792
	ds_read_b128 v[178:181], v151 offset:34816
	ds_read_b128 v[186:189], v151 offset:35840
	ds_read_b128 v[190:193], v151 offset:36864
	ds_read_b128 v[194:197], v151 offset:37888
	ds_read_b128 v[198:201], v151 offset:38912
	ds_read_b128 v[202:205], v151 offset:39936
	v_add_u32_e32 v218, 0x1c000, v148
	ds_read_b128 v[206:209], v218
	ds_read_b128 v[210:213], v218 offset:1024
	ds_read_b128 v[214:217], v218 offset:2048
	ds_read_b128 v[218:221], v218 offset:3072
	global_load_lds_dwordx4 v130, s[28:29]
	s_mov_b32 m0, s51
	s_nop 0
	global_load_lds_dwordx4 v134, s[28:29]
	s_waitcnt vmcnt(8)
	s_waitcnt lgkmcnt(0)
	s_barrier
	s_setprio 1
	v_mfma_f32_16x16x32_bf16 v[126:129], v[154:157], v[170:173], v[126:129]
	v_mfma_f32_16x16x32_bf16 v[122:125], v[162:165], v[170:173], v[122:125]
	v_mfma_f32_16x16x32_bf16 v[114:117], v[154:157], v[178:181], v[114:117]
	v_mfma_f32_16x16x32_bf16 v[106:109], v[162:165], v[178:181], v[106:109]
	v_mfma_f32_16x16x32_bf16 v[98:101], v[154:157], v[190:193], v[98:101]
	v_mfma_f32_16x16x32_bf16 v[90:93], v[162:165], v[190:193], v[90:93]
	v_mfma_f32_16x16x32_bf16 v[82:85], v[154:157], v[198:201], v[82:85]
	v_mfma_f32_16x16x32_bf16 v[74:77], v[162:165], v[198:201], v[74:77]
	v_mfma_f32_16x16x32_bf16 v[126:129], v[158:161], v[174:177], v[126:129]
	v_mfma_f32_16x16x32_bf16 v[122:125], v[166:169], v[174:177], v[122:125]
	v_mfma_f32_16x16x32_bf16 v[114:117], v[158:161], v[186:189], v[114:117]
	v_mfma_f32_16x16x32_bf16 v[106:109], v[166:169], v[186:189], v[106:109]
	v_mfma_f32_16x16x32_bf16 v[98:101], v[158:161], v[194:197], v[98:101]
	v_mfma_f32_16x16x32_bf16 v[90:93], v[166:169], v[194:197], v[90:93]
	v_mfma_f32_16x16x32_bf16 v[82:85], v[158:161], v[202:205], v[82:85]
	v_mfma_f32_16x16x32_bf16 v[74:77], v[166:169], v[202:205], v[74:77]
	v_mfma_f32_16x16x32_bf16 v[118:121], v[206:209], v[170:173], v[118:121]
	v_mfma_f32_16x16x32_bf16 v[110:113], v[214:217], v[170:173], v[110:113]
	v_mfma_f32_16x16x32_bf16 v[102:105], v[206:209], v[178:181], v[102:105]
	v_mfma_f32_16x16x32_bf16 v[94:97], v[214:217], v[178:181], v[94:97]
	v_mfma_f32_16x16x32_bf16 v[86:89], v[206:209], v[190:193], v[86:89]
	v_mfma_f32_16x16x32_bf16 v[78:81], v[214:217], v[190:193], v[78:81]
	v_mfma_f32_16x16x32_bf16 v[70:73], v[206:209], v[198:201], v[70:73]
	v_mfma_f32_16x16x32_bf16 v[66:69], v[214:217], v[198:201], v[66:69]
	v_mfma_f32_16x16x32_bf16 v[118:121], v[210:213], v[174:177], v[118:121]
	v_mfma_f32_16x16x32_bf16 v[110:113], v[218:221], v[174:177], v[110:113]
	v_mfma_f32_16x16x32_bf16 v[102:105], v[210:213], v[186:189], v[102:105]
	v_mfma_f32_16x16x32_bf16 v[94:97], v[218:221], v[186:189], v[94:97]
	v_mfma_f32_16x16x32_bf16 v[86:89], v[210:213], v[194:197], v[86:89]
	v_mfma_f32_16x16x32_bf16 v[78:81], v[218:221], v[194:197], v[78:81]
	v_mfma_f32_16x16x32_bf16 v[70:73], v[210:213], v[202:205], v[70:73]
	v_mfma_f32_16x16x32_bf16 v[66:69], v[218:221], v[202:205], v[66:69]
	s_setprio 0
	s_barrier
	s_add_i32 s34, 0, 0x1c000
	s_add_i32 s28, s82, s45
	v_lshl_add_u64 v[146:147], v[146:147], 0, s[6:7]
	s_mov_b32 m0, s28
	global_load_lds_dwordx4 v[146:147], off
	v_lshl_add_u64 v[146:147], v[182:183], 0, s[6:7]
	s_add_i32 m0, s28, 0x2000
	s_nop 0
	global_load_lds_dwordx4 v[146:147], off
	s_mov_b32 m0, s53
	v_lshl_add_u64 v[146:147], v[222:223], 0, s[6:7]
	ds_read_b128 v[170:173], v151 offset:49152
	ds_read_b128 v[174:177], v151 offset:50176
	ds_read_b128 v[178:181], v151 offset:51200
	ds_read_b128 v[186:189], v151 offset:52224
	ds_read_b128 v[190:193], v151 offset:53248
	ds_read_b128 v[194:197], v151 offset:54272
	ds_read_b128 v[198:201], v151 offset:55296
	ds_read_b128 v[202:205], v151 offset:56320
	global_load_lds_dwordx4 v[146:147], off
	v_lshl_add_u64 v[146:147], v[224:225], 0, s[6:7]
	s_mov_b32 m0, s58
	s_nop 0
	global_load_lds_dwordx4 v[146:147], off
	s_add_u32 s28, s30, 0x20080
	s_addc_u32 s29, s31, 0
	s_add_i32 s30, s34, s45
	s_mov_b32 m0, s30
	s_nop 0
	global_load_lds_dwordx4 v132, s[28:29]
	s_add_i32 m0, s30, 0x2000
	s_nop 0
	global_load_lds_dwordx4 v136, s[28:29]
	s_waitcnt vmcnt(8)
	s_waitcnt lgkmcnt(0)
	s_barrier
	s_setprio 1
	v_mfma_f32_16x16x32_bf16 v[62:65], v[154:157], v[170:173], v[62:65]
	v_mfma_f32_16x16x32_bf16 v[58:61], v[162:165], v[170:173], v[58:61]
	v_mfma_f32_16x16x32_bf16 v[54:57], v[154:157], v[178:181], v[54:57]
	v_mfma_f32_16x16x32_bf16 v[46:49], v[162:165], v[178:181], v[46:49]
	v_mfma_f32_16x16x32_bf16 v[38:41], v[154:157], v[190:193], v[38:41]
	v_mfma_f32_16x16x32_bf16 v[30:33], v[162:165], v[190:193], v[30:33]
	v_mfma_f32_16x16x32_bf16 v[22:25], v[154:157], v[198:201], v[22:25]
	v_mfma_f32_16x16x32_bf16 v[14:17], v[162:165], v[198:201], v[14:17]
	v_mfma_f32_16x16x32_bf16 v[62:65], v[158:161], v[174:177], v[62:65]
	v_mfma_f32_16x16x32_bf16 v[58:61], v[166:169], v[174:177], v[58:61]
	v_mfma_f32_16x16x32_bf16 v[54:57], v[158:161], v[186:189], v[54:57]
	v_mfma_f32_16x16x32_bf16 v[46:49], v[166:169], v[186:189], v[46:49]
	v_mfma_f32_16x16x32_bf16 v[38:41], v[158:161], v[194:197], v[38:41]
	v_mfma_f32_16x16x32_bf16 v[30:33], v[166:169], v[194:197], v[30:33]
	v_mfma_f32_16x16x32_bf16 v[22:25], v[158:161], v[202:205], v[22:25]
	v_mfma_f32_16x16x32_bf16 v[14:17], v[166:169], v[202:205], v[14:17]
	v_mfma_f32_16x16x32_bf16 v[50:53], v[206:209], v[170:173], v[50:53]
	v_mfma_f32_16x16x32_bf16 v[42:45], v[214:217], v[170:173], v[42:45]
	v_mfma_f32_16x16x32_bf16 v[34:37], v[206:209], v[178:181], v[34:37]
	v_mfma_f32_16x16x32_bf16 v[26:29], v[214:217], v[178:181], v[26:29]
	v_mfma_f32_16x16x32_bf16 v[18:21], v[206:209], v[190:193], v[18:21]
	v_mfma_f32_16x16x32_bf16 v[10:13], v[214:217], v[190:193], v[10:13]
	v_mfma_f32_16x16x32_bf16 v[6:9], v[206:209], v[198:201], v[6:9]
	v_mfma_f32_16x16x32_bf16 v[2:5], v[214:217], v[198:201], v[2:5]
	v_mfma_f32_16x16x32_bf16 v[50:53], v[210:213], v[174:177], v[50:53]
	v_mfma_f32_16x16x32_bf16 v[42:45], v[218:221], v[174:177], v[42:45]
	v_mfma_f32_16x16x32_bf16 v[34:37], v[210:213], v[186:189], v[34:37]
	v_mfma_f32_16x16x32_bf16 v[26:29], v[218:221], v[186:189], v[26:29]
	v_mfma_f32_16x16x32_bf16 v[18:21], v[210:213], v[194:197], v[18:21]
	v_mfma_f32_16x16x32_bf16 v[10:13], v[218:221], v[194:197], v[10:13]
	v_mfma_f32_16x16x32_bf16 v[6:9], v[210:213], v[202:205], v[6:9]
	v_mfma_f32_16x16x32_bf16 v[2:5], v[218:221], v[202:205], v[2:5]
	s_setprio 0
	s_add_i32 s81, s81, 2
	s_add_u32 s79, s79, 0x100
	s_addc_u32 s80, s80, 0
	s_cmp_gt_u32 s81, 5
	s_mov_b64 s[28:29], s[4:5]
	s_barrier
	s_cbranch_scc1 .Lgemm_epi_1
.LBB0_457:
	ds_read_b128 v[154:157], v150
	ds_read_b128 v[158:161], v150 offset:1024
	ds_read_b128 v[162:165], v150 offset:2048
	ds_read_b128 v[166:169], v150 offset:3072
	s_add_u32 s4, s28, 0x100
	s_addc_u32 s5, s29, 0
	s_cmp_eq_u32 s81, 4
	s_cselect_b32 s35, s25, s5
	s_cselect_b32 s34, s24, s4
	s_cselect_b32 s31, s23, s80
	s_cselect_b32 s30, s78, s79
	v_lshl_add_u64 v[146:147], s[28:29], 0, v[138:139]
	s_add_i32 m0, s46, 0xc000
	ds_read_b128 v[170:173], v151
	ds_read_b128 v[174:177], v151 offset:1024
	ds_read_b128 v[178:181], v151 offset:2048
	ds_read_b128 v[186:189], v151 offset:3072
	ds_read_b128 v[190:193], v151 offset:4096
	ds_read_b128 v[194:197], v151 offset:5120
	ds_read_b128 v[198:201], v151 offset:6144
	ds_read_b128 v[202:205], v151 offset:7168
	global_load_lds_dwordx4 v[146:147], off
	v_lshl_add_u64 v[146:147], s[28:29], 0, v[140:141]
	s_add_i32 m0, s46, 0xe000
	s_nop 0
	global_load_lds_dwordx4 v[146:147], off
	ds_read_b128 v[206:209], v152
	ds_read_b128 v[210:213], v152 offset:1024
	ds_read_b128 v[214:217], v152 offset:2048
	ds_read_b128 v[218:221], v152 offset:3072
	s_waitcnt vmcnt(8)
	s_waitcnt lgkmcnt(4)
	s_barrier
	s_setprio 1
	v_mfma_f32_16x16x32_bf16 v[126:129], v[154:157], v[170:173], v[126:129]
	v_mfma_f32_16x16x32_bf16 v[122:125], v[162:165], v[170:173], v[122:125]
	v_mfma_f32_16x16x32_bf16 v[114:117], v[154:157], v[178:181], v[114:117]
	v_mfma_f32_16x16x32_bf16 v[106:109], v[162:165], v[178:181], v[106:109]
	v_mfma_f32_16x16x32_bf16 v[98:101], v[154:157], v[190:193], v[98:101]
	v_mfma_f32_16x16x32_bf16 v[90:93], v[162:165], v[190:193], v[90:93]
	v_mfma_f32_16x16x32_bf16 v[82:85], v[154:157], v[198:201], v[82:85]
	v_mfma_f32_16x16x32_bf16 v[74:77], v[162:165], v[198:201], v[74:77]
	v_mfma_f32_16x16x32_bf16 v[126:129], v[158:161], v[174:177], v[126:129]
	v_mfma_f32_16x16x32_bf16 v[122:125], v[166:169], v[174:177], v[122:125]
	v_mfma_f32_16x16x32_bf16 v[114:117], v[158:161], v[186:189], v[114:117]
	v_mfma_f32_16x16x32_bf16 v[106:109], v[166:169], v[186:189], v[106:109]
	v_mfma_f32_16x16x32_bf16 v[98:101], v[158:161], v[194:197], v[98:101]
	v_mfma_f32_16x16x32_bf16 v[90:93], v[166:169], v[194:197], v[90:93]
	v_mfma_f32_16x16x32_bf16 v[82:85], v[158:161], v[202:205], v[82:85]
	v_mfma_f32_16x16x32_bf16 v[74:77], v[166:169], v[202:205], v[74:77]
	s_waitcnt lgkmcnt(0)
	v_mfma_f32_16x16x32_bf16 v[118:121], v[206:209], v[170:173], v[118:121]
	v_mfma_f32_16x16x32_bf16 v[110:113], v[214:217], v[170:173], v[110:113]
	v_mfma_f32_16x16x32_bf16 v[102:105], v[206:209], v[178:181], v[102:105]
	v_mfma_f32_16x16x32_bf16 v[94:97], v[214:217], v[178:181], v[94:97]
	v_mfma_f32_16x16x32_bf16 v[86:89], v[206:209], v[190:193], v[86:89]
	v_mfma_f32_16x16x32_bf16 v[78:81], v[214:217], v[190:193], v[78:81]
	v_mfma_f32_16x16x32_bf16 v[70:73], v[206:209], v[198:201], v[70:73]
	v_mfma_f32_16x16x32_bf16 v[66:69], v[214:217], v[198:201], v[66:69]
	v_mfma_f32_16x16x32_bf16 v[118:121], v[210:213], v[174:177], v[118:121]
	v_mfma_f32_16x16x32_bf16 v[110:113], v[218:221], v[174:177], v[110:113]
	v_mfma_f32_16x16x32_bf16 v[102:105], v[210:213], v[186:189], v[102:105]
	v_mfma_f32_16x16x32_bf16 v[94:97], v[218:221], v[186:189], v[94:97]
	v_mfma_f32_16x16x32_bf16 v[86:89], v[210:213], v[194:197], v[86:89]
	v_mfma_f32_16x16x32_bf16 v[78:81], v[218:221], v[194:197], v[78:81]
	v_mfma_f32_16x16x32_bf16 v[70:73], v[210:213], v[202:205], v[70:73]
	v_mfma_f32_16x16x32_bf16 v[66:69], v[218:221], v[202:205], v[66:69]
	s_setprio 0
	s_barrier
	s_add_i32 s28, s61, s45
	v_lshl_add_u64 v[146:147], s[30:31], 0, v[132:133]
	s_mov_b32 m0, s28
	global_load_lds_dwordx4 v132, s[30:31]
	v_lshl_add_u64 v[182:183], s[30:31], 0, v[136:137]
	s_add_i32 m0, s28, 0x2000
	s_nop 0
	global_load_lds_dwordx4 v136, s[30:31]
	s_mov_b32 m0, s46
	v_lshl_add_u64 v[222:223], s[34:35], 0, v[130:131]
	ds_read_b128 v[170:173], v151 offset:16384
	ds_read_b128 v[174:177], v151 offset:17408
	ds_read_b128 v[178:181], v151 offset:18432
	ds_read_b128 v[186:189], v151 offset:19456
	ds_read_b128 v[190:193], v151 offset:20480
	ds_read_b128 v[194:197], v151 offset:21504
	ds_read_b128 v[198:201], v151 offset:22528
	ds_read_b128 v[202:205], v151 offset:23552
	global_load_lds_dwordx4 v130, s[34:35]
	v_lshl_add_u64 v[224:225], s[34:35], 0, v[134:135]
	s_mov_b32 m0, s47
	s_nop 0
	global_load_lds_dwordx4 v134, s[34:35]
	s_waitcnt vmcnt(6)
	s_waitcnt lgkmcnt(0)
	s_barrier
	s_setprio 1
	v_mfma_f32_16x16x32_bf16 v[62:65], v[154:157], v[170:173], v[62:65]
	v_mfma_f32_16x16x32_bf16 v[58:61], v[162:165], v[170:173], v[58:61]
	v_mfma_f32_16x16x32_bf16 v[54:57], v[154:157], v[178:181], v[54:57]
	v_mfma_f32_16x16x32_bf16 v[46:49], v[162:165], v[178:181], v[46:49]
	v_mfma_f32_16x16x32_bf16 v[38:41], v[154:157], v[190:193], v[38:41]
	v_mfma_f32_16x16x32_bf16 v[30:33], v[162:165], v[190:193], v[30:33]
	v_mfma_f32_16x16x32_bf16 v[22:25], v[154:157], v[198:201], v[22:25]
	v_mfma_f32_16x16x32_bf16 v[14:17], v[162:165], v[198:201], v[14:17]
	v_mfma_f32_16x16x32_bf16 v[62:65], v[158:161], v[174:177], v[62:65]
	v_mfma_f32_16x16x32_bf16 v[58:61], v[166:169], v[174:177], v[58:61]
	v_mfma_f32_16x16x32_bf16 v[54:57], v[158:161], v[186:189], v[54:57]
	v_mfma_f32_16x16x32_bf16 v[46:49], v[166:169], v[186:189], v[46:49]
	v_mfma_f32_16x16x32_bf16 v[38:41], v[158:161], v[194:197], v[38:41]
	v_mfma_f32_16x16x32_bf16 v[30:33], v[166:169], v[194:197], v[30:33]
	v_mfma_f32_16x16x32_bf16 v[22:25], v[158:161], v[202:205], v[22:25]
	v_mfma_f32_16x16x32_bf16 v[14:17], v[166:169], v[202:205], v[14:17]
	v_mfma_f32_16x16x32_bf16 v[50:53], v[206:209], v[170:173], v[50:53]
	v_mfma_f32_16x16x32_bf16 v[42:45], v[214:217], v[170:173], v[42:45]
	v_mfma_f32_16x16x32_bf16 v[34:37], v[206:209], v[178:181], v[34:37]
	v_mfma_f32_16x16x32_bf16 v[26:29], v[214:217], v[178:181], v[26:29]
	v_mfma_f32_16x16x32_bf16 v[18:21], v[206:209], v[190:193], v[18:21]
	v_mfma_f32_16x16x32_bf16 v[10:13], v[214:217], v[190:193], v[10:13]
	v_mfma_f32_16x16x32_bf16 v[6:9], v[206:209], v[198:201], v[6:9]
	v_mfma_f32_16x16x32_bf16 v[2:5], v[214:217], v[198:201], v[2:5]
	v_mfma_f32_16x16x32_bf16 v[50:53], v[210:213], v[174:177], v[50:53]
	v_mfma_f32_16x16x32_bf16 v[42:45], v[218:221], v[174:177], v[42:45]
	v_mfma_f32_16x16x32_bf16 v[34:37], v[210:213], v[186:189], v[34:37]
	v_mfma_f32_16x16x32_bf16 v[26:29], v[218:221], v[186:189], v[26:29]
	v_mfma_f32_16x16x32_bf16 v[18:21], v[210:213], v[194:197], v[18:21]
	v_mfma_f32_16x16x32_bf16 v[10:13], v[218:221], v[194:197], v[10:13]
	v_mfma_f32_16x16x32_bf16 v[6:9], v[210:213], v[202:205], v[6:9]
	v_mfma_f32_16x16x32_bf16 v[2:5], v[218:221], v[202:205], v[2:5]
	s_setprio 0
	s_barrier
	s_add_u32 s28, s30, 0x20000
	s_addc_u32 s29, s31, 0
	s_add_i32 s82, s71, s45
	s_mov_b32 m0, s82
	s_nop 0
	global_load_lds_dwordx4 v132, s[28:29]
	s_add_i32 m0, s82, 0x2000
	s_nop 0
	global_load_lds_dwordx4 v136, s[28:29]
	s_add_i32 s82, 0, 0x18000
	v_add_u32_e32 v153, s82, v148
	ds_read_b128 v[154:157], v153
	ds_read_b128 v[158:161], v153 offset:1024
	ds_read_b128 v[162:165], v153 offset:2048
	ds_read_b128 v[166:169], v153 offset:3072
	s_add_u32 s28, s34, 0xf0000
	s_addc_u32 s29, s35, 0
	s_mov_b32 m0, s50
	ds_read_b128 v[170:173], v151 offset:32768
	ds_read_b128 v[174:177], v151 offset:33792
	ds_read_b128 v[178:181], v151 offset:34816
	ds_read_b128 v[186:189], v151 offset:35840
	ds_read_b128 v[190:193], v151 offset:36864
	ds_read_b128 v[194:197], v151 offset:37888
	ds_read_b128 v[198:201], v151 offset:38912
	ds_read_b128 v[202:205], v151 offset:39936
	v_add_u32_e32 v218, 0x1c000, v148
	ds_read_b128 v[206:209], v218
	ds_read_b128 v[210:213], v218 offset:1024
	ds_read_b128 v[214:217], v218 offset:2048
	ds_read_b128 v[218:221], v218 offset:3072
	global_load_lds_dwordx4 v130, s[28:29]
	s_mov_b32 m0, s51
	s_nop 0
	global_load_lds_dwordx4 v134, s[28:29]
	s_waitcnt vmcnt(8)
	s_waitcnt lgkmcnt(0)
	s_barrier
	s_setprio 1
	v_mfma_f32_16x16x32_bf16 v[126:129], v[154:157], v[170:173], v[126:129]
	v_mfma_f32_16x16x32_bf16 v[122:125], v[162:165], v[170:173], v[122:125]
	v_mfma_f32_16x16x32_bf16 v[114:117], v[154:157], v[178:181], v[114:117]
	v_mfma_f32_16x16x32_bf16 v[106:109], v[162:165], v[178:181], v[106:109]
	v_mfma_f32_16x16x32_bf16 v[98:101], v[154:157], v[190:193], v[98:101]
	v_mfma_f32_16x16x32_bf16 v[90:93], v[162:165], v[190:193], v[90:93]
	v_mfma_f32_16x16x32_bf16 v[82:85], v[154:157], v[198:201], v[82:85]
	v_mfma_f32_16x16x32_bf16 v[74:77], v[162:165], v[198:201], v[74:77]
	v_mfma_f32_16x16x32_bf16 v[126:129], v[158:161], v[174:177], v[126:129]
	v_mfma_f32_16x16x32_bf16 v[122:125], v[166:169], v[174:177], v[122:125]
	v_mfma_f32_16x16x32_bf16 v[114:117], v[158:161], v[186:189], v[114:117]
	v_mfma_f32_16x16x32_bf16 v[106:109], v[166:169], v[186:189], v[106:109]
	v_mfma_f32_16x16x32_bf16 v[98:101], v[158:161], v[194:197], v[98:101]
	v_mfma_f32_16x16x32_bf16 v[90:93], v[166:169], v[194:197], v[90:93]
	v_mfma_f32_16x16x32_bf16 v[82:85], v[158:161], v[202:205], v[82:85]
	v_mfma_f32_16x16x32_bf16 v[74:77], v[166:169], v[202:205], v[74:77]
	v_mfma_f32_16x16x32_bf16 v[118:121], v[206:209], v[170:173], v[118:121]
	v_mfma_f32_16x16x32_bf16 v[110:113], v[214:217], v[170:173], v[110:113]
	v_mfma_f32_16x16x32_bf16 v[102:105], v[206:209], v[178:181], v[102:105]
	v_mfma_f32_16x16x32_bf16 v[94:97], v[214:217], v[178:181], v[94:97]
	v_mfma_f32_16x16x32_bf16 v[86:89], v[206:209], v[190:193], v[86:89]
	v_mfma_f32_16x16x32_bf16 v[78:81], v[214:217], v[190:193], v[78:81]
	v_mfma_f32_16x16x32_bf16 v[70:73], v[206:209], v[198:201], v[70:73]
	v_mfma_f32_16x16x32_bf16 v[66:69], v[214:217], v[198:201], v[66:69]
	v_mfma_f32_16x16x32_bf16 v[118:121], v[210:213], v[174:177], v[118:121]
	v_mfma_f32_16x16x32_bf16 v[110:113], v[218:221], v[174:177], v[110:113]
	v_mfma_f32_16x16x32_bf16 v[102:105], v[210:213], v[186:189], v[102:105]
	v_mfma_f32_16x16x32_bf16 v[94:97], v[218:221], v[186:189], v[94:97]
	v_mfma_f32_16x16x32_bf16 v[86:89], v[210:213], v[194:197], v[86:89]
	v_mfma_f32_16x16x32_bf16 v[78:81], v[218:221], v[194:197], v[78:81]
	v_mfma_f32_16x16x32_bf16 v[70:73], v[210:213], v[202:205], v[70:73]
	v_mfma_f32_16x16x32_bf16 v[66:69], v[218:221], v[202:205], v[66:69]
	s_setprio 0
	s_barrier
	s_add_i32 s34, 0, 0x1c000
	s_add_i32 s28, s82, s45
	v_lshl_add_u64 v[146:147], v[146:147], 0, s[6:7]
	s_mov_b32 m0, s28
	global_load_lds_dwordx4 v[146:147], off
	v_lshl_add_u64 v[146:147], v[182:183], 0, s[6:7]
	s_add_i32 m0, s28, 0x2000
	s_nop 0
	global_load_lds_dwordx4 v[146:147], off
	s_mov_b32 m0, s53
	v_lshl_add_u64 v[146:147], v[222:223], 0, s[6:7]
	ds_read_b128 v[170:173], v151 offset:49152
	ds_read_b128 v[174:177], v151 offset:50176
	ds_read_b128 v[178:181], v151 offset:51200
	ds_read_b128 v[186:189], v151 offset:52224
	ds_read_b128 v[190:193], v151 offset:53248
	ds_read_b128 v[194:197], v151 offset:54272
	ds_read_b128 v[198:201], v151 offset:55296
	ds_read_b128 v[202:205], v151 offset:56320
	global_load_lds_dwordx4 v[146:147], off
	v_lshl_add_u64 v[146:147], v[224:225], 0, s[6:7]
	s_mov_b32 m0, s58
	s_nop 0
	global_load_lds_dwordx4 v[146:147], off
	s_add_u32 s28, s30, 0x20080
	s_addc_u32 s29, s31, 0
	s_add_i32 s30, s34, s45
	s_mov_b32 m0, s30
	s_nop 0
	global_load_lds_dwordx4 v132, s[28:29]
	s_add_i32 m0, s30, 0x2000
	s_nop 0
	global_load_lds_dwordx4 v136, s[28:29]
	s_waitcnt vmcnt(8)
	s_waitcnt lgkmcnt(0)
	s_barrier
	s_setprio 1
	v_mfma_f32_16x16x32_bf16 v[62:65], v[154:157], v[170:173], v[62:65]
	v_mfma_f32_16x16x32_bf16 v[58:61], v[162:165], v[170:173], v[58:61]
	v_mfma_f32_16x16x32_bf16 v[54:57], v[154:157], v[178:181], v[54:57]
	v_mfma_f32_16x16x32_bf16 v[46:49], v[162:165], v[178:181], v[46:49]
	v_mfma_f32_16x16x32_bf16 v[38:41], v[154:157], v[190:193], v[38:41]
	v_mfma_f32_16x16x32_bf16 v[30:33], v[162:165], v[190:193], v[30:33]
	v_mfma_f32_16x16x32_bf16 v[22:25], v[154:157], v[198:201], v[22:25]
	v_mfma_f32_16x16x32_bf16 v[14:17], v[162:165], v[198:201], v[14:17]
	v_mfma_f32_16x16x32_bf16 v[62:65], v[158:161], v[174:177], v[62:65]
	v_mfma_f32_16x16x32_bf16 v[58:61], v[166:169], v[174:177], v[58:61]
	v_mfma_f32_16x16x32_bf16 v[54:57], v[158:161], v[186:189], v[54:57]
	v_mfma_f32_16x16x32_bf16 v[46:49], v[166:169], v[186:189], v[46:49]
	v_mfma_f32_16x16x32_bf16 v[38:41], v[158:161], v[194:197], v[38:41]
	v_mfma_f32_16x16x32_bf16 v[30:33], v[166:169], v[194:197], v[30:33]
	v_mfma_f32_16x16x32_bf16 v[22:25], v[158:161], v[202:205], v[22:25]
	v_mfma_f32_16x16x32_bf16 v[14:17], v[166:169], v[202:205], v[14:17]
	v_mfma_f32_16x16x32_bf16 v[50:53], v[206:209], v[170:173], v[50:53]
	v_mfma_f32_16x16x32_bf16 v[42:45], v[214:217], v[170:173], v[42:45]
	v_mfma_f32_16x16x32_bf16 v[34:37], v[206:209], v[178:181], v[34:37]
	v_mfma_f32_16x16x32_bf16 v[26:29], v[214:217], v[178:181], v[26:29]
	v_mfma_f32_16x16x32_bf16 v[18:21], v[206:209], v[190:193], v[18:21]
	v_mfma_f32_16x16x32_bf16 v[10:13], v[214:217], v[190:193], v[10:13]
	v_mfma_f32_16x16x32_bf16 v[6:9], v[206:209], v[198:201], v[6:9]
	v_mfma_f32_16x16x32_bf16 v[2:5], v[214:217], v[198:201], v[2:5]
	v_mfma_f32_16x16x32_bf16 v[50:53], v[210:213], v[174:177], v[50:53]
	v_mfma_f32_16x16x32_bf16 v[42:45], v[218:221], v[174:177], v[42:45]
	v_mfma_f32_16x16x32_bf16 v[34:37], v[210:213], v[186:189], v[34:37]
	v_mfma_f32_16x16x32_bf16 v[26:29], v[218:221], v[186:189], v[26:29]
	v_mfma_f32_16x16x32_bf16 v[18:21], v[210:213], v[194:197], v[18:21]
	v_mfma_f32_16x16x32_bf16 v[10:13], v[218:221], v[194:197], v[10:13]
	v_mfma_f32_16x16x32_bf16 v[6:9], v[210:213], v[202:205], v[6:9]
	v_mfma_f32_16x16x32_bf16 v[2:5], v[218:221], v[202:205], v[2:5]
	s_setprio 0
	s_add_i32 s81, s81, 2
	s_add_u32 s79, s79, 0x100
	s_addc_u32 s80, s80, 0
	s_cmp_gt_u32 s81, 5
	s_mov_b64 s[28:29], s[4:5]
	s_barrier
	s_cbranch_scc0 .LBB0_457

.LBB0_696:
	ds_read_b128 v[82:85], v208
	ds_read_b128 v[86:89], v208 offset:1024
	ds_read_b128 v[94:97], v208 offset:2048
	ds_read_b128 v[102:105], v208 offset:3072
	s_add_u32 s8, s2, 0x100
	s_addc_u32 s9, s3, 0
	s_cmp_eq_u32 s68, 28
	s_cselect_b32 s31, s25, s9
	s_cselect_b32 s30, s24, s8
	s_cselect_b32 s29, s1, s63
	s_cselect_b32 s28, s23, s53
	v_lshl_add_u64 v[182:183], s[2:3], 0, v[170:171]
	s_add_i32 m0, s41, 0xc000
	ds_read_b128 v[146:149], v209
	ds_read_b128 v[150:153], v209 offset:1024
	ds_read_b128 v[154:157], v209 offset:2048
	ds_read_b128 v[158:161], v209 offset:3072
	ds_read_b128 v[178:181], v209 offset:4096
	ds_read_b128 v[186:189], v209 offset:5120
	ds_read_b128 v[190:193], v209 offset:6144
	ds_read_b128 v[194:197], v209 offset:7168
	global_load_lds_dwordx4 v[182:183], off
	v_lshl_add_u64 v[182:183], s[2:3], 0, v[172:173]
	s_add_i32 m0, s41, 0xe000
	s_nop 0
	global_load_lds_dwordx4 v[182:183], off
	ds_read_b128 v[198:201], v210
	ds_read_b128 v[202:205], v210 offset:1024
	ds_read_b128 v[212:215], v210 offset:2048
	ds_read_b128 v[216:219], v210 offset:3072
	s_waitcnt vmcnt(8)
	s_waitcnt lgkmcnt(4)
	s_barrier
	s_setprio 1
	v_mfma_f32_16x16x32_bf16 v[142:145], v[82:85], v[146:149], v[142:145]
	v_mfma_f32_16x16x32_bf16 v[138:141], v[94:97], v[146:149], v[138:141]
	v_mfma_f32_16x16x32_bf16 v[126:129], v[82:85], v[154:157], v[126:129]
	v_mfma_f32_16x16x32_bf16 v[122:125], v[94:97], v[154:157], v[122:125]
	v_mfma_f32_16x16x32_bf16 v[110:113], v[82:85], v[178:181], v[110:113]
	v_mfma_f32_16x16x32_bf16 v[106:109], v[94:97], v[178:181], v[106:109]
	v_mfma_f32_16x16x32_bf16 v[78:81], v[82:85], v[190:193], v[78:81]
	v_mfma_f32_16x16x32_bf16 v[74:77], v[94:97], v[190:193], v[74:77]
	v_mfma_f32_16x16x32_bf16 v[142:145], v[86:89], v[150:153], v[142:145]
	v_mfma_f32_16x16x32_bf16 v[138:141], v[102:105], v[150:153], v[138:141]
	v_mfma_f32_16x16x32_bf16 v[126:129], v[86:89], v[158:161], v[126:129]
	v_mfma_f32_16x16x32_bf16 v[122:125], v[102:105], v[158:161], v[122:125]
	v_mfma_f32_16x16x32_bf16 v[110:113], v[86:89], v[186:189], v[110:113]
	v_mfma_f32_16x16x32_bf16 v[106:109], v[102:105], v[186:189], v[106:109]
	v_mfma_f32_16x16x32_bf16 v[78:81], v[86:89], v[194:197], v[78:81]
	v_mfma_f32_16x16x32_bf16 v[74:77], v[102:105], v[194:197], v[74:77]
	s_waitcnt lgkmcnt(0)
	v_mfma_f32_16x16x32_bf16 v[134:137], v[198:201], v[146:149], v[134:137]
	v_mfma_f32_16x16x32_bf16 v[130:133], v[212:215], v[146:149], v[130:133]
	v_mfma_f32_16x16x32_bf16 v[118:121], v[198:201], v[154:157], v[118:121]
	v_mfma_f32_16x16x32_bf16 v[114:117], v[212:215], v[154:157], v[114:117]
	v_mfma_f32_16x16x32_bf16 v[98:101], v[198:201], v[178:181], v[98:101]
	v_mfma_f32_16x16x32_bf16 v[90:93], v[212:215], v[178:181], v[90:93]
	v_mfma_f32_16x16x32_bf16 v[70:73], v[198:201], v[190:193], v[70:73]
	v_mfma_f32_16x16x32_bf16 v[66:69], v[212:215], v[190:193], v[66:69]
	v_mfma_f32_16x16x32_bf16 v[134:137], v[202:205], v[150:153], v[134:137]
	v_mfma_f32_16x16x32_bf16 v[130:133], v[216:219], v[150:153], v[130:133]
	v_mfma_f32_16x16x32_bf16 v[118:121], v[202:205], v[158:161], v[118:121]
	v_mfma_f32_16x16x32_bf16 v[114:117], v[216:219], v[158:161], v[114:117]
	v_mfma_f32_16x16x32_bf16 v[98:101], v[202:205], v[186:189], v[98:101]
	v_mfma_f32_16x16x32_bf16 v[90:93], v[216:219], v[186:189], v[90:93]
	v_mfma_f32_16x16x32_bf16 v[70:73], v[202:205], v[194:197], v[70:73]
	v_mfma_f32_16x16x32_bf16 v[66:69], v[216:219], v[194:197], v[66:69]
	s_setprio 0
	s_barrier
	s_add_i32 s2, s59, s37
	v_lshl_add_u64 v[182:183], s[28:29], 0, v[164:165]
	s_mov_b32 m0, s2
	global_load_lds_dwordx4 v164, s[28:29]
	v_lshl_add_u64 v[220:221], s[28:29], 0, v[168:169]
	s_add_i32 m0, s2, 0x2000
	s_nop 0
	global_load_lds_dwordx4 v168, s[28:29]
	s_mov_b32 m0, s41
	v_lshl_add_u64 v[222:223], s[30:31], 0, v[162:163]
	ds_read_b128 v[146:149], v209 offset:16384
	ds_read_b128 v[150:153], v209 offset:17408
	ds_read_b128 v[154:157], v209 offset:18432
	ds_read_b128 v[158:161], v209 offset:19456
	ds_read_b128 v[178:181], v209 offset:20480
	ds_read_b128 v[186:189], v209 offset:21504
	ds_read_b128 v[190:193], v209 offset:22528
	ds_read_b128 v[194:197], v209 offset:23552
	global_load_lds_dwordx4 v162, s[30:31]
	v_lshl_add_u64 v[224:225], s[30:31], 0, v[166:167]
	s_mov_b32 m0, s42
	s_nop 0
	global_load_lds_dwordx4 v166, s[30:31]
	s_waitcnt vmcnt(6)
	s_waitcnt lgkmcnt(0)
	s_barrier
	s_setprio 1
	v_mfma_f32_16x16x32_bf16 v[62:65], v[82:85], v[146:149], v[62:65]
	v_mfma_f32_16x16x32_bf16 v[58:61], v[94:97], v[146:149], v[58:61]
	v_mfma_f32_16x16x32_bf16 v[46:49], v[82:85], v[154:157], v[46:49]
	v_mfma_f32_16x16x32_bf16 v[42:45], v[94:97], v[154:157], v[42:45]
	v_mfma_f32_16x16x32_bf16 v[30:33], v[82:85], v[178:181], v[30:33]
	v_mfma_f32_16x16x32_bf16 v[26:29], v[94:97], v[178:181], v[26:29]
	v_mfma_f32_16x16x32_bf16 v[14:17], v[82:85], v[190:193], v[14:17]
	v_mfma_f32_16x16x32_bf16 v[10:13], v[94:97], v[190:193], v[10:13]
	v_mfma_f32_16x16x32_bf16 v[62:65], v[86:89], v[150:153], v[62:65]
	v_mfma_f32_16x16x32_bf16 v[58:61], v[102:105], v[150:153], v[58:61]
	v_mfma_f32_16x16x32_bf16 v[46:49], v[86:89], v[158:161], v[46:49]
	v_mfma_f32_16x16x32_bf16 v[42:45], v[102:105], v[158:161], v[42:45]
	v_mfma_f32_16x16x32_bf16 v[30:33], v[86:89], v[186:189], v[30:33]
	v_mfma_f32_16x16x32_bf16 v[26:29], v[102:105], v[186:189], v[26:29]
	v_mfma_f32_16x16x32_bf16 v[14:17], v[86:89], v[194:197], v[14:17]
	v_mfma_f32_16x16x32_bf16 v[10:13], v[102:105], v[194:197], v[10:13]
	v_mfma_f32_16x16x32_bf16 v[54:57], v[198:201], v[146:149], v[54:57]
	v_mfma_f32_16x16x32_bf16 v[50:53], v[212:215], v[146:149], v[50:53]
	v_mfma_f32_16x16x32_bf16 v[38:41], v[198:201], v[154:157], v[38:41]
	v_mfma_f32_16x16x32_bf16 v[34:37], v[212:215], v[154:157], v[34:37]
	v_mfma_f32_16x16x32_bf16 v[22:25], v[198:201], v[178:181], v[22:25]
	v_mfma_f32_16x16x32_bf16 v[18:21], v[212:215], v[178:181], v[18:21]
	v_mfma_f32_16x16x32_bf16 v[6:9], v[198:201], v[190:193], v[6:9]
	v_mfma_f32_16x16x32_bf16 v[2:5], v[212:215], v[190:193], v[2:5]
	v_mfma_f32_16x16x32_bf16 v[54:57], v[202:205], v[150:153], v[54:57]
	v_mfma_f32_16x16x32_bf16 v[50:53], v[216:219], v[150:153], v[50:53]
	v_mfma_f32_16x16x32_bf16 v[38:41], v[202:205], v[158:161], v[38:41]
	v_mfma_f32_16x16x32_bf16 v[34:37], v[216:219], v[158:161], v[34:37]
	v_mfma_f32_16x16x32_bf16 v[22:25], v[202:205], v[186:189], v[22:25]
	v_mfma_f32_16x16x32_bf16 v[18:21], v[216:219], v[186:189], v[18:21]
	v_mfma_f32_16x16x32_bf16 v[6:9], v[202:205], v[194:197], v[6:9]
	v_mfma_f32_16x16x32_bf16 v[2:5], v[216:219], v[194:197], v[2:5]
	s_setprio 0
	s_barrier
	s_add_u32 s2, s28, 0x80000
	s_addc_u32 s3, s29, 0
	s_add_i32 s69, s60, s37
	s_mov_b32 m0, s69
	s_nop 0
	global_load_lds_dwordx4 v164, s[2:3]
	s_add_i32 m0, s69, 0x2000
	s_nop 0
	global_load_lds_dwordx4 v168, s[2:3]
	s_add_i32 s69, 0, 0x18000
	v_add_u32_e32 v102, s69, v206
	ds_read_b128 v[82:85], v102
	ds_read_b128 v[86:89], v102 offset:1024
	ds_read_b128 v[94:97], v102 offset:2048
	ds_read_b128 v[102:105], v102 offset:3072
	s_add_u32 s2, s30, 0xf0000
	s_addc_u32 s3, s31, 0
	s_mov_b32 m0, s43
	ds_read_b128 v[146:149], v209 offset:32768
	ds_read_b128 v[150:153], v209 offset:33792
	ds_read_b128 v[154:157], v209 offset:34816
	ds_read_b128 v[158:161], v209 offset:35840
	ds_read_b128 v[178:181], v209 offset:36864
	ds_read_b128 v[186:189], v209 offset:37888
	ds_read_b128 v[190:193], v209 offset:38912
	ds_read_b128 v[194:197], v209 offset:39936
	v_add_u32_e32 v216, 0x1c000, v206
	ds_read_b128 v[198:201], v216
	ds_read_b128 v[202:205], v216 offset:1024
	ds_read_b128 v[212:215], v216 offset:2048
	ds_read_b128 v[216:219], v216 offset:3072
	global_load_lds_dwordx4 v162, s[2:3]
	s_mov_b32 m0, s44
	s_nop 0
	global_load_lds_dwordx4 v166, s[2:3]
	s_waitcnt vmcnt(8)
	s_waitcnt lgkmcnt(0)
	s_barrier
	s_setprio 1
	v_mfma_f32_16x16x32_bf16 v[142:145], v[82:85], v[146:149], v[142:145]
	v_mfma_f32_16x16x32_bf16 v[138:141], v[94:97], v[146:149], v[138:141]
	v_mfma_f32_16x16x32_bf16 v[126:129], v[82:85], v[154:157], v[126:129]
	v_mfma_f32_16x16x32_bf16 v[122:125], v[94:97], v[154:157], v[122:125]
	v_mfma_f32_16x16x32_bf16 v[110:113], v[82:85], v[178:181], v[110:113]
	v_mfma_f32_16x16x32_bf16 v[106:109], v[94:97], v[178:181], v[106:109]
	v_mfma_f32_16x16x32_bf16 v[78:81], v[82:85], v[190:193], v[78:81]
	v_mfma_f32_16x16x32_bf16 v[74:77], v[94:97], v[190:193], v[74:77]
	v_mfma_f32_16x16x32_bf16 v[142:145], v[86:89], v[150:153], v[142:145]
	v_mfma_f32_16x16x32_bf16 v[138:141], v[102:105], v[150:153], v[138:141]
	v_mfma_f32_16x16x32_bf16 v[126:129], v[86:89], v[158:161], v[126:129]
	v_mfma_f32_16x16x32_bf16 v[122:125], v[102:105], v[158:161], v[122:125]
	v_mfma_f32_16x16x32_bf16 v[110:113], v[86:89], v[186:189], v[110:113]
	v_mfma_f32_16x16x32_bf16 v[106:109], v[102:105], v[186:189], v[106:109]
	v_mfma_f32_16x16x32_bf16 v[78:81], v[86:89], v[194:197], v[78:81]
	v_mfma_f32_16x16x32_bf16 v[74:77], v[102:105], v[194:197], v[74:77]
	v_mfma_f32_16x16x32_bf16 v[134:137], v[198:201], v[146:149], v[134:137]
	v_mfma_f32_16x16x32_bf16 v[130:133], v[212:215], v[146:149], v[130:133]
	v_mfma_f32_16x16x32_bf16 v[118:121], v[198:201], v[154:157], v[118:121]
	v_mfma_f32_16x16x32_bf16 v[114:117], v[212:215], v[154:157], v[114:117]
	v_mfma_f32_16x16x32_bf16 v[98:101], v[198:201], v[178:181], v[98:101]
	v_mfma_f32_16x16x32_bf16 v[90:93], v[212:215], v[178:181], v[90:93]
	v_mfma_f32_16x16x32_bf16 v[70:73], v[198:201], v[190:193], v[70:73]
	v_mfma_f32_16x16x32_bf16 v[66:69], v[212:215], v[190:193], v[66:69]
	v_mfma_f32_16x16x32_bf16 v[134:137], v[202:205], v[150:153], v[134:137]
	v_mfma_f32_16x16x32_bf16 v[130:133], v[216:219], v[150:153], v[130:133]
	v_mfma_f32_16x16x32_bf16 v[118:121], v[202:205], v[158:161], v[118:121]
	v_mfma_f32_16x16x32_bf16 v[114:117], v[216:219], v[158:161], v[114:117]
	v_mfma_f32_16x16x32_bf16 v[98:101], v[202:205], v[186:189], v[98:101]
	v_mfma_f32_16x16x32_bf16 v[90:93], v[216:219], v[186:189], v[90:93]
	v_mfma_f32_16x16x32_bf16 v[70:73], v[202:205], v[194:197], v[70:73]
	v_mfma_f32_16x16x32_bf16 v[66:69], v[216:219], v[194:197], v[66:69]
	s_setprio 0
	s_barrier
	s_add_i32 s30, 0, 0x1c000
	s_add_i32 s2, s69, s37
	v_lshl_add_u64 v[182:183], v[182:183], 0, s[20:21]
	s_mov_b32 m0, s2
	global_load_lds_dwordx4 v[182:183], off
	v_lshl_add_u64 v[182:183], v[220:221], 0, s[20:21]
	s_add_i32 m0, s2, 0x2000
	s_nop 0
	global_load_lds_dwordx4 v[182:183], off
	s_mov_b32 m0, s47
	v_lshl_add_u64 v[182:183], v[222:223], 0, s[20:21]
	ds_read_b128 v[146:149], v209 offset:49152
	ds_read_b128 v[150:153], v209 offset:50176
	ds_read_b128 v[154:157], v209 offset:51200
	ds_read_b128 v[158:161], v209 offset:52224
	ds_read_b128 v[178:181], v209 offset:53248
	ds_read_b128 v[186:189], v209 offset:54272
	ds_read_b128 v[190:193], v209 offset:55296
	ds_read_b128 v[194:197], v209 offset:56320
	global_load_lds_dwordx4 v[182:183], off
	v_lshl_add_u64 v[182:183], v[224:225], 0, s[20:21]
	s_mov_b32 m0, s48
	s_nop 0
	global_load_lds_dwordx4 v[182:183], off
	s_add_u32 s2, s28, 0x80080
	s_addc_u32 s3, s29, 0
	s_add_i32 s28, s30, s37
	s_mov_b32 m0, s28
	s_nop 0
	global_load_lds_dwordx4 v164, s[2:3]
	s_add_i32 m0, s28, 0x2000
	s_nop 0
	global_load_lds_dwordx4 v168, s[2:3]
	s_waitcnt vmcnt(8)
	s_waitcnt lgkmcnt(0)
	s_barrier
	s_setprio 1
	v_mfma_f32_16x16x32_bf16 v[62:65], v[82:85], v[146:149], v[62:65]
	v_mfma_f32_16x16x32_bf16 v[58:61], v[94:97], v[146:149], v[58:61]
	v_mfma_f32_16x16x32_bf16 v[46:49], v[82:85], v[154:157], v[46:49]
	v_mfma_f32_16x16x32_bf16 v[42:45], v[94:97], v[154:157], v[42:45]
	v_mfma_f32_16x16x32_bf16 v[30:33], v[82:85], v[178:181], v[30:33]
	v_mfma_f32_16x16x32_bf16 v[26:29], v[94:97], v[178:181], v[26:29]
	v_mfma_f32_16x16x32_bf16 v[14:17], v[82:85], v[190:193], v[14:17]
	v_mfma_f32_16x16x32_bf16 v[10:13], v[94:97], v[190:193], v[10:13]
	v_mfma_f32_16x16x32_bf16 v[62:65], v[86:89], v[150:153], v[62:65]
	v_mfma_f32_16x16x32_bf16 v[58:61], v[102:105], v[150:153], v[58:61]
	v_mfma_f32_16x16x32_bf16 v[46:49], v[86:89], v[158:161], v[46:49]
	v_mfma_f32_16x16x32_bf16 v[42:45], v[102:105], v[158:161], v[42:45]
	v_mfma_f32_16x16x32_bf16 v[30:33], v[86:89], v[186:189], v[30:33]
	v_mfma_f32_16x16x32_bf16 v[26:29], v[102:105], v[186:189], v[26:29]
	v_mfma_f32_16x16x32_bf16 v[14:17], v[86:89], v[194:197], v[14:17]
	v_mfma_f32_16x16x32_bf16 v[10:13], v[102:105], v[194:197], v[10:13]
	v_mfma_f32_16x16x32_bf16 v[54:57], v[198:201], v[146:149], v[54:57]
	v_mfma_f32_16x16x32_bf16 v[50:53], v[212:215], v[146:149], v[50:53]
	v_mfma_f32_16x16x32_bf16 v[38:41], v[198:201], v[154:157], v[38:41]
	v_mfma_f32_16x16x32_bf16 v[34:37], v[212:215], v[154:157], v[34:37]
	v_mfma_f32_16x16x32_bf16 v[22:25], v[198:201], v[178:181], v[22:25]
	v_mfma_f32_16x16x32_bf16 v[18:21], v[212:215], v[178:181], v[18:21]
	v_mfma_f32_16x16x32_bf16 v[6:9], v[198:201], v[190:193], v[6:9]
	v_mfma_f32_16x16x32_bf16 v[2:5], v[212:215], v[190:193], v[2:5]
	v_mfma_f32_16x16x32_bf16 v[54:57], v[202:205], v[150:153], v[54:57]
	v_mfma_f32_16x16x32_bf16 v[50:53], v[216:219], v[150:153], v[50:53]
	v_mfma_f32_16x16x32_bf16 v[38:41], v[202:205], v[158:161], v[38:41]
	v_mfma_f32_16x16x32_bf16 v[34:37], v[216:219], v[158:161], v[34:37]
	v_mfma_f32_16x16x32_bf16 v[22:25], v[202:205], v[186:189], v[22:25]
	v_mfma_f32_16x16x32_bf16 v[18:21], v[216:219], v[186:189], v[18:21]
	v_mfma_f32_16x16x32_bf16 v[6:9], v[202:205], v[194:197], v[6:9]
	v_mfma_f32_16x16x32_bf16 v[2:5], v[216:219], v[194:197], v[2:5]
	s_setprio 0
	s_add_i32 s68, s68, 2
	s_add_u32 s53, s53, 0x100
	s_addc_u32 s63, s63, 0
	s_cmp_gt_u32 s68, 29
	s_mov_b64 s[2:3], s[8:9]
	s_barrier
	s_cbranch_scc0 .LBB0_696
	s_min_i32 s1, s52, 64
	s_ashr_i32 s1, s1, 3
	v_lshl_or_b32 v178, s0, 8, v207
	s_mul_hi_i32 s2, s1, 0xc000
	s_mul_i32 s1, s1, 0xc000
	s_add_u32 s0, s10, s1
	v_ashrrev_i32_e32 v179, 31, v178
	s_addc_u32 s1, s11, s2
	v_lshlrev_b64 v[198:199], 2, v[178:179]
	v_lshl_add_u32 v200, s52, 8, v1
	v_lshl_add_u64 v[82:83], s[0:1], 0, v[198:199]
	v_add_u32_e32 v94, 0xffffc000, v200
	v_ashrrev_i32_e32 v201, 31, v200
	v_cmp_gt_i32_e64 s[0:1], s46, v200
	v_add_co_u32_e32 v84, vcc, s46, v82
	s_nop 0
	v_cndmask_b32_e64 v95, 0, v201, s[0:1]
	v_cndmask_b32_e64 v94, v94, v200, s[0:1]
	v_mov_b32_e32 v152, s15
	v_mov_b32_e32 v153, s13
	v_mov_b32_e32 v154, s14
	v_mov_b32_e32 v155, s12
	v_addc_co_u32_e32 v85, vcc, 0, v83, vcc
	v_cndmask_b32_e64 v97, v152, v153, s[0:1]
	v_cndmask_b32_e64 v96, v154, v155, s[0:1]
	v_lshlrev_b64 v[94:95], 13, v[94:95]
	v_add_co_u32_e32 v82, vcc, s49, v82
	v_lshl_add_u64 v[94:95], v[96:97], 0, v[94:95]
	v_lshl_add_u64 v[146:147], v[94:95], 0, v[198:199]
	v_addc_co_u32_e32 v83, vcc, 0, v83, vcc
	global_load_dwordx4 v[86:89], v[84:85], off
	global_load_dwordx4 v[180:183], v[146:147], off
	global_load_dwordx4 v[186:189], v[82:83], off
	global_load_dwordx4 v[190:193], v[82:83], off offset:64
	global_load_dwordx4 v[194:197], v[82:83], off offset:512
	global_load_dwordx4 v[212:215], v[82:83], off offset:576
	v_lshl_add_u64 v[82:83], s[56:57], 0, v[198:199]
	global_load_dwordx4 v[216:219], v[82:83], off
	global_load_dwordx4 v[220:223], v[82:83], off offset:64
	global_load_dwordx4 v[224:227], v[82:83], off offset:512
	global_load_dwordx4 v[228:231], v[82:83], off offset:576
	global_load_dwordx4 v[232:235], v[146:147], off offset:64
	global_load_dwordx4 v[102:105], v[84:85], off offset:64
	global_load_dwordx4 v[94:97], v[84:85], off offset:512
	global_load_dwordx4 v[236:239], v[146:147], off offset:512
	global_load_dwordx4 v[240:243], v[146:147], off offset:576
	s_nop 0
	global_load_dwordx4 v[82:85], v[84:85], off offset:576
	v_or_b32_e32 v202, 16, v200
	v_add_u32_e32 v150, 0xffffc010, v200
	v_ashrrev_i32_e32 v203, 31, v202
	v_cmp_gt_i32_e32 vcc, s46, v202
	v_lshlrev_b64 v[146:147], 13, v[200:201]
	v_lshl_add_u64 v[146:147], s[66:67], 0, v[146:147]
	v_cndmask_b32_e32 v151, 0, v203, vcc
	v_cndmask_b32_e32 v150, v150, v202, vcc
	v_cndmask_b32_e32 v153, v152, v153, vcc
	v_cndmask_b32_e32 v152, v154, v155, vcc
	v_lshlrev_b64 v[150:151], 13, v[150:151]
	v_lshlrev_b64 v[148:149], 12, v[200:201]
	v_lshl_add_u64 v[204:205], v[146:147], 0, v[198:199]
	v_lshl_add_u64 v[146:147], v[152:153], 0, v[150:151]
	v_lshl_add_u64 v[148:149], s[88:89], 0, v[148:149]
	v_lshl_add_u64 v[146:147], v[146:147], 0, v[198:199]
	v_lshl_add_u64 v[244:245], v[178:179], 1, v[148:149]
	global_load_dwordx4 v[158:161], v[146:147], off
	global_load_dwordx4 v[154:157], v[146:147], off offset:64
	global_load_dwordx4 v[150:153], v[146:147], off offset:512
	s_nop 0
	global_load_dwordx4 v[146:149], v[146:147], off offset:576
	s_waitcnt vmcnt(0)
	v_pk_fma_f32 v[138:139], v[138:139], v[102:103], v[232:233]
	v_pk_fma_f32 v[144:145], v[144:145], v[88:89], v[182:183]
	v_pk_fma_f32 v[142:143], v[142:143], v[86:87], v[180:181]
	v_pk_add_f32 v[180:181], v[188:189], 1.0 op_sel_hi:[1,0]
	v_pk_add_f32 v[182:183], v[186:187], 1.0 op_sel_hi:[1,0]
	v_pk_add_f32 v[212:213], v[212:213], 1.0 op_sel_hi:[1,0]
	v_pk_add_f32 v[246:247], v[196:197], 1.0 op_sel_hi:[1,0]
	v_pk_add_f32 v[248:249], v[194:195], 1.0 op_sel_hi:[1,0]
	v_pk_mul_f32 v[194:195], v[218:219], v[180:181]
	v_pk_mul_f32 v[196:197], v[216:217], v[182:183]
	v_pk_mul_f32 v[180:181], v[228:229], v[212:213]
	v_mul_f32_e32 v212, v143, v143
	global_store_dwordx4 v[204:205], v[142:145], off
	v_fmac_f32_e32 v212, v142, v142
	v_pk_add_f32 v[188:189], v[190:191], 1.0 op_sel_hi:[1,0]
	v_pk_mul_f32 v[142:143], v[196:197], v[142:143]
	v_fmac_f32_e32 v212, v144, v144
	v_cvt_pk_bf16_f32 v142, v142, v143
	v_pk_add_f32 v[186:187], v[192:193], 1.0 op_sel_hi:[1,0]
	v_pk_mul_f32 v[192:193], v[220:221], v[188:189]
	v_fmac_f32_e32 v212, v145, v145
	v_pk_mul_f32 v[144:145], v[194:195], v[144:145]
	v_pk_fma_f32 v[140:141], v[140:141], v[104:105], v[234:235]
	v_cvt_pk_bf16_f32 v143, v144, v145
	global_store_dwordx2 v[244:245], v[142:143], off
	v_mul_f32_e32 v142, v139, v139
	global_store_dwordx4 v[204:205], v[138:141], off offset:64
	v_fmac_f32_e32 v142, v138, v138
	v_pk_mul_f32 v[190:191], v[222:223], v[186:187]
	v_pk_mul_f32 v[138:139], v[192:193], v[138:139]
	v_fmac_f32_e32 v142, v140, v140
	v_cvt_pk_bf16_f32 v138, v138, v139
	v_pk_fma_f32 v[134:135], v[134:135], v[94:95], v[236:237]
	v_fmac_f32_e32 v142, v141, v141
	v_pk_mul_f32 v[140:141], v[190:191], v[140:141]
	v_pk_fma_f32 v[136:137], v[136:137], v[96:97], v[238:239]
	v_cvt_pk_bf16_f32 v139, v140, v141
	global_store_dwordx2 v[244:245], v[138:139], off offset:32
	v_mul_f32_e32 v138, v135, v135
	v_fmac_f32_e32 v138, v134, v134
	v_pk_mul_f32 v[188:189], v[224:225], v[248:249]
	v_fmac_f32_e32 v138, v136, v136
	v_add_f32_e32 v142, v212, v142
	global_store_dwordx4 v[204:205], v[134:137], off offset:512
	v_fmac_f32_e32 v138, v137, v137
	v_add_f32_e32 v139, v142, v138
	v_pk_mul_f32 v[134:135], v[188:189], v[134:135]
	v_pk_mul_f32 v[186:187], v[226:227], v[246:247]
	v_cvt_pk_bf16_f32 v138, v134, v135
	v_pk_fma_f32 v[134:135], v[132:133], v[84:85], v[242:243]
	v_pk_fma_f32 v[132:133], v[130:131], v[82:83], v[240:241]
	v_xor_b32_e32 v131, 16, v211
	v_mul_f32_e32 v130, v133, v133
	v_fmac_f32_e32 v130, v132, v132
	v_fmac_f32_e32 v130, v134, v134
	v_fmac_f32_e32 v130, v135, v135
	v_add_f32_e32 v130, v139, v130
	v_and_b32_e32 v139, 64, v211
	v_add_u32_e32 v140, 64, v139
	v_cmp_lt_i32_e32 vcc, v131, v140
	v_pk_add_f32 v[214:215], v[214:215], 1.0 op_sel_hi:[1,0]
	v_pk_mul_f32 v[136:137], v[186:187], v[136:137]
	v_cndmask_b32_e32 v131, v211, v131, vcc
	v_lshlrev_b32_e32 v212, 2, v131
	ds_bpermute_b32 v131, v212, v130
	v_cvt_pk_bf16_f32 v139, v136, v137
	v_pk_mul_f32 v[182:183], v[230:231], v[214:215]
	global_store_dwordx2 v[244:245], v[138:139], off offset:256
	global_store_dwordx4 v[204:205], v[132:135], off offset:576
	s_waitcnt lgkmcnt(0)
	v_add_f32_e32 v130, v130, v131
	v_xor_b32_e32 v131, 32, v211
	v_cmp_lt_i32_e32 vcc, v131, v140
	v_pk_mul_f32 v[132:133], v[180:181], v[132:133]
	v_pk_mul_f32 v[134:135], v[182:183], v[134:135]
	v_cndmask_b32_e32 v131, v211, v131, vcc
	v_lshlrev_b32_e32 v213, 2, v131
	ds_bpermute_b32 v131, v213, v130
	v_cvt_pk_bf16_f32 v132, v132, v133
	v_cvt_pk_bf16_f32 v133, v134, v135
	global_store_dwordx2 v[244:245], v[132:133], off offset:288
	s_and_saveexec_b64 s[0:1], s[4:5]
	s_cbranch_execz .LBB0_699
	v_lshl_add_u64 v[132:133], v[200:201], 2, s[18:19]
	s_waitcnt lgkmcnt(0)
	v_add_f32_e32 v130, v130, v131
	global_atomic_add_f32 v[132:133], v130, off

.LBB0_802:
	s_ashr_i32 s15, s14, 31
	v_cmp_lt_i64_e32 vcc, s[18:19], v[190:191]
	s_lshl_b64 s[18:19], s[14:15], 20
	s_add_u32 s18, s23, s18
	s_addc_u32 s19, s26, s19
	s_and_b64 s[24:25], vcc, exec
	s_cselect_b32 s15, s19, s13
	s_cselect_b32 s45, s18, s12
	s_ashr_i32 s3, s2, 31
	s_lshl_b64 s[24:25], s[2:3], 20
	s_add_u32 s28, s73, s24
	s_addc_u32 s29, s36, s25
	s_and_b64 s[24:25], vcc, exec
	s_cselect_b32 s3, s29, s21
	s_cselect_b32 s52, s28, s20
	s_add_u32 s12, s12, 0x80080
	s_addc_u32 s13, s13, 0
	s_add_u32 s53, s20, 0x100
	v_mov_b32_e32 v0, 0
	s_addc_u32 s56, s21, 0
	s_mov_b32 s57, -2
	v_mov_b32_e32 v1, v0
	v_mov_b32_e32 v2, v0
	v_mov_b32_e32 v3, v0
	v_mov_b32_e32 v4, v0
	v_mov_b32_e32 v5, v0
	v_mov_b32_e32 v6, v0
	v_mov_b32_e32 v7, v0
	v_mov_b32_e32 v16, v0
	v_mov_b32_e32 v17, v0
	v_mov_b32_e32 v18, v0
	v_mov_b32_e32 v19, v0
	v_mov_b32_e32 v20, v0
	v_mov_b32_e32 v21, v0
	v_mov_b32_e32 v22, v0
	v_mov_b32_e32 v23, v0
	v_mov_b32_e32 v32, v0
	v_mov_b32_e32 v33, v0
	v_mov_b32_e32 v34, v0
	v_mov_b32_e32 v35, v0
	v_mov_b32_e32 v36, v0
	v_mov_b32_e32 v37, v0
	v_mov_b32_e32 v38, v0
	v_mov_b32_e32 v39, v0
	v_mov_b32_e32 v48, v0
	v_mov_b32_e32 v49, v0
	v_mov_b32_e32 v50, v0
	v_mov_b32_e32 v51, v0
	v_mov_b32_e32 v52, v0
	v_mov_b32_e32 v53, v0
	v_mov_b32_e32 v54, v0
	v_mov_b32_e32 v55, v0
	v_mov_b32_e32 v8, v0
	v_mov_b32_e32 v9, v0
	v_mov_b32_e32 v10, v0
	v_mov_b32_e32 v11, v0
	v_mov_b32_e32 v12, v0
	v_mov_b32_e32 v13, v0
	v_mov_b32_e32 v14, v0
	v_mov_b32_e32 v15, v0
	v_mov_b32_e32 v24, v0
	v_mov_b32_e32 v25, v0
	v_mov_b32_e32 v26, v0
	v_mov_b32_e32 v27, v0
	v_mov_b32_e32 v28, v0
	v_mov_b32_e32 v29, v0
	v_mov_b32_e32 v30, v0
	v_mov_b32_e32 v31, v0
	v_mov_b32_e32 v40, v0
	v_mov_b32_e32 v41, v0
	v_mov_b32_e32 v42, v0
	v_mov_b32_e32 v43, v0
	v_mov_b32_e32 v44, v0
	v_mov_b32_e32 v45, v0
	v_mov_b32_e32 v46, v0
	v_mov_b32_e32 v47, v0
	v_mov_b32_e32 v56, v0
	v_mov_b32_e32 v57, v0
	v_mov_b32_e32 v58, v0
	v_mov_b32_e32 v59, v0
	v_mov_b32_e32 v60, v0
	v_mov_b32_e32 v61, v0
	v_mov_b32_e32 v62, v0
	v_mov_b32_e32 v63, v0
	v_mov_b32_e32 v64, v0
	v_mov_b32_e32 v65, v0
	v_mov_b32_e32 v66, v0
	v_mov_b32_e32 v67, v0
	v_mov_b32_e32 v68, v0
	v_mov_b32_e32 v69, v0
	v_mov_b32_e32 v70, v0
	v_mov_b32_e32 v71, v0
	v_mov_b32_e32 v80, v0
	v_mov_b32_e32 v81, v0
	v_mov_b32_e32 v82, v0
	v_mov_b32_e32 v83, v0
	v_mov_b32_e32 v84, v0
	v_mov_b32_e32 v85, v0
	v_mov_b32_e32 v86, v0
	v_mov_b32_e32 v87, v0
	v_mov_b32_e32 v96, v0
	v_mov_b32_e32 v97, v0
	v_mov_b32_e32 v98, v0
	v_mov_b32_e32 v99, v0
	v_mov_b32_e32 v100, v0
	v_mov_b32_e32 v101, v0
	v_mov_b32_e32 v102, v0
	v_mov_b32_e32 v103, v0
	v_mov_b32_e32 v112, v0
	v_mov_b32_e32 v113, v0
	v_mov_b32_e32 v114, v0
	v_mov_b32_e32 v115, v0
	v_mov_b32_e32 v116, v0
	v_mov_b32_e32 v117, v0
	v_mov_b32_e32 v118, v0
	v_mov_b32_e32 v119, v0
	v_mov_b32_e32 v72, v0
	v_mov_b32_e32 v73, v0
	v_mov_b32_e32 v74, v0
	v_mov_b32_e32 v75, v0
	v_mov_b32_e32 v76, v0
	v_mov_b32_e32 v77, v0
	v_mov_b32_e32 v78, v0
	v_mov_b32_e32 v79, v0
	v_mov_b32_e32 v88, v0
	v_mov_b32_e32 v89, v0
	v_mov_b32_e32 v90, v0
	v_mov_b32_e32 v91, v0
	v_mov_b32_e32 v92, v0
	v_mov_b32_e32 v93, v0
	v_mov_b32_e32 v94, v0
	v_mov_b32_e32 v95, v0
	v_mov_b32_e32 v104, v0
	v_mov_b32_e32 v105, v0
	v_mov_b32_e32 v106, v0
	v_mov_b32_e32 v107, v0
	v_mov_b32_e32 v108, v0
	v_mov_b32_e32 v109, v0
	v_mov_b32_e32 v110, v0
	v_mov_b32_e32 v111, v0
	v_mov_b32_e32 v120, v0
	v_mov_b32_e32 v121, v0
	v_mov_b32_e32 v122, v0
	v_mov_b32_e32 v123, v0
	v_mov_b32_e32 v124, v0
	v_mov_b32_e32 v125, v0
	v_mov_b32_e32 v126, v0
	v_mov_b32_e32 v127, v0
	s_cmp_eq_u32 s98, 0
	s_cbranch_scc1 .LBB0_803
	s_add_u32 s4, s12, 0xfff80080
	s_addc_u32 s20, s13, -1
	s_add_i32 s58, 0, 0x10000
	v_add_u32_e32 v140, s58, v161
	ds_read_b128 v[128:131], v140
	ds_read_b128 v[132:135], v140 offset:1024
	ds_read_b128 v[136:139], v140 offset:2048
	ds_read_b128 v[140:143], v140 offset:3072
	s_cmp_eq_u32 s57, 28
	s_cselect_b32 s25, s15, s20
	s_cselect_b32 s24, s45, s4
	s_cselect_b32 s21, s3, s56
	s_cselect_b32 s20, s52, s53
	v_lshl_add_u64 v[158:159], s[12:13], 0, v[150:151]
	s_add_i32 m0, s16, 0xc000
	ds_read_b128 v[154:157], v163
	ds_read_b128 v[164:167], v163 offset:1024
	ds_read_b128 v[168:171], v163 offset:2048
	ds_read_b128 v[172:175], v163 offset:3072
	ds_read_b128 v[176:179], v163 offset:4096
	ds_read_b128 v[180:183], v163 offset:5120
	ds_read_b128 v[196:199], v163 offset:6144
	ds_read_b128 v[200:203], v163 offset:7168
	v_add_u32_e32 v216, 0x14000, v161
	ds_read_b128 v[204:207], v216
	ds_read_b128 v[208:211], v216 offset:1024
	ds_read_b128 v[212:215], v216 offset:2048
	ds_read_b128 v[216:219], v216 offset:3072
	global_load_lds_dwordx4 v150, s[12:13]
	v_lshl_add_u64 v[158:159], s[12:13], 0, v[152:153]
	s_add_i32 m0, s16, 0xe000
	s_nop 0
	global_load_lds_dwordx4 v152, s[12:13]
	s_waitcnt vmcnt(24)
	s_waitcnt lgkmcnt(4)
	s_barrier
	s_setprio 1
	v_mfma_f32_16x16x32_bf16 v[124:127], v[128:131], v[154:157], v[124:127]
	v_mfma_f32_16x16x32_bf16 v[120:123], v[136:139], v[154:157], v[120:123]
	v_mfma_f32_16x16x32_bf16 v[108:111], v[128:131], v[168:171], v[108:111]
	v_mfma_f32_16x16x32_bf16 v[104:107], v[136:139], v[168:171], v[104:107]
	v_mfma_f32_16x16x32_bf16 v[92:95], v[128:131], v[176:179], v[92:95]
	v_mfma_f32_16x16x32_bf16 v[88:91], v[136:139], v[176:179], v[88:91]
	v_mfma_f32_16x16x32_bf16 v[76:79], v[128:131], v[196:199], v[76:79]
	v_mfma_f32_16x16x32_bf16 v[72:75], v[136:139], v[196:199], v[72:75]
	v_mfma_f32_16x16x32_bf16 v[124:127], v[132:135], v[164:167], v[124:127]
	v_mfma_f32_16x16x32_bf16 v[120:123], v[140:143], v[164:167], v[120:123]
	v_mfma_f32_16x16x32_bf16 v[108:111], v[132:135], v[172:175], v[108:111]
	v_mfma_f32_16x16x32_bf16 v[104:107], v[140:143], v[172:175], v[104:107]
	v_mfma_f32_16x16x32_bf16 v[92:95], v[132:135], v[180:183], v[92:95]
	v_mfma_f32_16x16x32_bf16 v[88:91], v[140:143], v[180:183], v[88:91]
	v_mfma_f32_16x16x32_bf16 v[76:79], v[132:135], v[200:203], v[76:79]
	v_mfma_f32_16x16x32_bf16 v[72:75], v[140:143], v[200:203], v[72:75]
	s_waitcnt lgkmcnt(0)
	v_mfma_f32_16x16x32_bf16 v[116:119], v[204:207], v[154:157], v[116:119]
	v_mfma_f32_16x16x32_bf16 v[112:115], v[212:215], v[154:157], v[112:115]
	v_mfma_f32_16x16x32_bf16 v[100:103], v[204:207], v[168:171], v[100:103]
	v_mfma_f32_16x16x32_bf16 v[96:99], v[212:215], v[168:171], v[96:99]
	v_mfma_f32_16x16x32_bf16 v[84:87], v[204:207], v[176:179], v[84:87]
	v_mfma_f32_16x16x32_bf16 v[80:83], v[212:215], v[176:179], v[80:83]
	v_mfma_f32_16x16x32_bf16 v[68:71], v[204:207], v[196:199], v[68:71]
	v_mfma_f32_16x16x32_bf16 v[64:67], v[212:215], v[196:199], v[64:67]
	v_mfma_f32_16x16x32_bf16 v[116:119], v[208:211], v[164:167], v[116:119]
	v_mfma_f32_16x16x32_bf16 v[112:115], v[216:219], v[164:167], v[112:115]
	v_mfma_f32_16x16x32_bf16 v[100:103], v[208:211], v[172:175], v[100:103]
	v_mfma_f32_16x16x32_bf16 v[96:99], v[216:219], v[172:175], v[96:99]
	v_mfma_f32_16x16x32_bf16 v[84:87], v[208:211], v[180:183], v[84:87]
	v_mfma_f32_16x16x32_bf16 v[80:83], v[216:219], v[180:183], v[80:83]
	v_mfma_f32_16x16x32_bf16 v[68:71], v[208:211], v[200:203], v[68:71]
	v_mfma_f32_16x16x32_bf16 v[64:67], v[216:219], v[200:203], v[64:67]
	s_setprio 0
	s_barrier
	s_add_i32 s4, 0, 0x14000
	s_add_i32 s58, s58, s27
	v_lshl_add_u64 v[158:159], s[20:21], 0, v[186:187]
	s_mov_b32 m0, s58
	v_lshl_add_u64 v[220:221], s[20:21], 0, v[144:145]
	global_load_lds_dwordx4 v186, s[20:21]
	s_add_i32 m0, s58, 0x2000
	s_nop 0
	global_load_lds_dwordx4 v144, s[20:21]
	s_mov_b32 m0, s16
	v_lshl_add_u64 v[222:223], s[24:25], 0, v[148:149]
	ds_read_b128 v[154:157], v163 offset:16384
	ds_read_b128 v[164:167], v163 offset:17408
	ds_read_b128 v[168:171], v163 offset:18432
	ds_read_b128 v[172:175], v163 offset:19456
	ds_read_b128 v[176:179], v163 offset:20480
	ds_read_b128 v[180:183], v163 offset:21504
	ds_read_b128 v[196:199], v163 offset:22528
	ds_read_b128 v[200:203], v163 offset:23552
	global_load_lds_dwordx4 v148, s[24:25]
	v_lshl_add_u64 v[224:225], s[24:25], 0, v[146:147]
	s_mov_b32 m0, s17
	s_nop 0
	global_load_lds_dwordx4 v146, s[24:25]
	s_waitcnt vmcnt(22)
	s_waitcnt lgkmcnt(0)
	s_barrier
	s_setprio 1
	v_mfma_f32_16x16x32_bf16 v[60:63], v[128:131], v[154:157], v[60:63]
	v_mfma_f32_16x16x32_bf16 v[56:59], v[136:139], v[154:157], v[56:59]
	v_mfma_f32_16x16x32_bf16 v[44:47], v[128:131], v[168:171], v[44:47]
	v_mfma_f32_16x16x32_bf16 v[40:43], v[136:139], v[168:171], v[40:43]
	v_mfma_f32_16x16x32_bf16 v[28:31], v[128:131], v[176:179], v[28:31]
	v_mfma_f32_16x16x32_bf16 v[24:27], v[136:139], v[176:179], v[24:27]
	v_mfma_f32_16x16x32_bf16 v[12:15], v[128:131], v[196:199], v[12:15]
	v_mfma_f32_16x16x32_bf16 v[8:11], v[136:139], v[196:199], v[8:11]
	v_mfma_f32_16x16x32_bf16 v[60:63], v[132:135], v[164:167], v[60:63]
	v_mfma_f32_16x16x32_bf16 v[56:59], v[140:143], v[164:167], v[56:59]
	v_mfma_f32_16x16x32_bf16 v[44:47], v[132:135], v[172:175], v[44:47]
	v_mfma_f32_16x16x32_bf16 v[40:43], v[140:143], v[172:175], v[40:43]
	v_mfma_f32_16x16x32_bf16 v[28:31], v[132:135], v[180:183], v[28:31]
	v_mfma_f32_16x16x32_bf16 v[24:27], v[140:143], v[180:183], v[24:27]
	v_mfma_f32_16x16x32_bf16 v[12:15], v[132:135], v[200:203], v[12:15]
	v_mfma_f32_16x16x32_bf16 v[8:11], v[140:143], v[200:203], v[8:11]
	v_mfma_f32_16x16x32_bf16 v[52:55], v[204:207], v[154:157], v[52:55]
	v_mfma_f32_16x16x32_bf16 v[48:51], v[212:215], v[154:157], v[48:51]
	v_mfma_f32_16x16x32_bf16 v[36:39], v[204:207], v[168:171], v[36:39]
	v_mfma_f32_16x16x32_bf16 v[32:35], v[212:215], v[168:171], v[32:35]
	v_mfma_f32_16x16x32_bf16 v[20:23], v[204:207], v[176:179], v[20:23]
	v_mfma_f32_16x16x32_bf16 v[16:19], v[212:215], v[176:179], v[16:19]
	v_mfma_f32_16x16x32_bf16 v[4:7], v[204:207], v[196:199], v[4:7]
	v_mfma_f32_16x16x32_bf16 v[0:3], v[212:215], v[196:199], v[0:3]
	v_mfma_f32_16x16x32_bf16 v[52:55], v[208:211], v[164:167], v[52:55]
	v_mfma_f32_16x16x32_bf16 v[48:51], v[216:219], v[164:167], v[48:51]
	v_mfma_f32_16x16x32_bf16 v[36:39], v[208:211], v[172:175], v[36:39]
	v_mfma_f32_16x16x32_bf16 v[32:35], v[216:219], v[172:175], v[32:35]
	v_mfma_f32_16x16x32_bf16 v[20:23], v[208:211], v[180:183], v[20:23]
	v_mfma_f32_16x16x32_bf16 v[16:19], v[216:219], v[180:183], v[16:19]
	v_mfma_f32_16x16x32_bf16 v[4:7], v[208:211], v[200:203], v[4:7]
	v_mfma_f32_16x16x32_bf16 v[0:3], v[216:219], v[200:203], v[0:3]
	s_setprio 0
	s_barrier
	s_add_u32 s58, s20, 0x80000
	s_addc_u32 s59, s21, 0
	s_add_i32 s4, s4, s27
	s_mov_b32 m0, s4
	s_nop 0
	global_load_lds_dwordx4 v186, s[58:59]
	s_add_i32 m0, s4, 0x2000
	s_nop 0
	global_load_lds_dwordx4 v144, s[58:59]
	s_add_i32 s4, 0, 0x18000
	v_add_u32_e32 v140, s4, v161
	ds_read_b128 v[128:131], v140
	ds_read_b128 v[132:135], v140 offset:1024
	ds_read_b128 v[136:139], v140 offset:2048
	ds_read_b128 v[140:143], v140 offset:3072
	s_add_u32 s24, s24, 0x80000
	s_addc_u32 s25, s25, 0
	s_mov_b32 m0, s30
	ds_read_b128 v[154:157], v163 offset:32768
	ds_read_b128 v[164:167], v163 offset:33792
	ds_read_b128 v[168:171], v163 offset:34816
	ds_read_b128 v[172:175], v163 offset:35840
	ds_read_b128 v[176:179], v163 offset:36864
	ds_read_b128 v[180:183], v163 offset:37888
	ds_read_b128 v[196:199], v163 offset:38912
	ds_read_b128 v[200:203], v163 offset:39936
	v_add_u32_e32 v216, 0x1c000, v161
	ds_read_b128 v[204:207], v216
	ds_read_b128 v[208:211], v216 offset:1024
	ds_read_b128 v[212:215], v216 offset:2048
	ds_read_b128 v[216:219], v216 offset:3072
	global_load_lds_dwordx4 v148, s[24:25]
	s_mov_b32 m0, s31
	s_nop 0
	global_load_lds_dwordx4 v146, s[24:25]
	s_waitcnt vmcnt(8)
	s_waitcnt lgkmcnt(0)
	s_barrier
	s_setprio 1
	v_mfma_f32_16x16x32_bf16 v[124:127], v[128:131], v[154:157], v[124:127]
	v_mfma_f32_16x16x32_bf16 v[120:123], v[136:139], v[154:157], v[120:123]
	v_mfma_f32_16x16x32_bf16 v[108:111], v[128:131], v[168:171], v[108:111]
	v_mfma_f32_16x16x32_bf16 v[104:107], v[136:139], v[168:171], v[104:107]
	v_mfma_f32_16x16x32_bf16 v[92:95], v[128:131], v[176:179], v[92:95]
	v_mfma_f32_16x16x32_bf16 v[88:91], v[136:139], v[176:179], v[88:91]
	v_mfma_f32_16x16x32_bf16 v[76:79], v[128:131], v[196:199], v[76:79]
	v_mfma_f32_16x16x32_bf16 v[72:75], v[136:139], v[196:199], v[72:75]
	v_mfma_f32_16x16x32_bf16 v[124:127], v[132:135], v[164:167], v[124:127]
	v_mfma_f32_16x16x32_bf16 v[120:123], v[140:143], v[164:167], v[120:123]
	v_mfma_f32_16x16x32_bf16 v[108:111], v[132:135], v[172:175], v[108:111]
	v_mfma_f32_16x16x32_bf16 v[104:107], v[140:143], v[172:175], v[104:107]
	v_mfma_f32_16x16x32_bf16 v[92:95], v[132:135], v[180:183], v[92:95]
	v_mfma_f32_16x16x32_bf16 v[88:91], v[140:143], v[180:183], v[88:91]
	v_mfma_f32_16x16x32_bf16 v[76:79], v[132:135], v[200:203], v[76:79]
	v_mfma_f32_16x16x32_bf16 v[72:75], v[140:143], v[200:203], v[72:75]
	v_mfma_f32_16x16x32_bf16 v[116:119], v[204:207], v[154:157], v[116:119]
	v_mfma_f32_16x16x32_bf16 v[112:115], v[212:215], v[154:157], v[112:115]
	v_mfma_f32_16x16x32_bf16 v[100:103], v[204:207], v[168:171], v[100:103]
	v_mfma_f32_16x16x32_bf16 v[96:99], v[212:215], v[168:171], v[96:99]
	v_mfma_f32_16x16x32_bf16 v[84:87], v[204:207], v[176:179], v[84:87]
	v_mfma_f32_16x16x32_bf16 v[80:83], v[212:215], v[176:179], v[80:83]
	v_mfma_f32_16x16x32_bf16 v[68:71], v[204:207], v[196:199], v[68:71]
	v_mfma_f32_16x16x32_bf16 v[64:67], v[212:215], v[196:199], v[64:67]
	v_mfma_f32_16x16x32_bf16 v[116:119], v[208:211], v[164:167], v[116:119]
	v_mfma_f32_16x16x32_bf16 v[112:115], v[216:219], v[164:167], v[112:115]
	v_mfma_f32_16x16x32_bf16 v[100:103], v[208:211], v[172:175], v[100:103]
	v_mfma_f32_16x16x32_bf16 v[96:99], v[216:219], v[172:175], v[96:99]
	v_mfma_f32_16x16x32_bf16 v[84:87], v[208:211], v[180:183], v[84:87]
	v_mfma_f32_16x16x32_bf16 v[80:83], v[216:219], v[180:183], v[80:83]
	v_mfma_f32_16x16x32_bf16 v[68:71], v[208:211], v[200:203], v[68:71]
	v_mfma_f32_16x16x32_bf16 v[64:67], v[216:219], v[200:203], v[64:67]
	s_setprio 0
	s_barrier
	s_add_i32 s24, 0, 0x1c000
	s_add_i32 s4, s4, s27
	v_lshl_add_u64 v[158:159], v[158:159], 0, s[0:1]
	s_mov_b32 m0, s4
	global_load_lds_dwordx4 v[158:159], off
	v_lshl_add_u64 v[158:159], v[220:221], 0, s[0:1]
	s_add_i32 m0, s4, 0x2000
	s_nop 0
	global_load_lds_dwordx4 v[158:159], off
	s_mov_b32 m0, s38
	v_lshl_add_u64 v[158:159], v[222:223], 0, s[0:1]
	ds_read_b128 v[154:157], v163 offset:49152
	ds_read_b128 v[164:167], v163 offset:50176
	ds_read_b128 v[168:171], v163 offset:51200
	ds_read_b128 v[172:175], v163 offset:52224
	ds_read_b128 v[176:179], v163 offset:53248
	ds_read_b128 v[180:183], v163 offset:54272
	ds_read_b128 v[196:199], v163 offset:55296
	ds_read_b128 v[200:203], v163 offset:56320
	global_load_lds_dwordx4 v[158:159], off
	v_lshl_add_u64 v[158:159], v[224:225], 0, s[0:1]
	s_mov_b32 m0, s39
	s_nop 0
	global_load_lds_dwordx4 v[158:159], off
	s_add_u32 s20, s20, 0x80080
	s_addc_u32 s21, s21, 0
	s_add_i32 s4, s24, s27
	s_mov_b32 m0, s4
	s_nop 0
	global_load_lds_dwordx4 v186, s[20:21]
	s_add_i32 m0, s4, 0x2000
	s_nop 0
	global_load_lds_dwordx4 v144, s[20:21]
	s_waitcnt vmcnt(8)
	s_waitcnt lgkmcnt(0)
	s_barrier
	s_setprio 1
	v_mfma_f32_16x16x32_bf16 v[60:63], v[128:131], v[154:157], v[60:63]
	v_mfma_f32_16x16x32_bf16 v[56:59], v[136:139], v[154:157], v[56:59]
	v_mfma_f32_16x16x32_bf16 v[44:47], v[128:131], v[168:171], v[44:47]
	v_mfma_f32_16x16x32_bf16 v[40:43], v[136:139], v[168:171], v[40:43]
	v_mfma_f32_16x16x32_bf16 v[28:31], v[128:131], v[176:179], v[28:31]
	v_mfma_f32_16x16x32_bf16 v[24:27], v[136:139], v[176:179], v[24:27]
	v_mfma_f32_16x16x32_bf16 v[12:15], v[128:131], v[196:199], v[12:15]
	v_mfma_f32_16x16x32_bf16 v[8:11], v[136:139], v[196:199], v[8:11]
	v_mfma_f32_16x16x32_bf16 v[60:63], v[132:135], v[164:167], v[60:63]
	v_mfma_f32_16x16x32_bf16 v[56:59], v[140:143], v[164:167], v[56:59]
	v_mfma_f32_16x16x32_bf16 v[44:47], v[132:135], v[172:175], v[44:47]
	v_mfma_f32_16x16x32_bf16 v[40:43], v[140:143], v[172:175], v[40:43]
	v_mfma_f32_16x16x32_bf16 v[28:31], v[132:135], v[180:183], v[28:31]
	v_mfma_f32_16x16x32_bf16 v[24:27], v[140:143], v[180:183], v[24:27]
	v_mfma_f32_16x16x32_bf16 v[12:15], v[132:135], v[200:203], v[12:15]
	v_mfma_f32_16x16x32_bf16 v[8:11], v[140:143], v[200:203], v[8:11]
	v_mfma_f32_16x16x32_bf16 v[52:55], v[204:207], v[154:157], v[52:55]
	v_mfma_f32_16x16x32_bf16 v[48:51], v[212:215], v[154:157], v[48:51]
	v_mfma_f32_16x16x32_bf16 v[36:39], v[204:207], v[168:171], v[36:39]
	v_mfma_f32_16x16x32_bf16 v[32:35], v[212:215], v[168:171], v[32:35]
	v_mfma_f32_16x16x32_bf16 v[20:23], v[204:207], v[176:179], v[20:23]
	v_mfma_f32_16x16x32_bf16 v[16:19], v[212:215], v[176:179], v[16:19]
	v_mfma_f32_16x16x32_bf16 v[4:7], v[204:207], v[196:199], v[4:7]
	v_mfma_f32_16x16x32_bf16 v[0:3], v[212:215], v[196:199], v[0:3]
	v_mfma_f32_16x16x32_bf16 v[52:55], v[208:211], v[164:167], v[52:55]
	v_mfma_f32_16x16x32_bf16 v[48:51], v[216:219], v[164:167], v[48:51]
	v_mfma_f32_16x16x32_bf16 v[36:39], v[208:211], v[172:175], v[36:39]
	v_mfma_f32_16x16x32_bf16 v[32:35], v[216:219], v[172:175], v[32:35]
	v_mfma_f32_16x16x32_bf16 v[20:23], v[208:211], v[180:183], v[20:23]
	v_mfma_f32_16x16x32_bf16 v[16:19], v[216:219], v[180:183], v[16:19]
	v_mfma_f32_16x16x32_bf16 v[4:7], v[208:211], v[200:203], v[4:7]
	v_mfma_f32_16x16x32_bf16 v[0:3], v[216:219], v[200:203], v[0:3]
	s_setprio 0
	s_add_i32 s57, s57, 2
	s_add_u32 s12, s12, 0x100
	s_addc_u32 s13, s13, 0
	s_add_u32 s53, s53, 0x100
	s_addc_u32 s56, s56, 0
	s_cmp_gt_u32 s57, 29
	s_barrier
	s_cbranch_scc1 .Lgemm_epi_2
.LBB0_803:
	s_add_u32 s4, s12, 0xfff80080
	s_addc_u32 s20, s13, -1
	s_add_i32 s58, 0, 0x10000
	v_add_u32_e32 v140, s58, v161
	ds_read_b128 v[128:131], v140
	ds_read_b128 v[132:135], v140 offset:1024
	ds_read_b128 v[136:139], v140 offset:2048
	ds_read_b128 v[140:143], v140 offset:3072
	s_cmp_eq_u32 s57, 28
	s_cselect_b32 s25, s15, s20
	s_cselect_b32 s24, s45, s4
	s_cselect_b32 s21, s3, s56
	s_cselect_b32 s20, s52, s53
	v_lshl_add_u64 v[158:159], s[12:13], 0, v[150:151]
	s_add_i32 m0, s16, 0xc000
	ds_read_b128 v[154:157], v163
	ds_read_b128 v[164:167], v163 offset:1024
	ds_read_b128 v[168:171], v163 offset:2048
	ds_read_b128 v[172:175], v163 offset:3072
	ds_read_b128 v[176:179], v163 offset:4096
	ds_read_b128 v[180:183], v163 offset:5120
	ds_read_b128 v[196:199], v163 offset:6144
	ds_read_b128 v[200:203], v163 offset:7168
	v_add_u32_e32 v216, 0x14000, v161
	ds_read_b128 v[204:207], v216
	ds_read_b128 v[208:211], v216 offset:1024
	ds_read_b128 v[212:215], v216 offset:2048
	ds_read_b128 v[216:219], v216 offset:3072
	global_load_lds_dwordx4 v150, s[12:13]
	v_lshl_add_u64 v[158:159], s[12:13], 0, v[152:153]
	s_add_i32 m0, s16, 0xe000
	s_nop 0
	global_load_lds_dwordx4 v152, s[12:13]
	s_waitcnt vmcnt(8)
	s_waitcnt lgkmcnt(4)
	s_barrier
	s_setprio 1
	v_mfma_f32_16x16x32_bf16 v[124:127], v[128:131], v[154:157], v[124:127]
	v_mfma_f32_16x16x32_bf16 v[120:123], v[136:139], v[154:157], v[120:123]
	v_mfma_f32_16x16x32_bf16 v[108:111], v[128:131], v[168:171], v[108:111]
	v_mfma_f32_16x16x32_bf16 v[104:107], v[136:139], v[168:171], v[104:107]
	v_mfma_f32_16x16x32_bf16 v[92:95], v[128:131], v[176:179], v[92:95]
	v_mfma_f32_16x16x32_bf16 v[88:91], v[136:139], v[176:179], v[88:91]
	v_mfma_f32_16x16x32_bf16 v[76:79], v[128:131], v[196:199], v[76:79]
	v_mfma_f32_16x16x32_bf16 v[72:75], v[136:139], v[196:199], v[72:75]
	v_mfma_f32_16x16x32_bf16 v[124:127], v[132:135], v[164:167], v[124:127]
	v_mfma_f32_16x16x32_bf16 v[120:123], v[140:143], v[164:167], v[120:123]
	v_mfma_f32_16x16x32_bf16 v[108:111], v[132:135], v[172:175], v[108:111]
	v_mfma_f32_16x16x32_bf16 v[104:107], v[140:143], v[172:175], v[104:107]
	v_mfma_f32_16x16x32_bf16 v[92:95], v[132:135], v[180:183], v[92:95]
	v_mfma_f32_16x16x32_bf16 v[88:91], v[140:143], v[180:183], v[88:91]
	v_mfma_f32_16x16x32_bf16 v[76:79], v[132:135], v[200:203], v[76:79]
	v_mfma_f32_16x16x32_bf16 v[72:75], v[140:143], v[200:203], v[72:75]
	s_waitcnt lgkmcnt(0)
	v_mfma_f32_16x16x32_bf16 v[116:119], v[204:207], v[154:157], v[116:119]
	v_mfma_f32_16x16x32_bf16 v[112:115], v[212:215], v[154:157], v[112:115]
	v_mfma_f32_16x16x32_bf16 v[100:103], v[204:207], v[168:171], v[100:103]
	v_mfma_f32_16x16x32_bf16 v[96:99], v[212:215], v[168:171], v[96:99]
	v_mfma_f32_16x16x32_bf16 v[84:87], v[204:207], v[176:179], v[84:87]
	v_mfma_f32_16x16x32_bf16 v[80:83], v[212:215], v[176:179], v[80:83]
	v_mfma_f32_16x16x32_bf16 v[68:71], v[204:207], v[196:199], v[68:71]
	v_mfma_f32_16x16x32_bf16 v[64:67], v[212:215], v[196:199], v[64:67]
	v_mfma_f32_16x16x32_bf16 v[116:119], v[208:211], v[164:167], v[116:119]
	v_mfma_f32_16x16x32_bf16 v[112:115], v[216:219], v[164:167], v[112:115]
	v_mfma_f32_16x16x32_bf16 v[100:103], v[208:211], v[172:175], v[100:103]
	v_mfma_f32_16x16x32_bf16 v[96:99], v[216:219], v[172:175], v[96:99]
	v_mfma_f32_16x16x32_bf16 v[84:87], v[208:211], v[180:183], v[84:87]
	v_mfma_f32_16x16x32_bf16 v[80:83], v[216:219], v[180:183], v[80:83]
	v_mfma_f32_16x16x32_bf16 v[68:71], v[208:211], v[200:203], v[68:71]
	v_mfma_f32_16x16x32_bf16 v[64:67], v[216:219], v[200:203], v[64:67]
	s_setprio 0
	s_barrier
	s_add_i32 s4, 0, 0x14000
	s_add_i32 s58, s58, s27
	v_lshl_add_u64 v[158:159], s[20:21], 0, v[186:187]
	s_mov_b32 m0, s58
	v_lshl_add_u64 v[220:221], s[20:21], 0, v[144:145]
	global_load_lds_dwordx4 v186, s[20:21]
	s_add_i32 m0, s58, 0x2000
	s_nop 0
	global_load_lds_dwordx4 v144, s[20:21]
	s_mov_b32 m0, s16
	v_lshl_add_u64 v[222:223], s[24:25], 0, v[148:149]
	ds_read_b128 v[154:157], v163 offset:16384
	ds_read_b128 v[164:167], v163 offset:17408
	ds_read_b128 v[168:171], v163 offset:18432
	ds_read_b128 v[172:175], v163 offset:19456
	ds_read_b128 v[176:179], v163 offset:20480
	ds_read_b128 v[180:183], v163 offset:21504
	ds_read_b128 v[196:199], v163 offset:22528
	ds_read_b128 v[200:203], v163 offset:23552
	global_load_lds_dwordx4 v148, s[24:25]
	v_lshl_add_u64 v[224:225], s[24:25], 0, v[146:147]
	s_mov_b32 m0, s17
	s_nop 0
	global_load_lds_dwordx4 v146, s[24:25]
	s_waitcnt vmcnt(6)
	s_waitcnt lgkmcnt(0)
	s_barrier
	s_setprio 1
	v_mfma_f32_16x16x32_bf16 v[60:63], v[128:131], v[154:157], v[60:63]
	v_mfma_f32_16x16x32_bf16 v[56:59], v[136:139], v[154:157], v[56:59]
	v_mfma_f32_16x16x32_bf16 v[44:47], v[128:131], v[168:171], v[44:47]
	v_mfma_f32_16x16x32_bf16 v[40:43], v[136:139], v[168:171], v[40:43]
	v_mfma_f32_16x16x32_bf16 v[28:31], v[128:131], v[176:179], v[28:31]
	v_mfma_f32_16x16x32_bf16 v[24:27], v[136:139], v[176:179], v[24:27]
	v_mfma_f32_16x16x32_bf16 v[12:15], v[128:131], v[196:199], v[12:15]
	v_mfma_f32_16x16x32_bf16 v[8:11], v[136:139], v[196:199], v[8:11]
	v_mfma_f32_16x16x32_bf16 v[60:63], v[132:135], v[164:167], v[60:63]
	v_mfma_f32_16x16x32_bf16 v[56:59], v[140:143], v[164:167], v[56:59]
	v_mfma_f32_16x16x32_bf16 v[44:47], v[132:135], v[172:175], v[44:47]
	v_mfma_f32_16x16x32_bf16 v[40:43], v[140:143], v[172:175], v[40:43]
	v_mfma_f32_16x16x32_bf16 v[28:31], v[132:135], v[180:183], v[28:31]
	v_mfma_f32_16x16x32_bf16 v[24:27], v[140:143], v[180:183], v[24:27]
	v_mfma_f32_16x16x32_bf16 v[12:15], v[132:135], v[200:203], v[12:15]
	v_mfma_f32_16x16x32_bf16 v[8:11], v[140:143], v[200:203], v[8:11]
	v_mfma_f32_16x16x32_bf16 v[52:55], v[204:207], v[154:157], v[52:55]
	v_mfma_f32_16x16x32_bf16 v[48:51], v[212:215], v[154:157], v[48:51]
	v_mfma_f32_16x16x32_bf16 v[36:39], v[204:207], v[168:171], v[36:39]
	v_mfma_f32_16x16x32_bf16 v[32:35], v[212:215], v[168:171], v[32:35]
	v_mfma_f32_16x16x32_bf16 v[20:23], v[204:207], v[176:179], v[20:23]
	v_mfma_f32_16x16x32_bf16 v[16:19], v[212:215], v[176:179], v[16:19]
	v_mfma_f32_16x16x32_bf16 v[4:7], v[204:207], v[196:199], v[4:7]
	v_mfma_f32_16x16x32_bf16 v[0:3], v[212:215], v[196:199], v[0:3]
	v_mfma_f32_16x16x32_bf16 v[52:55], v[208:211], v[164:167], v[52:55]
	v_mfma_f32_16x16x32_bf16 v[48:51], v[216:219], v[164:167], v[48:51]
	v_mfma_f32_16x16x32_bf16 v[36:39], v[208:211], v[172:175], v[36:39]
	v_mfma_f32_16x16x32_bf16 v[32:35], v[216:219], v[172:175], v[32:35]
	v_mfma_f32_16x16x32_bf16 v[20:23], v[208:211], v[180:183], v[20:23]
	v_mfma_f32_16x16x32_bf16 v[16:19], v[216:219], v[180:183], v[16:19]
	v_mfma_f32_16x16x32_bf16 v[4:7], v[208:211], v[200:203], v[4:7]
	v_mfma_f32_16x16x32_bf16 v[0:3], v[216:219], v[200:203], v[0:3]
	s_setprio 0
	s_barrier
	s_add_u32 s58, s20, 0x80000
	s_addc_u32 s59, s21, 0
	s_add_i32 s4, s4, s27
	s_mov_b32 m0, s4
	s_nop 0
	global_load_lds_dwordx4 v186, s[58:59]
	s_add_i32 m0, s4, 0x2000
	s_nop 0
	global_load_lds_dwordx4 v144, s[58:59]
	s_add_i32 s4, 0, 0x18000
	v_add_u32_e32 v140, s4, v161
	ds_read_b128 v[128:131], v140
	ds_read_b128 v[132:135], v140 offset:1024
	ds_read_b128 v[136:139], v140 offset:2048
	ds_read_b128 v[140:143], v140 offset:3072
	s_add_u32 s24, s24, 0x80000
	s_addc_u32 s25, s25, 0
	s_mov_b32 m0, s30
	ds_read_b128 v[154:157], v163 offset:32768
	ds_read_b128 v[164:167], v163 offset:33792
	ds_read_b128 v[168:171], v163 offset:34816
	ds_read_b128 v[172:175], v163 offset:35840
	ds_read_b128 v[176:179], v163 offset:36864
	ds_read_b128 v[180:183], v163 offset:37888
	ds_read_b128 v[196:199], v163 offset:38912
	ds_read_b128 v[200:203], v163 offset:39936
	v_add_u32_e32 v216, 0x1c000, v161
	ds_read_b128 v[204:207], v216
	ds_read_b128 v[208:211], v216 offset:1024
	ds_read_b128 v[212:215], v216 offset:2048
	ds_read_b128 v[216:219], v216 offset:3072
	global_load_lds_dwordx4 v148, s[24:25]
	s_mov_b32 m0, s31
	s_nop 0
	global_load_lds_dwordx4 v146, s[24:25]
	s_waitcnt vmcnt(8)
	s_waitcnt lgkmcnt(0)
	s_barrier
	s_setprio 1
	v_mfma_f32_16x16x32_bf16 v[124:127], v[128:131], v[154:157], v[124:127]
	v_mfma_f32_16x16x32_bf16 v[120:123], v[136:139], v[154:157], v[120:123]
	v_mfma_f32_16x16x32_bf16 v[108:111], v[128:131], v[168:171], v[108:111]
	v_mfma_f32_16x16x32_bf16 v[104:107], v[136:139], v[168:171], v[104:107]
	v_mfma_f32_16x16x32_bf16 v[92:95], v[128:131], v[176:179], v[92:95]
	v_mfma_f32_16x16x32_bf16 v[88:91], v[136:139], v[176:179], v[88:91]
	v_mfma_f32_16x16x32_bf16 v[76:79], v[128:131], v[196:199], v[76:79]
	v_mfma_f32_16x16x32_bf16 v[72:75], v[136:139], v[196:199], v[72:75]
	v_mfma_f32_16x16x32_bf16 v[124:127], v[132:135], v[164:167], v[124:127]
	v_mfma_f32_16x16x32_bf16 v[120:123], v[140:143], v[164:167], v[120:123]
	v_mfma_f32_16x16x32_bf16 v[108:111], v[132:135], v[172:175], v[108:111]
	v_mfma_f32_16x16x32_bf16 v[104:107], v[140:143], v[172:175], v[104:107]
	v_mfma_f32_16x16x32_bf16 v[92:95], v[132:135], v[180:183], v[92:95]
	v_mfma_f32_16x16x32_bf16 v[88:91], v[140:143], v[180:183], v[88:91]
	v_mfma_f32_16x16x32_bf16 v[76:79], v[132:135], v[200:203], v[76:79]
	v_mfma_f32_16x16x32_bf16 v[72:75], v[140:143], v[200:203], v[72:75]
	v_mfma_f32_16x16x32_bf16 v[116:119], v[204:207], v[154:157], v[116:119]
	v_mfma_f32_16x16x32_bf16 v[112:115], v[212:215], v[154:157], v[112:115]
	v_mfma_f32_16x16x32_bf16 v[100:103], v[204:207], v[168:171], v[100:103]
	v_mfma_f32_16x16x32_bf16 v[96:99], v[212:215], v[168:171], v[96:99]
	v_mfma_f32_16x16x32_bf16 v[84:87], v[204:207], v[176:179], v[84:87]
	v_mfma_f32_16x16x32_bf16 v[80:83], v[212:215], v[176:179], v[80:83]
	v_mfma_f32_16x16x32_bf16 v[68:71], v[204:207], v[196:199], v[68:71]
	v_mfma_f32_16x16x32_bf16 v[64:67], v[212:215], v[196:199], v[64:67]
	v_mfma_f32_16x16x32_bf16 v[116:119], v[208:211], v[164:167], v[116:119]
	v_mfma_f32_16x16x32_bf16 v[112:115], v[216:219], v[164:167], v[112:115]
	v_mfma_f32_16x16x32_bf16 v[100:103], v[208:211], v[172:175], v[100:103]
	v_mfma_f32_16x16x32_bf16 v[96:99], v[216:219], v[172:175], v[96:99]
	v_mfma_f32_16x16x32_bf16 v[84:87], v[208:211], v[180:183], v[84:87]
	v_mfma_f32_16x16x32_bf16 v[80:83], v[216:219], v[180:183], v[80:83]
	v_mfma_f32_16x16x32_bf16 v[68:71], v[208:211], v[200:203], v[68:71]
	v_mfma_f32_16x16x32_bf16 v[64:67], v[216:219], v[200:203], v[64:67]
	s_setprio 0
	s_barrier
	s_add_i32 s24, 0, 0x1c000
	s_add_i32 s4, s4, s27
	v_lshl_add_u64 v[158:159], v[158:159], 0, s[0:1]
	s_mov_b32 m0, s4
	global_load_lds_dwordx4 v[158:159], off
	v_lshl_add_u64 v[158:159], v[220:221], 0, s[0:1]
	s_add_i32 m0, s4, 0x2000
	s_nop 0
	global_load_lds_dwordx4 v[158:159], off
	s_mov_b32 m0, s38
	v_lshl_add_u64 v[158:159], v[222:223], 0, s[0:1]
	ds_read_b128 v[154:157], v163 offset:49152
	ds_read_b128 v[164:167], v163 offset:50176
	ds_read_b128 v[168:171], v163 offset:51200
	ds_read_b128 v[172:175], v163 offset:52224
	ds_read_b128 v[176:179], v163 offset:53248
	ds_read_b128 v[180:183], v163 offset:54272
	ds_read_b128 v[196:199], v163 offset:55296
	ds_read_b128 v[200:203], v163 offset:56320
	global_load_lds_dwordx4 v[158:159], off
	v_lshl_add_u64 v[158:159], v[224:225], 0, s[0:1]
	s_mov_b32 m0, s39
	s_nop 0
	global_load_lds_dwordx4 v[158:159], off
	s_add_u32 s20, s20, 0x80080
	s_addc_u32 s21, s21, 0
	s_add_i32 s4, s24, s27
	s_mov_b32 m0, s4
	s_nop 0
	global_load_lds_dwordx4 v186, s[20:21]
	s_add_i32 m0, s4, 0x2000
	s_nop 0
	global_load_lds_dwordx4 v144, s[20:21]
	s_waitcnt vmcnt(8)
	s_waitcnt lgkmcnt(0)
	s_barrier
	s_setprio 1
	v_mfma_f32_16x16x32_bf16 v[60:63], v[128:131], v[154:157], v[60:63]
	v_mfma_f32_16x16x32_bf16 v[56:59], v[136:139], v[154:157], v[56:59]
	v_mfma_f32_16x16x32_bf16 v[44:47], v[128:131], v[168:171], v[44:47]
	v_mfma_f32_16x16x32_bf16 v[40:43], v[136:139], v[168:171], v[40:43]
	v_mfma_f32_16x16x32_bf16 v[28:31], v[128:131], v[176:179], v[28:31]
	v_mfma_f32_16x16x32_bf16 v[24:27], v[136:139], v[176:179], v[24:27]
	v_mfma_f32_16x16x32_bf16 v[12:15], v[128:131], v[196:199], v[12:15]
	v_mfma_f32_16x16x32_bf16 v[8:11], v[136:139], v[196:199], v[8:11]
	v_mfma_f32_16x16x32_bf16 v[60:63], v[132:135], v[164:167], v[60:63]
	v_mfma_f32_16x16x32_bf16 v[56:59], v[140:143], v[164:167], v[56:59]
	v_mfma_f32_16x16x32_bf16 v[44:47], v[132:135], v[172:175], v[44:47]
	v_mfma_f32_16x16x32_bf16 v[40:43], v[140:143], v[172:175], v[40:43]
	v_mfma_f32_16x16x32_bf16 v[28:31], v[132:135], v[180:183], v[28:31]
	v_mfma_f32_16x16x32_bf16 v[24:27], v[140:143], v[180:183], v[24:27]
	v_mfma_f32_16x16x32_bf16 v[12:15], v[132:135], v[200:203], v[12:15]
	v_mfma_f32_16x16x32_bf16 v[8:11], v[140:143], v[200:203], v[8:11]
	v_mfma_f32_16x16x32_bf16 v[52:55], v[204:207], v[154:157], v[52:55]
	v_mfma_f32_16x16x32_bf16 v[48:51], v[212:215], v[154:157], v[48:51]
	v_mfma_f32_16x16x32_bf16 v[36:39], v[204:207], v[168:171], v[36:39]
	v_mfma_f32_16x16x32_bf16 v[32:35], v[212:215], v[168:171], v[32:35]
	v_mfma_f32_16x16x32_bf16 v[20:23], v[204:207], v[176:179], v[20:23]
	v_mfma_f32_16x16x32_bf16 v[16:19], v[212:215], v[176:179], v[16:19]
	v_mfma_f32_16x16x32_bf16 v[4:7], v[204:207], v[196:199], v[4:7]
	v_mfma_f32_16x16x32_bf16 v[0:3], v[212:215], v[196:199], v[0:3]
	v_mfma_f32_16x16x32_bf16 v[52:55], v[208:211], v[164:167], v[52:55]
	v_mfma_f32_16x16x32_bf16 v[48:51], v[216:219], v[164:167], v[48:51]
	v_mfma_f32_16x16x32_bf16 v[36:39], v[208:211], v[172:175], v[36:39]
	v_mfma_f32_16x16x32_bf16 v[32:35], v[216:219], v[172:175], v[32:35]
	v_mfma_f32_16x16x32_bf16 v[20:23], v[208:211], v[180:183], v[20:23]
	v_mfma_f32_16x16x32_bf16 v[16:19], v[216:219], v[180:183], v[16:19]
	v_mfma_f32_16x16x32_bf16 v[4:7], v[208:211], v[200:203], v[4:7]
	v_mfma_f32_16x16x32_bf16 v[0:3], v[216:219], v[200:203], v[0:3]
	s_setprio 0
	s_add_i32 s57, s57, 2
	s_add_u32 s12, s12, 0x100
	s_addc_u32 s13, s13, 0
	s_add_u32 s53, s53, 0x100
	s_addc_u32 s56, s56, 0
	s_cmp_gt_u32 s57, 29
	s_barrier
	s_cbranch_scc0 .LBB0_803

.LBB0_889:
	s_add_u32 s4, s12, 0xffe00080
	s_addc_u32 s20, s13, -1
	s_add_i32 s58, 0, 0x10000
	v_add_u32_e32 v124, s58, v161
	ds_read_b128 v[104:107], v124
	ds_read_b128 v[108:111], v124 offset:1024
	ds_read_b128 v[116:119], v124 offset:2048
	ds_read_b128 v[124:127], v124 offset:3072
	s_cmpk_eq_i32 vcc_hi, 0x7c
	s_cselect_b32 s25, s29, s20
	s_cselect_b32 s24, s57, s4
	s_cselect_b32 s21, s19, vcc_lo
	s_cselect_b32 s20, s68, s69
	s_add_i32 m0, s22, 0xc000
	ds_read_b128 v[152:155], v163
	ds_read_b128 v[156:159], v163 offset:1024
	ds_read_b128 v[164:167], v163 offset:2048
	ds_read_b128 v[168:171], v163 offset:3072
	ds_read_b128 v[172:175], v163 offset:4096
	ds_read_b128 v[176:179], v163 offset:5120
	ds_read_b128 v[180:183], v163 offset:6144
	ds_read_b128 v[196:199], v163 offset:7168
	v_add_u32_e32 v212, 0x14000, v161
	ds_read_b128 v[200:203], v212
	ds_read_b128 v[204:207], v212 offset:1024
	ds_read_b128 v[208:211], v212 offset:2048
	ds_read_b128 v[212:215], v212 offset:3072
	global_load_lds_dwordx4 v148, s[12:13]
	s_add_i32 m0, s22, 0xe000
	s_nop 0
	global_load_lds_dwordx4 v150, s[12:13]
	s_waitcnt vmcnt(8)
	s_waitcnt lgkmcnt(4)
	s_barrier
	s_setprio 1
	v_mfma_f32_16x16x32_bf16 v[140:143], v[104:107], v[152:155], v[140:143]
	v_mfma_f32_16x16x32_bf16 v[136:139], v[116:119], v[152:155], v[136:139]
	v_mfma_f32_16x16x32_bf16 v[120:123], v[104:107], v[164:167], v[120:123]
	v_mfma_f32_16x16x32_bf16 v[112:115], v[116:119], v[164:167], v[112:115]
	v_mfma_f32_16x16x32_bf16 v[92:95], v[104:107], v[172:175], v[92:95]
	v_mfma_f32_16x16x32_bf16 v[88:91], v[116:119], v[172:175], v[88:91]
	v_mfma_f32_16x16x32_bf16 v[76:79], v[104:107], v[180:183], v[76:79]
	v_mfma_f32_16x16x32_bf16 v[72:75], v[116:119], v[180:183], v[72:75]
	v_mfma_f32_16x16x32_bf16 v[140:143], v[108:111], v[156:159], v[140:143]
	v_mfma_f32_16x16x32_bf16 v[136:139], v[124:127], v[156:159], v[136:139]
	v_mfma_f32_16x16x32_bf16 v[120:123], v[108:111], v[168:171], v[120:123]
	v_mfma_f32_16x16x32_bf16 v[112:115], v[124:127], v[168:171], v[112:115]
	v_mfma_f32_16x16x32_bf16 v[92:95], v[108:111], v[176:179], v[92:95]
	v_mfma_f32_16x16x32_bf16 v[88:91], v[124:127], v[176:179], v[88:91]
	v_mfma_f32_16x16x32_bf16 v[76:79], v[108:111], v[196:199], v[76:79]
	v_mfma_f32_16x16x32_bf16 v[72:75], v[124:127], v[196:199], v[72:75]
	s_waitcnt lgkmcnt(0)
	v_mfma_f32_16x16x32_bf16 v[132:135], v[200:203], v[152:155], v[132:135]
	v_mfma_f32_16x16x32_bf16 v[128:131], v[208:211], v[152:155], v[128:131]
	v_mfma_f32_16x16x32_bf16 v[100:103], v[200:203], v[164:167], v[100:103]
	v_mfma_f32_16x16x32_bf16 v[96:99], v[208:211], v[164:167], v[96:99]
	v_mfma_f32_16x16x32_bf16 v[84:87], v[200:203], v[172:175], v[84:87]
	v_mfma_f32_16x16x32_bf16 v[80:83], v[208:211], v[172:175], v[80:83]
	v_mfma_f32_16x16x32_bf16 v[68:71], v[200:203], v[180:183], v[68:71]
	v_mfma_f32_16x16x32_bf16 v[64:67], v[208:211], v[180:183], v[64:67]
	v_mfma_f32_16x16x32_bf16 v[132:135], v[204:207], v[156:159], v[132:135]
	v_mfma_f32_16x16x32_bf16 v[128:131], v[212:215], v[156:159], v[128:131]
	v_mfma_f32_16x16x32_bf16 v[100:103], v[204:207], v[168:171], v[100:103]
	v_mfma_f32_16x16x32_bf16 v[96:99], v[212:215], v[168:171], v[96:99]
	v_mfma_f32_16x16x32_bf16 v[84:87], v[204:207], v[176:179], v[84:87]
	v_mfma_f32_16x16x32_bf16 v[80:83], v[212:215], v[176:179], v[80:83]
	v_mfma_f32_16x16x32_bf16 v[68:71], v[204:207], v[196:199], v[68:71]
	v_mfma_f32_16x16x32_bf16 v[64:67], v[212:215], v[196:199], v[64:67]
	s_setprio 0
	s_barrier
	s_add_i32 s4, 0, 0x14000
	s_add_i32 s58, s58, s27
	v_lshl_add_u64 v[216:217], s[20:21], 0, v[146:147]
	s_mov_b32 m0, s58
	global_load_lds_dwordx4 v146, s[20:21]
	v_lshl_add_u64 v[218:219], s[20:21], 0, v[144:145]
	s_add_i32 m0, s58, 0x2000
	s_nop 0
	global_load_lds_dwordx4 v144, s[20:21]
	s_mov_b32 m0, s22
	v_lshl_add_u64 v[220:221], s[24:25], 0, v[146:147]
	ds_read_b128 v[152:155], v163 offset:16384
	ds_read_b128 v[156:159], v163 offset:17408
	ds_read_b128 v[164:167], v163 offset:18432
	ds_read_b128 v[168:171], v163 offset:19456
	ds_read_b128 v[172:175], v163 offset:20480
	ds_read_b128 v[176:179], v163 offset:21504
	ds_read_b128 v[180:183], v163 offset:22528
	ds_read_b128 v[196:199], v163 offset:23552
	global_load_lds_dwordx4 v146, s[24:25]
	v_lshl_add_u64 v[222:223], s[24:25], 0, v[144:145]
	s_mov_b32 m0, s23
	s_nop 0
	global_load_lds_dwordx4 v144, s[24:25]
	s_waitcnt vmcnt(6)
	s_waitcnt lgkmcnt(0)
	s_barrier
	s_setprio 1
	v_mfma_f32_16x16x32_bf16 v[60:63], v[104:107], v[152:155], v[60:63]
	v_mfma_f32_16x16x32_bf16 v[56:59], v[116:119], v[152:155], v[56:59]
	v_mfma_f32_16x16x32_bf16 v[44:47], v[104:107], v[164:167], v[44:47]
	v_mfma_f32_16x16x32_bf16 v[40:43], v[116:119], v[164:167], v[40:43]
	v_mfma_f32_16x16x32_bf16 v[28:31], v[104:107], v[172:175], v[28:31]
	v_mfma_f32_16x16x32_bf16 v[24:27], v[116:119], v[172:175], v[24:27]
	v_mfma_f32_16x16x32_bf16 v[12:15], v[104:107], v[180:183], v[12:15]
	v_mfma_f32_16x16x32_bf16 v[8:11], v[116:119], v[180:183], v[8:11]
	v_mfma_f32_16x16x32_bf16 v[60:63], v[108:111], v[156:159], v[60:63]
	v_mfma_f32_16x16x32_bf16 v[56:59], v[124:127], v[156:159], v[56:59]
	v_mfma_f32_16x16x32_bf16 v[44:47], v[108:111], v[168:171], v[44:47]
	v_mfma_f32_16x16x32_bf16 v[40:43], v[124:127], v[168:171], v[40:43]
	v_mfma_f32_16x16x32_bf16 v[28:31], v[108:111], v[176:179], v[28:31]
	v_mfma_f32_16x16x32_bf16 v[24:27], v[124:127], v[176:179], v[24:27]
	v_mfma_f32_16x16x32_bf16 v[12:15], v[108:111], v[196:199], v[12:15]
	v_mfma_f32_16x16x32_bf16 v[8:11], v[124:127], v[196:199], v[8:11]
	v_mfma_f32_16x16x32_bf16 v[52:55], v[200:203], v[152:155], v[52:55]
	v_mfma_f32_16x16x32_bf16 v[48:51], v[208:211], v[152:155], v[48:51]
	v_mfma_f32_16x16x32_bf16 v[36:39], v[200:203], v[164:167], v[36:39]
	v_mfma_f32_16x16x32_bf16 v[32:35], v[208:211], v[164:167], v[32:35]
	v_mfma_f32_16x16x32_bf16 v[20:23], v[200:203], v[172:175], v[20:23]
	v_mfma_f32_16x16x32_bf16 v[16:19], v[208:211], v[172:175], v[16:19]
	v_mfma_f32_16x16x32_bf16 v[4:7], v[200:203], v[180:183], v[4:7]
	v_mfma_f32_16x16x32_bf16 v[0:3], v[208:211], v[180:183], v[0:3]
	v_mfma_f32_16x16x32_bf16 v[52:55], v[204:207], v[156:159], v[52:55]
	v_mfma_f32_16x16x32_bf16 v[48:51], v[212:215], v[156:159], v[48:51]
	v_mfma_f32_16x16x32_bf16 v[36:39], v[204:207], v[168:171], v[36:39]
	v_mfma_f32_16x16x32_bf16 v[32:35], v[212:215], v[168:171], v[32:35]
	v_mfma_f32_16x16x32_bf16 v[20:23], v[204:207], v[176:179], v[20:23]
	v_mfma_f32_16x16x32_bf16 v[16:19], v[212:215], v[176:179], v[16:19]
	v_mfma_f32_16x16x32_bf16 v[4:7], v[204:207], v[196:199], v[4:7]
	v_mfma_f32_16x16x32_bf16 v[0:3], v[212:215], v[196:199], v[0:3]
	s_setprio 0
	s_barrier
	s_add_u32 s58, s20, 0x200000
	s_addc_u32 s59, s21, 0
	s_add_i32 s4, s4, s27
	s_mov_b32 m0, s4
	s_nop 0
	global_load_lds_dwordx4 v146, s[58:59]
	s_add_i32 m0, s4, 0x2000
	s_nop 0
	global_load_lds_dwordx4 v144, s[58:59]
	s_add_i32 s4, 0, 0x18000
	v_add_u32_e32 v124, s4, v161
	ds_read_b128 v[104:107], v124
	ds_read_b128 v[108:111], v124 offset:1024
	ds_read_b128 v[116:119], v124 offset:2048
	ds_read_b128 v[124:127], v124 offset:3072
	s_add_u32 s24, s24, 0x200000
	s_addc_u32 s25, s25, 0
	s_mov_b32 m0, s30
	ds_read_b128 v[152:155], v163 offset:32768
	ds_read_b128 v[156:159], v163 offset:33792
	ds_read_b128 v[164:167], v163 offset:34816
	ds_read_b128 v[168:171], v163 offset:35840
	ds_read_b128 v[172:175], v163 offset:36864
	ds_read_b128 v[176:179], v163 offset:37888
	ds_read_b128 v[180:183], v163 offset:38912
	ds_read_b128 v[196:199], v163 offset:39936
	v_add_u32_e32 v212, 0x1c000, v161
	ds_read_b128 v[200:203], v212
	ds_read_b128 v[204:207], v212 offset:1024
	ds_read_b128 v[208:211], v212 offset:2048
	ds_read_b128 v[212:215], v212 offset:3072
	global_load_lds_dwordx4 v146, s[24:25]
	s_mov_b32 m0, s31
	s_nop 0
	global_load_lds_dwordx4 v144, s[24:25]
	s_waitcnt vmcnt(8)
	s_waitcnt lgkmcnt(0)
	s_barrier
	s_setprio 1
	v_mfma_f32_16x16x32_bf16 v[140:143], v[104:107], v[152:155], v[140:143]
	v_mfma_f32_16x16x32_bf16 v[136:139], v[116:119], v[152:155], v[136:139]
	v_mfma_f32_16x16x32_bf16 v[120:123], v[104:107], v[164:167], v[120:123]
	v_mfma_f32_16x16x32_bf16 v[112:115], v[116:119], v[164:167], v[112:115]
	v_mfma_f32_16x16x32_bf16 v[92:95], v[104:107], v[172:175], v[92:95]
	v_mfma_f32_16x16x32_bf16 v[88:91], v[116:119], v[172:175], v[88:91]
	v_mfma_f32_16x16x32_bf16 v[76:79], v[104:107], v[180:183], v[76:79]
	v_mfma_f32_16x16x32_bf16 v[72:75], v[116:119], v[180:183], v[72:75]
	v_mfma_f32_16x16x32_bf16 v[140:143], v[108:111], v[156:159], v[140:143]
	v_mfma_f32_16x16x32_bf16 v[136:139], v[124:127], v[156:159], v[136:139]
	v_mfma_f32_16x16x32_bf16 v[120:123], v[108:111], v[168:171], v[120:123]
	v_mfma_f32_16x16x32_bf16 v[112:115], v[124:127], v[168:171], v[112:115]
	v_mfma_f32_16x16x32_bf16 v[92:95], v[108:111], v[176:179], v[92:95]
	v_mfma_f32_16x16x32_bf16 v[88:91], v[124:127], v[176:179], v[88:91]
	v_mfma_f32_16x16x32_bf16 v[76:79], v[108:111], v[196:199], v[76:79]
	v_mfma_f32_16x16x32_bf16 v[72:75], v[124:127], v[196:199], v[72:75]
	v_mfma_f32_16x16x32_bf16 v[132:135], v[200:203], v[152:155], v[132:135]
	v_mfma_f32_16x16x32_bf16 v[128:131], v[208:211], v[152:155], v[128:131]
	v_mfma_f32_16x16x32_bf16 v[100:103], v[200:203], v[164:167], v[100:103]
	v_mfma_f32_16x16x32_bf16 v[96:99], v[208:211], v[164:167], v[96:99]
	v_mfma_f32_16x16x32_bf16 v[84:87], v[200:203], v[172:175], v[84:87]
	v_mfma_f32_16x16x32_bf16 v[80:83], v[208:211], v[172:175], v[80:83]
	v_mfma_f32_16x16x32_bf16 v[68:71], v[200:203], v[180:183], v[68:71]
	v_mfma_f32_16x16x32_bf16 v[64:67], v[208:211], v[180:183], v[64:67]
	v_mfma_f32_16x16x32_bf16 v[132:135], v[204:207], v[156:159], v[132:135]
	v_mfma_f32_16x16x32_bf16 v[128:131], v[212:215], v[156:159], v[128:131]
	v_mfma_f32_16x16x32_bf16 v[100:103], v[204:207], v[168:171], v[100:103]
	v_mfma_f32_16x16x32_bf16 v[96:99], v[212:215], v[168:171], v[96:99]
	v_mfma_f32_16x16x32_bf16 v[84:87], v[204:207], v[176:179], v[84:87]
	v_mfma_f32_16x16x32_bf16 v[80:83], v[212:215], v[176:179], v[80:83]
	v_mfma_f32_16x16x32_bf16 v[68:71], v[204:207], v[196:199], v[68:71]
	v_mfma_f32_16x16x32_bf16 v[64:67], v[212:215], v[196:199], v[64:67]
	s_setprio 0
	s_barrier
	s_add_i32 s24, 0, 0x1c000
	s_add_i32 s4, s4, s27
	v_lshl_add_u64 v[216:217], v[216:217], 0, s[0:1]
	s_mov_b32 m0, s4
	global_load_lds_dwordx4 v[216:217], off
	v_lshl_add_u64 v[216:217], v[218:219], 0, s[0:1]
	s_add_i32 m0, s4, 0x2000
	s_nop 0
	global_load_lds_dwordx4 v[216:217], off
	s_mov_b32 m0, s16
	v_lshl_add_u64 v[216:217], v[220:221], 0, s[0:1]
	ds_read_b128 v[152:155], v163 offset:49152
	ds_read_b128 v[156:159], v163 offset:50176
	ds_read_b128 v[164:167], v163 offset:51200
	ds_read_b128 v[168:171], v163 offset:52224
	ds_read_b128 v[172:175], v163 offset:53248
	ds_read_b128 v[176:179], v163 offset:54272
	ds_read_b128 v[180:183], v163 offset:55296
	ds_read_b128 v[196:199], v163 offset:56320
	global_load_lds_dwordx4 v[216:217], off
	v_lshl_add_u64 v[216:217], v[222:223], 0, s[0:1]
	s_mov_b32 m0, s17
	s_nop 0
	global_load_lds_dwordx4 v[216:217], off
	s_add_u32 s20, s20, 0x200080
	s_addc_u32 s21, s21, 0
	s_add_i32 s4, s24, s27
	s_mov_b32 m0, s4
	s_nop 0
	global_load_lds_dwordx4 v146, s[20:21]
	s_add_i32 m0, s4, 0x2000
	s_nop 0
	global_load_lds_dwordx4 v144, s[20:21]
	s_waitcnt vmcnt(8)
	s_waitcnt lgkmcnt(0)
	s_barrier
	s_setprio 1
	v_mfma_f32_16x16x32_bf16 v[60:63], v[104:107], v[152:155], v[60:63]
	v_mfma_f32_16x16x32_bf16 v[56:59], v[116:119], v[152:155], v[56:59]
	v_mfma_f32_16x16x32_bf16 v[44:47], v[104:107], v[164:167], v[44:47]
	v_mfma_f32_16x16x32_bf16 v[40:43], v[116:119], v[164:167], v[40:43]
	v_mfma_f32_16x16x32_bf16 v[28:31], v[104:107], v[172:175], v[28:31]
	v_mfma_f32_16x16x32_bf16 v[24:27], v[116:119], v[172:175], v[24:27]
	v_mfma_f32_16x16x32_bf16 v[12:15], v[104:107], v[180:183], v[12:15]
	v_mfma_f32_16x16x32_bf16 v[8:11], v[116:119], v[180:183], v[8:11]
	v_mfma_f32_16x16x32_bf16 v[60:63], v[108:111], v[156:159], v[60:63]
	v_mfma_f32_16x16x32_bf16 v[56:59], v[124:127], v[156:159], v[56:59]
	v_mfma_f32_16x16x32_bf16 v[44:47], v[108:111], v[168:171], v[44:47]
	v_mfma_f32_16x16x32_bf16 v[40:43], v[124:127], v[168:171], v[40:43]
	v_mfma_f32_16x16x32_bf16 v[28:31], v[108:111], v[176:179], v[28:31]
	v_mfma_f32_16x16x32_bf16 v[24:27], v[124:127], v[176:179], v[24:27]
	v_mfma_f32_16x16x32_bf16 v[12:15], v[108:111], v[196:199], v[12:15]
	v_mfma_f32_16x16x32_bf16 v[8:11], v[124:127], v[196:199], v[8:11]
	v_mfma_f32_16x16x32_bf16 v[52:55], v[200:203], v[152:155], v[52:55]
	v_mfma_f32_16x16x32_bf16 v[48:51], v[208:211], v[152:155], v[48:51]
	v_mfma_f32_16x16x32_bf16 v[36:39], v[200:203], v[164:167], v[36:39]
	v_mfma_f32_16x16x32_bf16 v[32:35], v[208:211], v[164:167], v[32:35]
	v_mfma_f32_16x16x32_bf16 v[20:23], v[200:203], v[172:175], v[20:23]
	v_mfma_f32_16x16x32_bf16 v[16:19], v[208:211], v[172:175], v[16:19]
	v_mfma_f32_16x16x32_bf16 v[4:7], v[200:203], v[180:183], v[4:7]
	v_mfma_f32_16x16x32_bf16 v[0:3], v[208:211], v[180:183], v[0:3]
	v_mfma_f32_16x16x32_bf16 v[52:55], v[204:207], v[156:159], v[52:55]
	v_mfma_f32_16x16x32_bf16 v[48:51], v[212:215], v[156:159], v[48:51]
	v_mfma_f32_16x16x32_bf16 v[36:39], v[204:207], v[168:171], v[36:39]
	v_mfma_f32_16x16x32_bf16 v[32:35], v[212:215], v[168:171], v[32:35]
	v_mfma_f32_16x16x32_bf16 v[20:23], v[204:207], v[176:179], v[20:23]
	v_mfma_f32_16x16x32_bf16 v[16:19], v[212:215], v[176:179], v[16:19]
	v_mfma_f32_16x16x32_bf16 v[4:7], v[204:207], v[196:199], v[4:7]
	v_mfma_f32_16x16x32_bf16 v[0:3], v[212:215], v[196:199], v[0:3]
	s_setprio 0
	s_add_i32 vcc_hi, vcc_hi, 2
	s_add_u32 s12, s12, 0x100
	s_addc_u32 s13, s13, 0
	s_add_u32 s69, s69, 0x100
	s_addc_u32 vcc_lo, vcc_lo, 0
	s_cmpk_gt_u32 vcc_hi, 0x7d
	s_barrier
	s_cbranch_scc0 .LBB0_889
	s_lshl_b32 s4, s56, 8
	s_add_i32 s4, s4, s35
	s_min_i32 s12, s4, 0x4000
	s_ashr_i32 s12, s12, 11
	s_mul_hi_i32 s13, s12, 0xc000
	s_mul_i32 s12, s12, 0xc000
	v_lshl_or_b32 v154, s53, 8, v162
	s_add_u32 s12, s8, s12
	s_addc_u32 s13, s9, s13
	v_ashrrev_i32_e32 v155, 31, v154
	v_lshl_add_u64 v[104:105], v[154:155], 2, s[12:13]
	global_load_dwordx4 v[124:127], v[104:105], off
	global_load_dwordx4 v[116:119], v[104:105], off offset:64
	global_load_dwordx4 v[108:111], v[104:105], off offset:512
	s_nop 0
	global_load_dwordx4 v[104:107], v[104:105], off offset:576
	v_add_u32_e32 v152, s4, v160
	s_movk_i32 s4, 0x3fff
	v_cmp_lt_i32_e32 vcc, s4, v152
	s_and_saveexec_b64 s[12:13], vcc
	s_xor_b64 s[12:13], exec, s[12:13]
	v_add_u32_e32 v186, 0xffffc000, v152
	v_lshlrev_b64 v[156:157], 13, v[186:187]
	v_mov_b32_e32 v153, v187
	v_lshl_add_u64 v[158:159], s[10:11], 0, v[156:157]
	v_lshlrev_b64 v[156:157], 13, v[152:153]
	s_andn2_saveexec_b64 s[12:13], s[12:13]
	v_ashrrev_i32_e32 v153, 31, v152
	v_lshlrev_b64 v[156:157], 13, v[152:153]
	v_lshl_add_u64 v[158:159], s[66:67], 0, v[156:157]
	s_or_b64 exec, exec, s[12:13]
	v_lshlrev_b64 v[154:155], 2, v[154:155]
	v_lshl_add_u64 v[158:159], v[158:159], 0, v[154:155]
	global_load_dwordx4 v[164:167], v[158:159], off
	v_lshl_add_u64 v[156:157], s[66:67], 0, v[156:157]
	v_lshl_add_u64 v[156:157], v[156:157], 0, v[154:155]
	s_movk_i32 s4, 0x3fef
	v_cmp_lt_i32_e32 vcc, s4, v152
	s_waitcnt vmcnt(0)
	v_pk_fma_f32 v[142:143], v[142:143], v[126:127], v[166:167]
	v_pk_fma_f32 v[140:141], v[140:141], v[124:125], v[164:165]
	global_store_dwordx4 v[156:157], v[140:143], off
	global_load_dwordx4 v[140:143], v[158:159], off offset:64
	s_waitcnt vmcnt(0)
	v_pk_fma_f32 v[138:139], v[138:139], v[118:119], v[142:143]
	v_pk_fma_f32 v[136:137], v[136:137], v[116:117], v[140:141]
	global_store_dwordx4 v[156:157], v[136:139], off offset:64
	global_load_dwordx4 v[136:139], v[158:159], off offset:512
	s_waitcnt vmcnt(0)
	v_pk_fma_f32 v[134:135], v[134:135], v[110:111], v[138:139]
	v_pk_fma_f32 v[132:133], v[132:133], v[108:109], v[136:137]
	global_store_dwordx4 v[156:157], v[132:135], off offset:512
	global_load_dwordx4 v[134:137], v[158:159], off offset:576
	s_waitcnt vmcnt(0)
	v_pk_fma_f32 v[130:131], v[130:131], v[106:107], v[136:137]
	v_or_b32_e32 v132, 16, v152
	v_pk_fma_f32 v[128:129], v[128:129], v[104:105], v[134:135]
	global_store_dwordx4 v[156:157], v[128:131], off offset:576
	s_and_saveexec_b64 s[12:13], vcc
	s_xor_b64 s[12:13], exec, s[12:13]
	v_add_u32_e32 v186, 0xffffc010, v152
	v_lshlrev_b64 v[128:129], 13, v[186:187]
	v_mov_b32_e32 v133, v187
	v_lshl_add_u64 v[130:131], s[10:11], 0, v[128:129]
	v_lshlrev_b64 v[128:129], 13, v[132:133]
	s_andn2_saveexec_b64 s[12:13], s[12:13]
	v_ashrrev_i32_e32 v133, 31, v132
	v_lshlrev_b64 v[128:129], 13, v[132:133]
	v_lshl_add_u64 v[130:131], s[66:67], 0, v[128:129]
	s_or_b64 exec, exec, s[12:13]
	v_lshl_add_u64 v[134:135], v[130:131], 0, v[154:155]
	global_load_dwordx4 v[130:133], v[134:135], off
	v_lshl_add_u64 v[128:129], s[66:67], 0, v[128:129]
	v_lshl_add_u64 v[128:129], v[128:129], 0, v[154:155]
	s_movk_i32 s4, 0x3fdf
	v_cmp_lt_i32_e32 vcc, s4, v152
	s_waitcnt vmcnt(0)
	v_pk_fma_f32 v[122:123], v[122:123], v[126:127], v[132:133]
	v_pk_fma_f32 v[120:121], v[120:121], v[124:125], v[130:131]
	global_store_dwordx4 v[128:129], v[120:123], off
	global_load_dwordx4 v[120:123], v[134:135], off offset:64
	s_waitcnt vmcnt(0)
	v_pk_fma_f32 v[114:115], v[114:115], v[118:119], v[122:123]
	v_pk_fma_f32 v[112:113], v[112:113], v[116:117], v[120:121]
	global_store_dwordx4 v[128:129], v[112:115], off offset:64
	global_load_dwordx4 v[112:115], v[134:135], off offset:512
	s_waitcnt vmcnt(0)
	v_pk_fma_f32 v[102:103], v[102:103], v[110:111], v[114:115]
	v_pk_fma_f32 v[100:101], v[100:101], v[108:109], v[112:113]
	global_store_dwordx4 v[128:129], v[100:103], off offset:512
	global_load_dwordx4 v[112:115], v[134:135], off offset:576
	s_waitcnt vmcnt(0)
	v_pk_fma_f32 v[98:99], v[98:99], v[106:107], v[114:115]
	v_or_b32_e32 v100, 32, v152
	v_pk_fma_f32 v[96:97], v[96:97], v[104:105], v[112:113]
	global_store_dwordx4 v[128:129], v[96:99], off offset:576
	s_and_saveexec_b64 s[12:13], vcc
	s_xor_b64 s[12:13], exec, s[12:13]
	v_add_u32_e32 v186, 0xffffc020, v152
	v_lshlrev_b64 v[96:97], 13, v[186:187]
	v_mov_b32_e32 v101, v187
	v_lshl_add_u64 v[98:99], s[10:11], 0, v[96:97]
	v_lshlrev_b64 v[96:97], 13, v[100:101]
	s_andn2_saveexec_b64 s[12:13], s[12:13]
	v_ashrrev_i32_e32 v101, 31, v100
	v_lshlrev_b64 v[96:97], 13, v[100:101]
	v_lshl_add_u64 v[98:99], s[66:67], 0, v[96:97]
	s_or_b64 exec, exec, s[12:13]
	v_lshl_add_u64 v[102:103], v[98:99], 0, v[154:155]
	global_load_dwordx4 v[98:101], v[102:103], off
	v_lshl_add_u64 v[96:97], s[66:67], 0, v[96:97]
	v_lshl_add_u64 v[96:97], v[96:97], 0, v[154:155]
	s_movk_i32 s4, 0x3fcf
	v_cmp_lt_i32_e32 vcc, s4, v152
	s_waitcnt vmcnt(0)
	v_pk_fma_f32 v[94:95], v[94:95], v[126:127], v[100:101]
	v_pk_fma_f32 v[92:93], v[92:93], v[124:125], v[98:99]
	global_store_dwordx4 v[96:97], v[92:95], off
	global_load_dwordx4 v[92:95], v[102:103], off offset:64
	s_waitcnt vmcnt(0)
	v_pk_fma_f32 v[90:91], v[90:91], v[118:119], v[94:95]
	v_pk_fma_f32 v[88:89], v[88:89], v[116:117], v[92:93]
	global_store_dwordx4 v[96:97], v[88:91], off offset:64
	global_load_dwordx4 v[88:91], v[102:103], off offset:512
	s_waitcnt vmcnt(0)
	v_pk_fma_f32 v[86:87], v[86:87], v[110:111], v[90:91]
	v_pk_fma_f32 v[84:85], v[84:85], v[108:109], v[88:89]
	global_store_dwordx4 v[96:97], v[84:87], off offset:512
	global_load_dwordx4 v[86:89], v[102:103], off offset:576
	s_waitcnt vmcnt(0)
	v_pk_fma_f32 v[82:83], v[82:83], v[106:107], v[88:89]
	v_or_b32_e32 v84, 48, v152
	v_pk_fma_f32 v[80:81], v[80:81], v[104:105], v[86:87]
	global_store_dwordx4 v[96:97], v[80:83], off offset:576
	s_and_saveexec_b64 s[12:13], vcc
	s_xor_b64 s[12:13], exec, s[12:13]
	v_add_u32_e32 v186, 0xffffc030, v152
	v_lshlrev_b64 v[80:81], 13, v[186:187]
	v_mov_b32_e32 v85, v187
	v_lshl_add_u64 v[82:83], s[10:11], 0, v[80:81]
	v_lshlrev_b64 v[80:81], 13, v[84:85]
	s_andn2_saveexec_b64 s[12:13], s[12:13]
	v_ashrrev_i32_e32 v85, 31, v84
	v_lshlrev_b64 v[80:81], 13, v[84:85]
	v_lshl_add_u64 v[82:83], s[66:67], 0, v[80:81]
	s_or_b64 exec, exec, s[12:13]
	v_lshl_add_u64 v[86:87], v[82:83], 0, v[154:155]
	global_load_dwordx4 v[82:85], v[86:87], off
	v_lshl_add_u64 v[80:81], s[66:67], 0, v[80:81]
	v_lshl_add_u64 v[80:81], v[80:81], 0, v[154:155]
	s_movk_i32 s4, 0x3f7f
	v_cmp_lt_i32_e32 vcc, s4, v152
	s_waitcnt vmcnt(0)
	v_pk_fma_f32 v[78:79], v[78:79], v[126:127], v[84:85]
	v_pk_fma_f32 v[76:77], v[76:77], v[124:125], v[82:83]
	global_store_dwordx4 v[80:81], v[76:79], off
	global_load_dwordx4 v[76:79], v[86:87], off offset:64
	s_waitcnt vmcnt(0)
	v_pk_fma_f32 v[74:75], v[74:75], v[118:119], v[78:79]
	v_pk_fma_f32 v[72:73], v[72:73], v[116:117], v[76:77]
	global_store_dwordx4 v[80:81], v[72:75], off offset:64
	global_load_dwordx4 v[72:75], v[86:87], off offset:512
	s_waitcnt vmcnt(0)
	v_pk_fma_f32 v[70:71], v[70:71], v[110:111], v[74:75]
	v_pk_fma_f32 v[68:69], v[68:69], v[108:109], v[72:73]
	global_store_dwordx4 v[80:81], v[68:71], off offset:512
	global_load_dwordx4 v[70:73], v[86:87], off offset:576
	s_waitcnt vmcnt(0)
	v_pk_fma_f32 v[66:67], v[66:67], v[106:107], v[72:73]
	v_add_u32_e32 v68, 0x80, v152
	v_pk_fma_f32 v[64:65], v[64:65], v[104:105], v[70:71]
	global_store_dwordx4 v[80:81], v[64:67], off offset:576
	s_and_saveexec_b64 s[12:13], vcc
	s_xor_b64 s[12:13], exec, s[12:13]
	v_add_u32_e32 v186, 0xffffc080, v152
	v_lshlrev_b64 v[64:65], 13, v[186:187]
	v_mov_b32_e32 v69, v187
	v_lshl_add_u64 v[66:67], s[10:11], 0, v[64:65]
	v_lshlrev_b64 v[64:65], 13, v[68:69]
	s_andn2_saveexec_b64 s[12:13], s[12:13]
	v_ashrrev_i32_e32 v69, 31, v68
	v_lshlrev_b64 v[64:65], 13, v[68:69]
	v_lshl_add_u64 v[66:67], s[66:67], 0, v[64:65]
	s_or_b64 exec, exec, s[12:13]
	v_lshl_add_u64 v[70:71], v[66:67], 0, v[154:155]
	global_load_dwordx4 v[66:69], v[70:71], off
	v_lshl_add_u64 v[64:65], s[66:67], 0, v[64:65]
	v_lshl_add_u64 v[64:65], v[64:65], 0, v[154:155]
	s_movk_i32 s4, 0x3f6f
	v_cmp_lt_i32_e32 vcc, s4, v152
	s_waitcnt vmcnt(0)
	v_pk_fma_f32 v[62:63], v[62:63], v[126:127], v[68:69]
	v_pk_fma_f32 v[60:61], v[60:61], v[124:125], v[66:67]
	global_store_dwordx4 v[64:65], v[60:63], off
	global_load_dwordx4 v[60:63], v[70:71], off offset:64
	s_waitcnt vmcnt(0)
	v_pk_fma_f32 v[58:59], v[58:59], v[118:119], v[62:63]
	v_pk_fma_f32 v[56:57], v[56:57], v[116:117], v[60:61]
	global_store_dwordx4 v[64:65], v[56:59], off offset:64
	global_load_dwordx4 v[56:59], v[70:71], off offset:512
	s_waitcnt vmcnt(0)
	v_pk_fma_f32 v[54:55], v[54:55], v[110:111], v[58:59]
	v_pk_fma_f32 v[52:53], v[52:53], v[108:109], v[56:57]
	global_store_dwordx4 v[64:65], v[52:55], off offset:512
	global_load_dwordx4 v[54:57], v[70:71], off offset:576
	s_waitcnt vmcnt(0)
	v_pk_fma_f32 v[50:51], v[50:51], v[106:107], v[56:57]
	v_add_u32_e32 v52, 0x90, v152
	v_pk_fma_f32 v[48:49], v[48:49], v[104:105], v[54:55]
	global_store_dwordx4 v[64:65], v[48:51], off offset:576
	s_and_saveexec_b64 s[12:13], vcc
	s_xor_b64 s[12:13], exec, s[12:13]
	v_add_u32_e32 v186, 0xffffc090, v152
	v_lshlrev_b64 v[48:49], 13, v[186:187]
	v_mov_b32_e32 v53, v187
	v_lshl_add_u64 v[50:51], s[10:11], 0, v[48:49]
	v_lshlrev_b64 v[48:49], 13, v[52:53]
	s_andn2_saveexec_b64 s[12:13], s[12:13]
	v_ashrrev_i32_e32 v53, 31, v52
	v_lshlrev_b64 v[48:49], 13, v[52:53]
	v_lshl_add_u64 v[50:51], s[66:67], 0, v[48:49]
	s_or_b64 exec, exec, s[12:13]
	v_lshl_add_u64 v[54:55], v[50:51], 0, v[154:155]
	global_load_dwordx4 v[50:53], v[54:55], off
	v_lshl_add_u64 v[48:49], s[66:67], 0, v[48:49]
	v_lshl_add_u64 v[48:49], v[48:49], 0, v[154:155]
	s_movk_i32 s4, 0x3f5f
	v_cmp_lt_i32_e32 vcc, s4, v152
	s_waitcnt vmcnt(0)
	v_pk_fma_f32 v[46:47], v[46:47], v[126:127], v[52:53]
	v_pk_fma_f32 v[44:45], v[44:45], v[124:125], v[50:51]
	global_store_dwordx4 v[48:49], v[44:47], off
	global_load_dwordx4 v[44:47], v[54:55], off offset:64
	s_waitcnt vmcnt(0)
	v_pk_fma_f32 v[42:43], v[42:43], v[118:119], v[46:47]
	v_pk_fma_f32 v[40:41], v[40:41], v[116:117], v[44:45]
	global_store_dwordx4 v[48:49], v[40:43], off offset:64
	global_load_dwordx4 v[40:43], v[54:55], off offset:512
	s_waitcnt vmcnt(0)
	v_pk_fma_f32 v[38:39], v[38:39], v[110:111], v[42:43]
	v_pk_fma_f32 v[36:37], v[36:37], v[108:109], v[40:41]
	global_store_dwordx4 v[48:49], v[36:39], off offset:512
	global_load_dwordx4 v[38:41], v[54:55], off offset:576
	s_waitcnt vmcnt(0)
	v_pk_fma_f32 v[34:35], v[34:35], v[106:107], v[40:41]
	v_add_u32_e32 v36, 0xa0, v152
	v_pk_fma_f32 v[32:33], v[32:33], v[104:105], v[38:39]
	global_store_dwordx4 v[48:49], v[32:35], off offset:576
	s_and_saveexec_b64 s[12:13], vcc
	s_xor_b64 s[12:13], exec, s[12:13]
	v_add_u32_e32 v186, 0xffffc0a0, v152
	v_lshlrev_b64 v[32:33], 13, v[186:187]
	v_mov_b32_e32 v37, v187
	v_lshl_add_u64 v[34:35], s[10:11], 0, v[32:33]
	v_lshlrev_b64 v[32:33], 13, v[36:37]
	s_andn2_saveexec_b64 s[12:13], s[12:13]
	v_ashrrev_i32_e32 v37, 31, v36
	v_lshlrev_b64 v[32:33], 13, v[36:37]
	v_lshl_add_u64 v[34:35], s[66:67], 0, v[32:33]
	s_or_b64 exec, exec, s[12:13]
	v_lshl_add_u64 v[38:39], v[34:35], 0, v[154:155]
	global_load_dwordx4 v[34:37], v[38:39], off
	v_lshl_add_u64 v[32:33], s[66:67], 0, v[32:33]
	v_lshl_add_u64 v[32:33], v[32:33], 0, v[154:155]
	s_movk_i32 s4, 0x3f4f
	v_cmp_lt_i32_e32 vcc, s4, v152
	s_waitcnt vmcnt(0)
	v_pk_fma_f32 v[30:31], v[30:31], v[126:127], v[36:37]
	v_pk_fma_f32 v[28:29], v[28:29], v[124:125], v[34:35]
	global_store_dwordx4 v[32:33], v[28:31], off
	global_load_dwordx4 v[28:31], v[38:39], off offset:64
	s_waitcnt vmcnt(0)
	v_pk_fma_f32 v[26:27], v[26:27], v[118:119], v[30:31]
	v_pk_fma_f32 v[24:25], v[24:25], v[116:117], v[28:29]
	global_store_dwordx4 v[32:33], v[24:27], off offset:64
	global_load_dwordx4 v[24:27], v[38:39], off offset:512
	s_waitcnt vmcnt(0)
	v_pk_fma_f32 v[22:23], v[22:23], v[110:111], v[26:27]
	v_pk_fma_f32 v[20:21], v[20:21], v[108:109], v[24:25]
	global_store_dwordx4 v[32:33], v[20:23], off offset:512
	global_load_dwordx4 v[22:25], v[38:39], off offset:576
	s_waitcnt vmcnt(0)
	v_pk_fma_f32 v[18:19], v[18:19], v[106:107], v[24:25]
	v_add_u32_e32 v20, 0xb0, v152
	v_pk_fma_f32 v[16:17], v[16:17], v[104:105], v[22:23]
	global_store_dwordx4 v[32:33], v[16:19], off offset:576
	s_and_saveexec_b64 s[12:13], vcc
	s_xor_b64 s[12:13], exec, s[12:13]
	v_add_u32_e32 v186, 0xffffc0b0, v152
	v_lshlrev_b64 v[16:17], 13, v[186:187]
	v_mov_b32_e32 v21, v187
	v_lshl_add_u64 v[16:17], s[10:11], 0, v[16:17]
	v_lshlrev_b64 v[18:19], 13, v[20:21]
	s_andn2_saveexec_b64 s[12:13], s[12:13]
	s_cbranch_execz .LBB0_881
	v_ashrrev_i32_e32 v21, 31, v20
	v_lshlrev_b64 v[18:19], 13, v[20:21]
	v_lshl_add_u64 v[16:17], s[66:67], 0, v[18:19]
	s_branch .LBB0_881

.LBB0_940:
	s_add_u32 s24, s2, vcc_lo
	s_addc_u32 s25, s3, vcc_hi
	s_add_u32 s24, s24, 0x100
	s_addc_u32 s25, s25, 0
	s_add_u32 s61, s19, vcc_lo
	s_addc_u32 s62, s4, vcc_hi
	s_add_i32 s63, 0, 0x10000
	v_add_u32_e32 v152, s63, v138
	ds_read_b128 v[140:143], v152
	ds_read_b128 v[144:147], v152 offset:1024
	ds_read_b128 v[148:151], v152 offset:2048
	ds_read_b128 v[152:155], v152 offset:3072
	s_cmpk_eq_i32 vcc_lo, 0x3f00
	s_cselect_b32 s27, s39, s25
	s_cselect_b32 s26, s58, s24
	s_cselect_b32 s25, s29, s62
	s_cselect_b32 s24, s59, s61
	v_lshl_add_u64 v[182:183], v[134:135], 0, vcc
	s_add_i32 m0, s23, 0xc000
	ds_read_b128 v[156:159], v139
	ds_read_b128 v[162:165], v139 offset:1024
	ds_read_b128 v[166:169], v139 offset:2048
	ds_read_b128 v[170:173], v139 offset:3072
	ds_read_b128 v[174:177], v139 offset:4096
	ds_read_b128 v[178:181], v139 offset:5120
	ds_read_b128 v[196:199], v139 offset:6144
	ds_read_b128 v[200:203], v139 offset:7168
	global_load_lds_dwordx4 v[182:183], off
	v_lshl_add_u64 v[182:183], v[136:137], 0, vcc
	s_add_i32 m0, s23, 0xe000
	s_nop 0
	global_load_lds_dwordx4 v[182:183], off
	v_add_u32_e32 v216, 0x14000, v138
	ds_read_b128 v[204:207], v216
	ds_read_b128 v[208:211], v216 offset:1024
	ds_read_b128 v[212:215], v216 offset:2048
	ds_read_b128 v[216:219], v216 offset:3072
	s_waitcnt vmcnt(8)
	s_waitcnt lgkmcnt(4)
	s_barrier
	s_setprio 1
	v_mfma_f32_16x16x32_bf16 v[124:127], v[140:143], v[156:159], v[124:127]
	v_mfma_f32_16x16x32_bf16 v[120:123], v[148:151], v[156:159], v[120:123]
	v_mfma_f32_16x16x32_bf16 v[108:111], v[140:143], v[166:169], v[108:111]
	v_mfma_f32_16x16x32_bf16 v[104:107], v[148:151], v[166:169], v[104:107]
	v_mfma_f32_16x16x32_bf16 v[92:95], v[140:143], v[174:177], v[92:95]
	v_mfma_f32_16x16x32_bf16 v[88:91], v[148:151], v[174:177], v[88:91]
	v_mfma_f32_16x16x32_bf16 v[76:79], v[140:143], v[196:199], v[76:79]
	v_mfma_f32_16x16x32_bf16 v[72:75], v[148:151], v[196:199], v[72:75]
	v_mfma_f32_16x16x32_bf16 v[124:127], v[144:147], v[162:165], v[124:127]
	v_mfma_f32_16x16x32_bf16 v[120:123], v[152:155], v[162:165], v[120:123]
	v_mfma_f32_16x16x32_bf16 v[108:111], v[144:147], v[170:173], v[108:111]
	v_mfma_f32_16x16x32_bf16 v[104:107], v[152:155], v[170:173], v[104:107]
	v_mfma_f32_16x16x32_bf16 v[92:95], v[144:147], v[178:181], v[92:95]
	v_mfma_f32_16x16x32_bf16 v[88:91], v[152:155], v[178:181], v[88:91]
	v_mfma_f32_16x16x32_bf16 v[76:79], v[144:147], v[200:203], v[76:79]
	v_mfma_f32_16x16x32_bf16 v[72:75], v[152:155], v[200:203], v[72:75]
	s_waitcnt lgkmcnt(0)
	v_mfma_f32_16x16x32_bf16 v[116:119], v[204:207], v[156:159], v[116:119]
	v_mfma_f32_16x16x32_bf16 v[112:115], v[212:215], v[156:159], v[112:115]
	v_mfma_f32_16x16x32_bf16 v[100:103], v[204:207], v[166:169], v[100:103]
	v_mfma_f32_16x16x32_bf16 v[96:99], v[212:215], v[166:169], v[96:99]
	v_mfma_f32_16x16x32_bf16 v[84:87], v[204:207], v[174:177], v[84:87]
	v_mfma_f32_16x16x32_bf16 v[80:83], v[212:215], v[174:177], v[80:83]
	v_mfma_f32_16x16x32_bf16 v[68:71], v[204:207], v[196:199], v[68:71]
	v_mfma_f32_16x16x32_bf16 v[64:67], v[212:215], v[196:199], v[64:67]
	v_mfma_f32_16x16x32_bf16 v[116:119], v[208:211], v[162:165], v[116:119]
	v_mfma_f32_16x16x32_bf16 v[112:115], v[216:219], v[162:165], v[112:115]
	v_mfma_f32_16x16x32_bf16 v[100:103], v[208:211], v[170:173], v[100:103]
	v_mfma_f32_16x16x32_bf16 v[96:99], v[216:219], v[170:173], v[96:99]
	v_mfma_f32_16x16x32_bf16 v[84:87], v[208:211], v[178:181], v[84:87]
	v_mfma_f32_16x16x32_bf16 v[80:83], v[216:219], v[178:181], v[80:83]
	v_mfma_f32_16x16x32_bf16 v[68:71], v[208:211], v[200:203], v[68:71]
	v_mfma_f32_16x16x32_bf16 v[64:67], v[216:219], v[200:203], v[64:67]
	s_setprio 0
	s_barrier
	s_add_i32 s61, 0, 0x14000
	s_add_i32 s62, s63, s17
	v_lshl_add_u64 v[182:183], s[24:25], 0, v[186:187]
	s_mov_b32 m0, s62
	global_load_lds_dwordx4 v186, s[24:25]
	v_lshl_add_u64 v[220:221], s[24:25], 0, v[128:129]
	s_add_i32 m0, s62, 0x2000
	s_nop 0
	global_load_lds_dwordx4 v128, s[24:25]
	s_mov_b32 m0, s23
	v_lshl_add_u64 v[222:223], s[26:27], 0, v[186:187]
	ds_read_b128 v[156:159], v139 offset:16384
	ds_read_b128 v[162:165], v139 offset:17408
	ds_read_b128 v[166:169], v139 offset:18432
	ds_read_b128 v[170:173], v139 offset:19456
	ds_read_b128 v[174:177], v139 offset:20480
	ds_read_b128 v[178:181], v139 offset:21504
	ds_read_b128 v[196:199], v139 offset:22528
	ds_read_b128 v[200:203], v139 offset:23552
	global_load_lds_dwordx4 v186, s[26:27]
	v_lshl_add_u64 v[224:225], s[26:27], 0, v[128:129]
	s_mov_b32 m0, s30
	s_nop 0
	global_load_lds_dwordx4 v128, s[26:27]
	s_waitcnt vmcnt(6)
	s_waitcnt lgkmcnt(0)
	s_barrier
	s_setprio 1
	v_mfma_f32_16x16x32_bf16 v[60:63], v[140:143], v[156:159], v[60:63]
	v_mfma_f32_16x16x32_bf16 v[56:59], v[148:151], v[156:159], v[56:59]
	v_mfma_f32_16x16x32_bf16 v[44:47], v[140:143], v[166:169], v[44:47]
	v_mfma_f32_16x16x32_bf16 v[40:43], v[148:151], v[166:169], v[40:43]
	v_mfma_f32_16x16x32_bf16 v[32:35], v[140:143], v[174:177], v[32:35]
	v_mfma_f32_16x16x32_bf16 v[24:27], v[148:151], v[174:177], v[24:27]
	v_mfma_f32_16x16x32_bf16 v[16:19], v[140:143], v[196:199], v[16:19]
	v_mfma_f32_16x16x32_bf16 v[8:11], v[148:151], v[196:199], v[8:11]
	v_mfma_f32_16x16x32_bf16 v[60:63], v[144:147], v[162:165], v[60:63]
	v_mfma_f32_16x16x32_bf16 v[56:59], v[152:155], v[162:165], v[56:59]
	v_mfma_f32_16x16x32_bf16 v[44:47], v[144:147], v[170:173], v[44:47]
	v_mfma_f32_16x16x32_bf16 v[40:43], v[152:155], v[170:173], v[40:43]
	v_mfma_f32_16x16x32_bf16 v[32:35], v[144:147], v[178:181], v[32:35]
	v_mfma_f32_16x16x32_bf16 v[24:27], v[152:155], v[178:181], v[24:27]
	v_mfma_f32_16x16x32_bf16 v[16:19], v[144:147], v[200:203], v[16:19]
	v_mfma_f32_16x16x32_bf16 v[8:11], v[152:155], v[200:203], v[8:11]
	v_mfma_f32_16x16x32_bf16 v[52:55], v[204:207], v[156:159], v[52:55]
	v_mfma_f32_16x16x32_bf16 v[48:51], v[212:215], v[156:159], v[48:51]
	v_mfma_f32_16x16x32_bf16 v[36:39], v[204:207], v[166:169], v[36:39]
	v_mfma_f32_16x16x32_bf16 v[28:31], v[212:215], v[166:169], v[28:31]
	v_mfma_f32_16x16x32_bf16 v[20:23], v[204:207], v[174:177], v[20:23]
	v_mfma_f32_16x16x32_bf16 v[12:15], v[212:215], v[174:177], v[12:15]
	v_mfma_f32_16x16x32_bf16 v[4:7], v[204:207], v[196:199], v[4:7]
	v_mfma_f32_16x16x32_bf16 v[0:3], v[212:215], v[196:199], v[0:3]
	v_mfma_f32_16x16x32_bf16 v[52:55], v[208:211], v[162:165], v[52:55]
	v_mfma_f32_16x16x32_bf16 v[48:51], v[216:219], v[162:165], v[48:51]
	v_mfma_f32_16x16x32_bf16 v[36:39], v[208:211], v[170:173], v[36:39]
	v_mfma_f32_16x16x32_bf16 v[28:31], v[216:219], v[170:173], v[28:31]
	v_mfma_f32_16x16x32_bf16 v[20:23], v[208:211], v[178:181], v[20:23]
	v_mfma_f32_16x16x32_bf16 v[12:15], v[216:219], v[178:181], v[12:15]
	v_mfma_f32_16x16x32_bf16 v[4:7], v[208:211], v[200:203], v[4:7]
	v_mfma_f32_16x16x32_bf16 v[0:3], v[216:219], v[200:203], v[0:3]
	s_setprio 0
	s_barrier
	s_add_u32 s62, s24, 0x200000
	s_addc_u32 s63, s25, 0
	s_add_i32 s61, s61, s17
	s_mov_b32 m0, s61
	s_nop 0
	global_load_lds_dwordx4 v186, s[62:63]
	s_add_i32 m0, s61, 0x2000
	s_nop 0
	global_load_lds_dwordx4 v128, s[62:63]
	s_add_i32 s61, 0, 0x18000
	v_add_u32_e32 v152, s61, v138
	ds_read_b128 v[140:143], v152
	ds_read_b128 v[144:147], v152 offset:1024
	ds_read_b128 v[148:151], v152 offset:2048
	ds_read_b128 v[152:155], v152 offset:3072
	s_add_u32 s26, s26, 0x200000
	s_addc_u32 s27, s27, 0
	s_mov_b32 m0, s31
	ds_read_b128 v[156:159], v139 offset:32768
	ds_read_b128 v[162:165], v139 offset:33792
	ds_read_b128 v[166:169], v139 offset:34816
	ds_read_b128 v[170:173], v139 offset:35840
	ds_read_b128 v[174:177], v139 offset:36864
	ds_read_b128 v[178:181], v139 offset:37888
	ds_read_b128 v[196:199], v139 offset:38912
	ds_read_b128 v[200:203], v139 offset:39936
	v_add_u32_e32 v216, 0x1c000, v138
	ds_read_b128 v[204:207], v216
	ds_read_b128 v[208:211], v216 offset:1024
	ds_read_b128 v[212:215], v216 offset:2048
	ds_read_b128 v[216:219], v216 offset:3072
	global_load_lds_dwordx4 v186, s[26:27]
	s_mov_b32 m0, s52
	s_nop 0
	global_load_lds_dwordx4 v128, s[26:27]
	s_waitcnt vmcnt(8)
	s_waitcnt lgkmcnt(0)
	s_barrier
	s_setprio 1
	v_mfma_f32_16x16x32_bf16 v[124:127], v[140:143], v[156:159], v[124:127]
	v_mfma_f32_16x16x32_bf16 v[120:123], v[148:151], v[156:159], v[120:123]
	v_mfma_f32_16x16x32_bf16 v[108:111], v[140:143], v[166:169], v[108:111]
	v_mfma_f32_16x16x32_bf16 v[104:107], v[148:151], v[166:169], v[104:107]
	v_mfma_f32_16x16x32_bf16 v[92:95], v[140:143], v[174:177], v[92:95]
	v_mfma_f32_16x16x32_bf16 v[88:91], v[148:151], v[174:177], v[88:91]
	v_mfma_f32_16x16x32_bf16 v[76:79], v[140:143], v[196:199], v[76:79]
	v_mfma_f32_16x16x32_bf16 v[72:75], v[148:151], v[196:199], v[72:75]
	v_mfma_f32_16x16x32_bf16 v[124:127], v[144:147], v[162:165], v[124:127]
	v_mfma_f32_16x16x32_bf16 v[120:123], v[152:155], v[162:165], v[120:123]
	v_mfma_f32_16x16x32_bf16 v[108:111], v[144:147], v[170:173], v[108:111]
	v_mfma_f32_16x16x32_bf16 v[104:107], v[152:155], v[170:173], v[104:107]
	v_mfma_f32_16x16x32_bf16 v[92:95], v[144:147], v[178:181], v[92:95]
	v_mfma_f32_16x16x32_bf16 v[88:91], v[152:155], v[178:181], v[88:91]
	v_mfma_f32_16x16x32_bf16 v[76:79], v[144:147], v[200:203], v[76:79]
	v_mfma_f32_16x16x32_bf16 v[72:75], v[152:155], v[200:203], v[72:75]
	v_mfma_f32_16x16x32_bf16 v[116:119], v[204:207], v[156:159], v[116:119]
	v_mfma_f32_16x16x32_bf16 v[112:115], v[212:215], v[156:159], v[112:115]
	v_mfma_f32_16x16x32_bf16 v[100:103], v[204:207], v[166:169], v[100:103]
	v_mfma_f32_16x16x32_bf16 v[96:99], v[212:215], v[166:169], v[96:99]
	v_mfma_f32_16x16x32_bf16 v[84:87], v[204:207], v[174:177], v[84:87]
	v_mfma_f32_16x16x32_bf16 v[80:83], v[212:215], v[174:177], v[80:83]
	v_mfma_f32_16x16x32_bf16 v[68:71], v[204:207], v[196:199], v[68:71]
	v_mfma_f32_16x16x32_bf16 v[64:67], v[212:215], v[196:199], v[64:67]
	v_mfma_f32_16x16x32_bf16 v[116:119], v[208:211], v[162:165], v[116:119]
	v_mfma_f32_16x16x32_bf16 v[112:115], v[216:219], v[162:165], v[112:115]
	v_mfma_f32_16x16x32_bf16 v[100:103], v[208:211], v[170:173], v[100:103]
	v_mfma_f32_16x16x32_bf16 v[96:99], v[216:219], v[170:173], v[96:99]
	v_mfma_f32_16x16x32_bf16 v[84:87], v[208:211], v[178:181], v[84:87]
	v_mfma_f32_16x16x32_bf16 v[80:83], v[216:219], v[178:181], v[80:83]
	v_mfma_f32_16x16x32_bf16 v[68:71], v[208:211], v[200:203], v[68:71]
	v_mfma_f32_16x16x32_bf16 v[64:67], v[216:219], v[200:203], v[64:67]
	s_setprio 0
	s_barrier
	s_add_i32 s26, 0, 0x1c000
	s_add_i32 s27, s61, s17
	v_lshl_add_u64 v[182:183], v[182:183], 0, s[0:1]
	s_mov_b32 m0, s27
	global_load_lds_dwordx4 v[182:183], off
	v_lshl_add_u64 v[182:183], v[220:221], 0, s[0:1]
	s_add_i32 m0, s27, 0x2000
	s_nop 0
	global_load_lds_dwordx4 v[182:183], off
	s_mov_b32 m0, s53
	v_lshl_add_u64 v[182:183], v[222:223], 0, s[0:1]
	ds_read_b128 v[156:159], v139 offset:49152
	ds_read_b128 v[162:165], v139 offset:50176
	ds_read_b128 v[166:169], v139 offset:51200
	ds_read_b128 v[170:173], v139 offset:52224
	ds_read_b128 v[174:177], v139 offset:53248
	ds_read_b128 v[178:181], v139 offset:54272
	ds_read_b128 v[196:199], v139 offset:55296
	ds_read_b128 v[200:203], v139 offset:56320
	global_load_lds_dwordx4 v[182:183], off
	v_lshl_add_u64 v[182:183], v[224:225], 0, s[0:1]
	s_mov_b32 m0, s68
	s_nop 0
	global_load_lds_dwordx4 v[182:183], off
	s_add_u32 s24, s24, 0x200080
	s_addc_u32 s25, s25, 0
	s_add_i32 s26, s26, s17
	s_mov_b32 m0, s26
	s_nop 0
	global_load_lds_dwordx4 v186, s[24:25]
	s_add_i32 m0, s26, 0x2000
	s_nop 0
	global_load_lds_dwordx4 v128, s[24:25]
	s_waitcnt vmcnt(8)
	s_waitcnt lgkmcnt(0)
	s_barrier
	s_setprio 1
	v_mfma_f32_16x16x32_bf16 v[60:63], v[140:143], v[156:159], v[60:63]
	v_mfma_f32_16x16x32_bf16 v[56:59], v[148:151], v[156:159], v[56:59]
	v_mfma_f32_16x16x32_bf16 v[44:47], v[140:143], v[166:169], v[44:47]
	v_mfma_f32_16x16x32_bf16 v[40:43], v[148:151], v[166:169], v[40:43]
	v_mfma_f32_16x16x32_bf16 v[32:35], v[140:143], v[174:177], v[32:35]
	v_mfma_f32_16x16x32_bf16 v[24:27], v[148:151], v[174:177], v[24:27]
	v_mfma_f32_16x16x32_bf16 v[16:19], v[140:143], v[196:199], v[16:19]
	v_mfma_f32_16x16x32_bf16 v[8:11], v[148:151], v[196:199], v[8:11]
	v_mfma_f32_16x16x32_bf16 v[60:63], v[144:147], v[162:165], v[60:63]
	v_mfma_f32_16x16x32_bf16 v[56:59], v[152:155], v[162:165], v[56:59]
	v_mfma_f32_16x16x32_bf16 v[44:47], v[144:147], v[170:173], v[44:47]
	v_mfma_f32_16x16x32_bf16 v[40:43], v[152:155], v[170:173], v[40:43]
	v_mfma_f32_16x16x32_bf16 v[32:35], v[144:147], v[178:181], v[32:35]
	v_mfma_f32_16x16x32_bf16 v[24:27], v[152:155], v[178:181], v[24:27]
	v_mfma_f32_16x16x32_bf16 v[16:19], v[144:147], v[200:203], v[16:19]
	v_mfma_f32_16x16x32_bf16 v[8:11], v[152:155], v[200:203], v[8:11]
	v_mfma_f32_16x16x32_bf16 v[52:55], v[204:207], v[156:159], v[52:55]
	v_mfma_f32_16x16x32_bf16 v[48:51], v[212:215], v[156:159], v[48:51]
	v_mfma_f32_16x16x32_bf16 v[36:39], v[204:207], v[166:169], v[36:39]
	v_mfma_f32_16x16x32_bf16 v[28:31], v[212:215], v[166:169], v[28:31]
	v_mfma_f32_16x16x32_bf16 v[20:23], v[204:207], v[174:177], v[20:23]
	v_mfma_f32_16x16x32_bf16 v[12:15], v[212:215], v[174:177], v[12:15]
	v_mfma_f32_16x16x32_bf16 v[4:7], v[204:207], v[196:199], v[4:7]
	v_mfma_f32_16x16x32_bf16 v[0:3], v[212:215], v[196:199], v[0:3]
	v_mfma_f32_16x16x32_bf16 v[52:55], v[208:211], v[162:165], v[52:55]
	v_mfma_f32_16x16x32_bf16 v[48:51], v[216:219], v[162:165], v[48:51]
	v_mfma_f32_16x16x32_bf16 v[36:39], v[208:211], v[170:173], v[36:39]
	v_mfma_f32_16x16x32_bf16 v[28:31], v[216:219], v[170:173], v[28:31]
	v_mfma_f32_16x16x32_bf16 v[20:23], v[208:211], v[178:181], v[20:23]
	v_mfma_f32_16x16x32_bf16 v[12:15], v[216:219], v[178:181], v[12:15]
	v_mfma_f32_16x16x32_bf16 v[4:7], v[208:211], v[200:203], v[4:7]
	v_mfma_f32_16x16x32_bf16 v[0:3], v[216:219], v[200:203], v[0:3]
	s_setprio 0
	s_add_i32 s60, s60, 2
	s_add_u32 vcc_lo, vcc_lo, 0x100
	s_addc_u32 vcc_hi, vcc_hi, 0
	s_cmpk_gt_u32 s60, 0x7d
	s_barrier
	s_cbranch_scc0 .LBB0_940
	s_add_u32 s24, s19, 0xffffff00
	s_addc_u32 s25, s4, -1
	s_andn2_b64 vcc, exec, s[44:45]
	s_cbranch_vccnz .LBB0_931
	v_mov_b32_e32 v0, 0
	s_mov_b32 s18, s28
	s_mov_b32 s56, s38
	s_mov_b64 s[2:3], s[20:21]
	s_mov_b32 s69, s57
	v_mov_b32_e32 v1, v0
	v_mov_b32_e32 v2, v0
	v_mov_b32_e32 v3, v0
	v_mov_b32_e32 v4, v0
	v_mov_b32_e32 v5, v0
	v_mov_b32_e32 v6, v0
	v_mov_b32_e32 v7, v0
	v_mov_b32_e32 v12, v0
	v_mov_b32_e32 v13, v0
	v_mov_b32_e32 v14, v0
	v_mov_b32_e32 v15, v0
	v_mov_b32_e32 v20, v0
	v_mov_b32_e32 v21, v0
	v_mov_b32_e32 v22, v0
	v_mov_b32_e32 v23, v0
	v_mov_b32_e32 v28, v0
	v_mov_b32_e32 v29, v0
	v_mov_b32_e32 v30, v0
	v_mov_b32_e32 v31, v0
	v_mov_b32_e32 v36, v0
	v_mov_b32_e32 v37, v0
	v_mov_b32_e32 v38, v0
	v_mov_b32_e32 v39, v0
	v_mov_b32_e32 v48, v0
	v_mov_b32_e32 v49, v0
	v_mov_b32_e32 v50, v0
	v_mov_b32_e32 v51, v0
	v_mov_b32_e32 v52, v0
	v_mov_b32_e32 v53, v0
	v_mov_b32_e32 v54, v0
	v_mov_b32_e32 v55, v0
	v_mov_b32_e32 v8, v0
	v_mov_b32_e32 v9, v0
	v_mov_b32_e32 v10, v0
	v_mov_b32_e32 v11, v0
	v_mov_b32_e32 v16, v0
	v_mov_b32_e32 v17, v0
	v_mov_b32_e32 v18, v0
	v_mov_b32_e32 v19, v0
	v_mov_b32_e32 v24, v0
	v_mov_b32_e32 v25, v0
	v_mov_b32_e32 v26, v0
	v_mov_b32_e32 v27, v0
	v_mov_b32_e32 v32, v0
	v_mov_b32_e32 v33, v0
	v_mov_b32_e32 v34, v0
	v_mov_b32_e32 v35, v0
	v_mov_b32_e32 v40, v0
	v_mov_b32_e32 v41, v0
	v_mov_b32_e32 v42, v0
	v_mov_b32_e32 v43, v0
	v_mov_b32_e32 v44, v0
	v_mov_b32_e32 v45, v0
	v_mov_b32_e32 v46, v0
	v_mov_b32_e32 v47, v0
	v_mov_b32_e32 v56, v0
	v_mov_b32_e32 v57, v0
	v_mov_b32_e32 v58, v0
	v_mov_b32_e32 v59, v0
	v_mov_b32_e32 v60, v0
	v_mov_b32_e32 v61, v0
	v_mov_b32_e32 v62, v0
	v_mov_b32_e32 v63, v0
	v_mov_b32_e32 v64, v0
	v_mov_b32_e32 v65, v0
	v_mov_b32_e32 v66, v0
	v_mov_b32_e32 v67, v0
	v_mov_b32_e32 v68, v0
	v_mov_b32_e32 v69, v0
	v_mov_b32_e32 v70, v0
	v_mov_b32_e32 v71, v0
	v_mov_b32_e32 v80, v0
	v_mov_b32_e32 v81, v0
	v_mov_b32_e32 v82, v0
	v_mov_b32_e32 v83, v0
	v_mov_b32_e32 v84, v0
	v_mov_b32_e32 v85, v0
	v_mov_b32_e32 v86, v0
	v_mov_b32_e32 v87, v0
	v_mov_b32_e32 v96, v0
	v_mov_b32_e32 v97, v0
	v_mov_b32_e32 v98, v0
	v_mov_b32_e32 v99, v0
	v_mov_b32_e32 v100, v0
	v_mov_b32_e32 v101, v0
	v_mov_b32_e32 v102, v0
	v_mov_b32_e32 v103, v0
	v_mov_b32_e32 v112, v0
	v_mov_b32_e32 v113, v0
	v_mov_b32_e32 v114, v0
	v_mov_b32_e32 v115, v0
	v_mov_b32_e32 v116, v0
	v_mov_b32_e32 v117, v0
	v_mov_b32_e32 v118, v0
	v_mov_b32_e32 v119, v0
	v_mov_b32_e32 v72, v0
	v_mov_b32_e32 v73, v0
	v_mov_b32_e32 v74, v0
	v_mov_b32_e32 v75, v0
	v_mov_b32_e32 v76, v0
	v_mov_b32_e32 v77, v0
	v_mov_b32_e32 v78, v0
	v_mov_b32_e32 v79, v0
	v_mov_b32_e32 v88, v0
	v_mov_b32_e32 v89, v0
	v_mov_b32_e32 v90, v0
	v_mov_b32_e32 v91, v0
	v_mov_b32_e32 v92, v0
	v_mov_b32_e32 v93, v0
	v_mov_b32_e32 v94, v0
	v_mov_b32_e32 v95, v0
	v_mov_b32_e32 v104, v0
	v_mov_b32_e32 v105, v0
	v_mov_b32_e32 v106, v0
	v_mov_b32_e32 v107, v0
	v_mov_b32_e32 v108, v0
	v_mov_b32_e32 v109, v0
	v_mov_b32_e32 v110, v0
	v_mov_b32_e32 v111, v0
	v_mov_b32_e32 v120, v0
	v_mov_b32_e32 v121, v0
	v_mov_b32_e32 v122, v0
	v_mov_b32_e32 v123, v0
	v_mov_b32_e32 v124, v0
	v_mov_b32_e32 v125, v0
	v_mov_b32_e32 v126, v0
	v_mov_b32_e32 v127, v0
	s_andn2_b64 vcc, exec, s[42:43]
	s_cbranch_vccnz .LBB0_932
